# all four GEMM phases fully LDS-DMA staged (K-loop, tail, header, prologue)
# speedup vs baseline: 1.0189x; 1.0073x over previous
.LBB0_123:
	s_andn2_b64 vcc, exec, s[28:29]
	s_cbranch_vccnz .LBB0_131
	v_readlane_b32 s4, v254, 37
	v_readlane_b32 s5, v254, 38
	s_mov_b64 s[0:1], 0
	v_mov_b32_e32 v80, v169
	s_andn2_b64 vcc, exec, s[4:5]
	s_cbranch_vccnz .LBB0_131
	s_load_dword s2, s[22:23], 0x0
	s_add_u32 s0, s72, s0
	s_addc_u32 s1, s73, s1
	s_add_u32 s0, s0, 0x1a991000
	v_readlane_b32 s4, v255, 36
	s_addc_u32 s1, s1, 0
	s_waitcnt lgkmcnt(0)
	s_lshr_b32 s2, s2, 3
	s_mul_hi_i32 s29, s4, 0x580000
	s_mul_i32 s28, s4, 0x580000
	v_readlane_b32 s4, v254, 35
	v_mov_b32_e32 v0, v169
	s_add_u32 s38, s4, s28
	v_readlane_b32 s4, v254, 36
	v_readlane_b32 s9, v254, 39
	s_waitcnt vmcnt(7)
	v_lshrrev_b32_e32 v2, 3, v0
	s_addc_u32 s39, s4, s29
	v_add_u32_e32 v2, s9, v2
	s_movk_i32 s4, 0xb00
	v_lshlrev_b32_e32 v0, 3, v0
	v_mul_lo_u32 v2, v2, s4
	v_and_or_b32 v0, v0, 56, v2
	v_mov_b32_e32 v2, v169
	v_readlane_b32 s10, v254, 40
	v_lshrrev_b32_e32 v3, 3, v2
	v_readlane_b32 s5, v255, 37
	v_add_u32_e32 v3, s10, v3
	v_lshlrev_b32_e32 v2, 3, v2
	v_mul_lo_u32 v3, v3, s4
	v_and_or_b32 v72, v2, 56, v3
	v_readlane_b32 s4, v254, 33
	v_add_u32_e32 v66, 0x16000, v0
	v_add_u32_e32 v68, 0x2c000, v0
	v_add_u32_e32 v70, 0x42000, v0
	v_add_u32_e32 v74, 0x16000, v72
	v_add_u32_e32 v76, 0x2c000, v72
	v_add_u32_e32 v78, 0x42000, v72
	v_readlane_b32 s5, v254, 34
	v_mov_b32_e32 v73, v1
	v_mov_b32_e32 v67, v1
	v_mov_b32_e32 v75, v1
	v_mov_b32_e32 v69, v1
	v_mov_b32_e32 v77, v1
	v_mov_b32_e32 v71, v1
	v_mov_b32_e32 v79, v1
	v_lshl_add_u64 v[2:3], v[0:1], 1, s[4:5]
	s_waitcnt vmcnt(6)
	v_lshl_add_u64 v[6:7], v[72:73], 1, s[38:39]
	s_waitcnt vmcnt(5)
	v_lshl_add_u64 v[10:11], v[66:67], 1, s[4:5]
	s_waitcnt vmcnt(4)
	v_lshl_add_u64 v[14:15], v[74:75], 1, s[38:39]
	s_waitcnt vmcnt(3)
	v_lshl_add_u64 v[18:19], v[68:69], 1, s[4:5]
	s_waitcnt vmcnt(2)
	v_lshl_add_u64 v[22:23], v[76:77], 1, s[38:39]
	s_waitcnt vmcnt(1)
	v_lshl_add_u64 v[26:27], v[70:71], 1, s[4:5]
	s_waitcnt vmcnt(0)
	v_lshl_add_u64 v[30:31], v[78:79], 1, s[38:39]
	v_lshrrev_b32_e32 v34, 6, v169
	v_lshlrev_b32_e32 v34, 10, v34
	s_nop 0
	v_readfirstlane_b32 s100, v34
	v_lshrrev_b32_e32 v35, 3, v169
	v_and_b32_e32 v36, 3, v35
	v_bfe_u32 v37, v35, 4, 1
	v_lshl_or_b32 v36, v37, 2, v36
	v_bfe_u32 v37, v35, 2, 1
	v_lshl_or_b32 v36, v37, 3, v36
	v_bfe_u32 v37, v35, 3, 1
	v_lshl_or_b32 v36, v37, 4, v36
	v_sub_u32_e32 v36, v36, v35
	v_mul_i32_i24_e32 v36, 0x1600, v36
	v_and_b32_e32 v35, 7, v35
	v_lshlrev_b32_e32 v35, 4, v35
	v_ashrrev_i32_e32 v37, 31, v36
	v_xor_b32_e32 v2, v2, v35
	v_lshl_add_u64 v[6:7], v[6:7], 0, v[36:37]
	v_xor_b32_e32 v6, v6, v35
	v_xor_b32_e32 v10, v10, v35
	v_lshl_add_u64 v[14:15], v[14:15], 0, v[36:37]
	v_xor_b32_e32 v14, v14, v35
	v_xor_b32_e32 v18, v18, v35
	v_lshl_add_u64 v[22:23], v[22:23], 0, v[36:37]
	v_xor_b32_e32 v22, v22, v35
	v_xor_b32_e32 v26, v26, v35
	v_lshl_add_u64 v[30:31], v[30:31], 0, v[36:37]
	v_xor_b32_e32 v30, v30, v35
	s_add_u32 m0, s100, 0x0
	s_nop 0
	global_load_lds_dwordx4 v[2:3], off
	s_add_u32 m0, s100, 0x4000
	s_nop 0
	global_load_lds_dwordx4 v[6:7], off
	s_add_u32 m0, s100, 0x1000
	s_nop 0
	global_load_lds_dwordx4 v[10:11], off
	s_add_u32 m0, s100, 0x5000
	s_nop 0
	global_load_lds_dwordx4 v[14:15], off
	s_add_u32 m0, s100, 0x2000
	s_nop 0
	global_load_lds_dwordx4 v[18:19], off
	s_add_u32 m0, s100, 0x6000
	s_nop 0
	global_load_lds_dwordx4 v[22:23], off
	s_add_u32 m0, s100, 0x3000
	s_nop 0
	global_load_lds_dwordx4 v[26:27], off
	s_add_u32 m0, s100, 0x7000
	s_nop 0
	global_load_lds_dwordx4 v[30:31], off
	s_waitcnt vmcnt(0)
	v_and_b32_e32 v69, 15, v80
	v_ashrrev_i32_e32 v71, 1, v80
	s_movk_i32 s4, 0xffc0
	v_and_b32_e32 v67, 64, v80
	v_and_or_b32 v116, v71, s4, v69
	v_lshrrev_b32_e32 v69, 1, v80
	v_and_or_b32 v117, v69, 24, v67
	v_or_b32_e32 v118, 16, v116
	v_or_b32_e32 v119, 32, v116
	v_or_b32_e32 v120, 48, v116
	v_readlane_b32 s8, v254, 57
	s_branch .LBB0_127

.LBB0_127:
	v_mov_b32_e32 v67, v169
	s_mov_b32 s11, s8
	v_lshrrev_b32_e32 v69, 4, v67
	v_ashrrev_i32_e32 v71, 3, v67
	v_lshrrev_b32_e32 v77, 1, v67
	v_and_b32_e32 v80, 4, v69
	v_and_b32_e32 v81, 3, v71
	v_and_b32_e32 v73, 7, v67
	v_xor_b32_e32 v75, v71, v67
	v_and_b32_e32 v77, 16, v77
	v_and_b32_e32 v79, 8, v69
	v_or_b32_e32 v82, v80, v81
	v_lshlrev_b32_e32 v75, 4, v75
	v_or3_b32 v77, v77, v79, v82
	v_bitop3_b32 v79, v80, v73, v81 bitop3:0x36
	v_lshlrev_b32_e32 v71, 7, v71
	v_lshlrev_b32_e32 v79, 4, v79
	v_and_or_b32 v122, v75, s24, v71
	v_lshl_or_b32 v121, v77, 7, v79
	v_lshlrev_b32_e32 v34, 7, v67
	v_and_b32_e32 v35, 0x780, v34
	v_and_b32_e32 v123, 0x2780, v34
	v_bitop3_b32 v34, v69, v73, 3 bitop3:0x6c
	v_bfe_u32 v77, v67, 4, 2
	v_lshlrev_b32_e32 v124, 4, v34
	v_lshlrev_b32_e32 v34, 6, v67
	v_mov_b32_e32 v75, v1
	v_and_or_b32 v125, v34, s30, v35
	v_bitop3_b32 v34, v77, v73, 4 bitop3:0x36
	v_mov_b32_e32 v73, v1
	v_mov_b32_e32 v67, v1
	v_mov_b32_e32 v69, v1
	v_mov_b32_e32 v77, v1
	v_mov_b32_e32 v71, v1
	v_mov_b32_e32 v79, v1
	v_lshl_add_u64 v[100:101], v[74:75], 1, s[28:29]
	v_mov_b32_e32 v74, 0
	s_mov_b32 s5, s10
	s_mov_b32 s4, s9
	v_lshlrev_b32_e32 v126, 4, v34
	v_lshl_add_u64 v[98:99], v[72:73], 1, s[28:29]
	v_lshl_add_u64 v[102:103], v[76:77], 1, s[28:29]
	v_lshl_add_u64 v[104:105], v[78:79], 1, s[28:29]
	v_lshlrev_b64 v[106:107], 1, v[0:1]
	v_lshlrev_b64 v[108:109], 1, v[66:67]
	v_lshlrev_b64 v[110:111], 1, v[68:69]
	v_lshlrev_b64 v[112:113], 1, v[70:71]
	s_mov_b32 s8, -2
	s_mov_b64 s[42:43], s[72:73]
	v_mov_b32_e32 v75, v74
	v_mov_b32_e32 v76, v74
	v_mov_b32_e32 v77, v74
	v_mov_b32_e32 v62, v74
	v_mov_b32_e32 v63, v74
	v_mov_b32_e32 v64, v74
	v_mov_b32_e32 v65, v74
	v_mov_b32_e32 v66, v74
	v_mov_b32_e32 v67, v74
	v_mov_b32_e32 v68, v74
	v_mov_b32_e32 v69, v74
	v_mov_b32_e32 v58, v74
	v_mov_b32_e32 v59, v74
	v_mov_b32_e32 v60, v74
	v_mov_b32_e32 v61, v74
	v_mov_b32_e32 v70, v74
	v_mov_b32_e32 v71, v74
	v_mov_b32_e32 v72, v74
	v_mov_b32_e32 v73, v74
	v_mov_b32_e32 v54, v74
	v_mov_b32_e32 v55, v74
	v_mov_b32_e32 v56, v74
	v_mov_b32_e32 v57, v74
	v_mov_b32_e32 v78, v74
	v_mov_b32_e32 v79, v74
	v_mov_b32_e32 v80, v74
	v_mov_b32_e32 v81, v74
	v_mov_b32_e32 v50, v74
	v_mov_b32_e32 v51, v74
	v_mov_b32_e32 v52, v74
	v_mov_b32_e32 v53, v74
	v_mov_b32_e32 v82, v74
	v_mov_b32_e32 v83, v74
	v_mov_b32_e32 v84, v74
	v_mov_b32_e32 v85, v74
	v_mov_b32_e32 v46, v74
	v_mov_b32_e32 v47, v74
	v_mov_b32_e32 v48, v74
	v_mov_b32_e32 v49, v74
	v_mov_b32_e32 v86, v74
	v_mov_b32_e32 v87, v74
	v_mov_b32_e32 v88, v74
	v_mov_b32_e32 v89, v74
	v_mov_b32_e32 v42, v74
	v_mov_b32_e32 v43, v74
	v_mov_b32_e32 v44, v74
	v_mov_b32_e32 v45, v74
	v_mov_b32_e32 v90, v74
	v_mov_b32_e32 v91, v74
	v_mov_b32_e32 v92, v74
	v_mov_b32_e32 v93, v74
	v_mov_b32_e32 v38, v74
	v_mov_b32_e32 v39, v74
	v_mov_b32_e32 v40, v74
	v_mov_b32_e32 v41, v74
	v_mov_b32_e32 v94, v74
	v_mov_b32_e32 v95, v74
	v_mov_b32_e32 v96, v74
	v_mov_b32_e32 v97, v74
	v_mov_b32_e32 v34, v74
	v_mov_b32_e32 v35, v74
	v_mov_b32_e32 v36, v74
	v_mov_b32_e32 v37, v74
	s_waitcnt vmcnt(1)
	s_waitcnt lgkmcnt(0)
	s_barrier
	v_add_u32_e32 v127, v124, v123
	v_add_u32_e32 v129, v124, v125
	v_add_u32_e32 v128, v126, v125
	v_add_u32_e32 v130, v126, v123
	v_lshrrev_b32_e32 v218, 6, v169
	v_lshlrev_b32_e32 v218, 10, v218
	v_lshrrev_b32_e32 v219, 3, v169
	v_readfirstlane_b32 s100, v218
	v_and_b32_e32 v218, 3, v219
	v_bfe_u32 v220, v219, 4, 1
	v_lshl_or_b32 v218, v220, 2, v218
	v_bfe_u32 v220, v219, 2, 1
	v_lshl_or_b32 v218, v220, 3, v218
	v_bfe_u32 v220, v219, 3, 1
	v_lshl_or_b32 v218, v220, 4, v218
	v_sub_u32_e32 v218, v218, v219
	v_mul_i32_i24_e32 v218, 0x1600, v218
	v_and_b32_e32 v219, 7, v219
	v_lshlrev_b32_e32 v219, 4, v219
	v_add_u32_e32 v206, 0x7511000, v106
	v_xor_b32_e32 v194, v206, v219
	v_mov_b32_e32 v207, v98
	v_add_u32_e32 v195, v207, v218
	v_xor_b32_e32 v195, v195, v219
	v_add_u32_e32 v208, 0x7511000, v108
	v_xor_b32_e32 v196, v208, v219
	v_mov_b32_e32 v209, v100
	v_add_u32_e32 v197, v209, v218
	v_xor_b32_e32 v197, v197, v219
	v_add_u32_e32 v214, 0x7511000, v110
	v_xor_b32_e32 v202, v214, v219
	v_mov_b32_e32 v215, v102
	v_add_u32_e32 v203, v215, v218
	v_xor_b32_e32 v203, v203, v219
	v_add_u32_e32 v216, 0x7511000, v112
	v_xor_b32_e32 v204, v216, v219
	v_mov_b32_e32 v217, v104
	v_add_u32_e32 v205, v217, v218
	v_xor_b32_e32 v205, v205, v219
.LBB0_128:
	s_setprio 1
	s_add_u32 s98, s42, s27
	s_addc_u32 s99, s43, 0
	s_add_u32 s98, s98, 0x80
	s_addc_u32 s99, s99, 0
	ds_read_b128 v[132:135], v127 offset:16384
	ds_read_b128 v[152:155], v127 offset:18432
	ds_read_b128 v[160:163], v127 offset:20480
	ds_read_b128 v[164:167], v127 offset:22528
	ds_read_b128 v[140:143], v129
	ds_read_b128 v[144:147], v129 offset:2048
	ds_read_b128 v[148:151], v129 offset:4096
	ds_read_b128 v[156:159], v129 offset:6144
	s_add_u32 m0, s100, 0x8000
	s_waitcnt lgkmcnt(3)
	v_mfma_f32_16x16x32_bf16 v[34:37], v[132:135], v[140:143], v[34:37]
	global_load_lds_dwordx4 v194, s[98:99]
	v_mfma_f32_16x16x32_bf16 v[94:97], v[152:155], v[140:143], v[94:97]
	ds_read_b128 v[198:201], v128
	s_add_u32 m0, s100, 0xc000
	v_mfma_f32_16x16x32_bf16 v[38:41], v[160:163], v[140:143], v[38:41]
	global_load_lds_dwordx4 v195, s[98:99]
	v_mfma_f32_16x16x32_bf16 v[90:93], v[164:167], v[140:143], v[90:93]
	ds_read_b128 v[140:143], v128 offset:2048
	s_add_u32 m0, s100, 0x9000
	s_waitcnt lgkmcnt(4)
	v_mfma_f32_16x16x32_bf16 v[42:45], v[132:135], v[144:147], v[42:45]
	global_load_lds_dwordx4 v196, s[98:99]
	v_mfma_f32_16x16x32_bf16 v[86:89], v[152:155], v[144:147], v[86:89]
	ds_read_b128 v[210:213], v128 offset:4096
	s_add_u32 m0, s100, 0xd000
	v_mfma_f32_16x16x32_bf16 v[46:49], v[160:163], v[144:147], v[46:49]
	global_load_lds_dwordx4 v197, s[98:99]
	v_mfma_f32_16x16x32_bf16 v[82:85], v[164:167], v[144:147], v[82:85]
	ds_read_b128 v[144:147], v128 offset:6144
	s_add_u32 m0, s100, 0xa000
	s_waitcnt lgkmcnt(5)
	v_mfma_f32_16x16x32_bf16 v[50:53], v[132:135], v[148:151], v[50:53]
	global_load_lds_dwordx4 v202, s[98:99]
	v_mfma_f32_16x16x32_bf16 v[78:81], v[152:155], v[148:151], v[78:81]
	ds_read_b128 v[222:225], v130 offset:16384
	s_add_u32 m0, s100, 0xe000
	v_mfma_f32_16x16x32_bf16 v[54:57], v[160:163], v[148:151], v[54:57]
	global_load_lds_dwordx4 v203, s[98:99]
	v_mfma_f32_16x16x32_bf16 v[70:73], v[164:167], v[148:151], v[70:73]
	ds_read_b128 v[148:151], v130 offset:18432
	s_add_u32 m0, s100, 0xb000
	s_waitcnt lgkmcnt(6)
	v_mfma_f32_16x16x32_bf16 v[58:61], v[132:135], v[156:159], v[58:61]
	global_load_lds_dwordx4 v204, s[98:99]
	v_mfma_f32_16x16x32_bf16 v[66:69], v[152:155], v[156:159], v[66:69]
	ds_read_b128 v[152:155], v130 offset:20480
	s_add_u32 m0, s100, 0xf000
	v_mfma_f32_16x16x32_bf16 v[62:65], v[160:163], v[156:159], v[62:65]
	global_load_lds_dwordx4 v205, s[98:99]
	v_mfma_f32_16x16x32_bf16 v[74:77], v[164:167], v[156:159], v[74:77]
	ds_read_b128 v[156:159], v130 offset:22528
	s_waitcnt lgkmcnt(3)
	v_mfma_f32_16x16x32_bf16 v[34:37], v[222:225], v[198:201], v[34:37]
	s_waitcnt lgkmcnt(2)
	v_mfma_f32_16x16x32_bf16 v[94:97], v[148:151], v[198:201], v[94:97]
	s_waitcnt lgkmcnt(1)
	v_mfma_f32_16x16x32_bf16 v[38:41], v[152:155], v[198:201], v[38:41]
	s_waitcnt lgkmcnt(0)
	v_mfma_f32_16x16x32_bf16 v[90:93], v[156:159], v[198:201], v[90:93]
	v_mfma_f32_16x16x32_bf16 v[42:45], v[222:225], v[140:143], v[42:45]
	v_mfma_f32_16x16x32_bf16 v[86:89], v[148:151], v[140:143], v[86:89]
	v_mfma_f32_16x16x32_bf16 v[46:49], v[152:155], v[140:143], v[46:49]
	v_mfma_f32_16x16x32_bf16 v[82:85], v[156:159], v[140:143], v[82:85]
	v_mfma_f32_16x16x32_bf16 v[50:53], v[222:225], v[210:213], v[50:53]
	v_mfma_f32_16x16x32_bf16 v[78:81], v[148:151], v[210:213], v[78:81]
	v_mfma_f32_16x16x32_bf16 v[54:57], v[152:155], v[210:213], v[54:57]
	v_mfma_f32_16x16x32_bf16 v[70:73], v[156:159], v[210:213], v[70:73]
	v_mfma_f32_16x16x32_bf16 v[58:61], v[222:225], v[144:147], v[58:61]
	v_mfma_f32_16x16x32_bf16 v[66:69], v[148:151], v[144:147], v[66:69]
	v_mfma_f32_16x16x32_bf16 v[62:65], v[152:155], v[144:147], v[62:65]
	v_mfma_f32_16x16x32_bf16 v[74:77], v[156:159], v[144:147], v[74:77]
	s_waitcnt vmcnt(0)
	s_setprio 0
	s_waitcnt lgkmcnt(0)
	s_barrier
	s_setprio 1
	s_add_u32 s98, s98, 0x80
	s_addc_u32 s99, s99, 0
	ds_read_b128 v[26:29], v127 offset:49152
	ds_read_b128 v[30:33], v127 offset:51200
	ds_read_b128 v[148:151], v127 offset:53248
	ds_read_b128 v[152:155], v127 offset:55296
	ds_read_b128 v[10:13], v129 offset:32768
	ds_read_b128 v[18:21], v129 offset:34816
	ds_read_b128 v[140:143], v129 offset:36864
	ds_read_b128 v[144:147], v129 offset:38912
	s_add_u32 m0, s100, 0x0
	s_waitcnt lgkmcnt(3)
	v_mfma_f32_16x16x32_bf16 v[34:37], v[26:29], v[10:13], v[34:37]
	global_load_lds_dwordx4 v194, s[98:99]
	v_mfma_f32_16x16x32_bf16 v[94:97], v[30:33], v[10:13], v[94:97]
	ds_read_b128 v[156:159], v128 offset:32768
	s_add_u32 m0, s100, 0x4000
	v_mfma_f32_16x16x32_bf16 v[38:41], v[148:151], v[10:13], v[38:41]
	global_load_lds_dwordx4 v195, s[98:99]
	v_mfma_f32_16x16x32_bf16 v[90:93], v[152:155], v[10:13], v[90:93]
	ds_read_b128 v[164:167], v128 offset:34816
	s_add_u32 m0, s100, 0x1000
	s_waitcnt lgkmcnt(4)
	v_mfma_f32_16x16x32_bf16 v[42:45], v[26:29], v[18:21], v[42:45]
	global_load_lds_dwordx4 v196, s[98:99]
	v_mfma_f32_16x16x32_bf16 v[86:89], v[30:33], v[18:21], v[86:89]
	ds_read_b128 v[198:201], v128 offset:36864
	s_add_u32 m0, s100, 0x5000
	v_mfma_f32_16x16x32_bf16 v[46:49], v[148:151], v[18:21], v[46:49]
	global_load_lds_dwordx4 v197, s[98:99]
	v_mfma_f32_16x16x32_bf16 v[82:85], v[152:155], v[18:21], v[82:85]
	ds_read_b128 v[210:213], v128 offset:38912
	s_add_u32 m0, s100, 0x2000
	s_waitcnt lgkmcnt(5)
	v_mfma_f32_16x16x32_bf16 v[50:53], v[26:29], v[140:143], v[50:53]
	global_load_lds_dwordx4 v202, s[98:99]
	v_mfma_f32_16x16x32_bf16 v[78:81], v[30:33], v[140:143], v[78:81]
	ds_read_b128 v[222:225], v130 offset:49152
	s_add_u32 m0, s100, 0x6000
	v_mfma_f32_16x16x32_bf16 v[54:57], v[148:151], v[140:143], v[54:57]
	global_load_lds_dwordx4 v203, s[98:99]
	v_mfma_f32_16x16x32_bf16 v[70:73], v[152:155], v[140:143], v[70:73]
	ds_read_b128 v[140:143], v130 offset:51200
	s_add_u32 m0, s100, 0x3000
	s_waitcnt lgkmcnt(6)
	v_mfma_f32_16x16x32_bf16 v[58:61], v[26:29], v[144:147], v[58:61]
	global_load_lds_dwordx4 v204, s[98:99]
	v_mfma_f32_16x16x32_bf16 v[66:69], v[30:33], v[144:147], v[66:69]
	ds_read_b128 v[230:233], v130 offset:53248
	s_add_u32 m0, s100, 0x7000
	v_mfma_f32_16x16x32_bf16 v[62:65], v[148:151], v[144:147], v[62:65]
	global_load_lds_dwordx4 v205, s[98:99]
	v_mfma_f32_16x16x32_bf16 v[74:77], v[152:155], v[144:147], v[74:77]
	ds_read_b128 v[144:147], v130 offset:55296
	s_waitcnt lgkmcnt(3)
	v_mfma_f32_16x16x32_bf16 v[34:37], v[222:225], v[156:159], v[34:37]
	s_waitcnt lgkmcnt(2)
	v_mfma_f32_16x16x32_bf16 v[94:97], v[140:143], v[156:159], v[94:97]
	s_waitcnt lgkmcnt(1)
	v_mfma_f32_16x16x32_bf16 v[38:41], v[230:233], v[156:159], v[38:41]
	s_waitcnt lgkmcnt(0)
	v_mfma_f32_16x16x32_bf16 v[90:93], v[144:147], v[156:159], v[90:93]
	v_mfma_f32_16x16x32_bf16 v[42:45], v[222:225], v[164:167], v[42:45]
	v_mfma_f32_16x16x32_bf16 v[86:89], v[140:143], v[164:167], v[86:89]
	v_mfma_f32_16x16x32_bf16 v[46:49], v[230:233], v[164:167], v[46:49]
	v_mfma_f32_16x16x32_bf16 v[82:85], v[144:147], v[164:167], v[82:85]
	v_mfma_f32_16x16x32_bf16 v[50:53], v[222:225], v[198:201], v[50:53]
	v_mfma_f32_16x16x32_bf16 v[78:81], v[140:143], v[198:201], v[78:81]
	v_mfma_f32_16x16x32_bf16 v[54:57], v[230:233], v[198:201], v[54:57]
	v_mfma_f32_16x16x32_bf16 v[70:73], v[144:147], v[198:201], v[70:73]
	v_mfma_f32_16x16x32_bf16 v[58:61], v[222:225], v[210:213], v[58:61]
	v_mfma_f32_16x16x32_bf16 v[66:69], v[140:143], v[210:213], v[66:69]
	v_mfma_f32_16x16x32_bf16 v[62:65], v[230:233], v[210:213], v[62:65]
	v_mfma_f32_16x16x32_bf16 v[74:77], v[144:147], v[210:213], v[74:77]
	s_waitcnt vmcnt(0)
	s_setprio 0
	s_add_i32 s8, s8, 2
	s_add_u32 s42, s42, 0x100
	s_addc_u32 s43, s43, 0
	s_cmp_lt_u32 s8, 40
	s_waitcnt lgkmcnt(0)
	s_barrier
	s_cbranch_scc1 .LBB0_128
	v_mov_b32_e32 v2, v194
	v_mov_b32_e32 v3, v195
	v_mov_b32_e32 v4, v196
	v_mov_b32_e32 v5, v197
	v_mov_b32_e32 v6, v202
	v_mov_b32_e32 v7, v203
	v_mov_b32_e32 v8, v204
	v_mov_b32_e32 v9, v205
	s_add_u32 s98, s42, s27
	s_addc_u32 s99, s43, 0
	s_add_u32 s98, s98, 0x80
	s_addc_u32 s99, s99, 0
	s_add_i32 s8, s11, s2
	s_cmpk_lt_u32 s8, 0x100
	s_cselect_b32 s10, s8, s11
	s_lshr_b32 s9, s10, 3
	s_and_b32 s9, s9, 0x1fffff8
	s_add_i32 s9, s9, s21
	s_and_b32 s11, s10, 7
	s_or_b32 s9, s9, s11
	v_mov_b32_e32 v0, v169
	s_lshl_b32 s9, s9, 7
	s_movk_i32 s11, 0xb00
	v_lshrrev_b32_e32 v98, 3, v0
	v_add_u32_e32 v98, s9, v98
	v_lshlrev_b32_e32 v0, 3, v0
	v_mul_lo_u32 v98, v98, s11
	s_lshl_b32 s10, s10, 4
	v_and_or_b32 v0, v0, 56, v98
	v_mov_b32_e32 v98, v169
	s_and_b32 s10, s10, 0x380
	s_cmpk_gt_u32 s8, 0xff
	s_cselect_b32 s101, 1, 0
	v_lshrrev_b32_e32 v99, 3, v98
	v_add_u32_e32 v99, s10, v99
	v_lshlrev_b32_e32 v98, 3, v98
	v_mul_lo_u32 v99, v99, s11
	v_and_or_b32 v164, v98, 56, v99
	v_add_u32_e32 v114, 0x16000, v0
	v_add_u32_e32 v124, 0x2c000, v0
	v_add_u32_e32 v136, 0x42000, v0
	v_add_u32_e32 v174, 0x16000, v164
	v_add_u32_e32 v176, 0x2c000, v164
	v_add_u32_e32 v178, 0x42000, v164
	s_setprio 1
	ds_read_b128 v[98:101], v127 offset:16384
	ds_read_b128 v[110:113], v127 offset:18432
	ds_read_b128 v[144:147], v127 offset:20480
	ds_read_b128 v[148:151], v127 offset:22528
	ds_read_b128 v[102:105], v129
	ds_read_b128 v[106:109], v129 offset:2048
	ds_read_b128 v[132:135], v129 offset:4096
	ds_read_b128 v[140:143], v129 offset:6144
	v_lshrrev_b32_e32 v14, 3, v169
	v_and_b32_e32 v15, 3, v14
	v_bfe_u32 v16, v14, 4, 1
	v_lshl_or_b32 v15, v16, 2, v15
	v_bfe_u32 v16, v14, 2, 1
	v_lshl_or_b32 v15, v16, 3, v15
	v_bfe_u32 v16, v14, 3, 1
	v_lshl_or_b32 v15, v16, 4, v15
	v_sub_u32_e32 v15, v15, v14
	v_mul_i32_i24_e32 v15, 0xb00, v15
	v_and_b32_e32 v14, 7, v14
	v_lshlrev_b32_e32 v14, 3, v14
	v_xor_b32_e32 v0, v0, v14
	v_add_u32_e32 v164, v164, v15
	v_xor_b32_e32 v164, v164, v14
	v_xor_b32_e32 v114, v114, v14
	v_add_u32_e32 v174, v174, v15
	v_xor_b32_e32 v174, v174, v14
	v_xor_b32_e32 v124, v124, v14
	v_add_u32_e32 v176, v176, v15
	v_xor_b32_e32 v176, v176, v14
	v_xor_b32_e32 v136, v136, v14
	v_add_u32_e32 v178, v178, v15
	v_xor_b32_e32 v178, v178, v14
	v_readlane_b32 s14, v254, 33
	v_readlane_b32 s15, v254, 34
	v_mov_b32_e32 v165, v1
	v_mov_b32_e32 v115, v1
	v_mov_b32_e32 v175, v1
	v_mov_b32_e32 v125, v1
	v_mov_b32_e32 v177, v1
	v_mov_b32_e32 v137, v1
	v_mov_b32_e32 v179, v1
	v_lshl_add_u64 v[180:181], v[0:1], 1, s[14:15]
	v_lshl_add_u64 v[186:187], v[164:165], 1, s[38:39]
	v_lshl_add_u64 v[114:115], v[114:115], 1, s[14:15]
	v_lshl_add_u64 v[174:175], v[174:175], 1, s[38:39]
	v_lshl_add_u64 v[188:189], v[124:125], 1, s[14:15]
	v_lshl_add_u64 v[176:177], v[176:177], 1, s[38:39]
	v_lshl_add_u64 v[136:137], v[136:137], 1, s[14:15]
	v_lshl_add_u64 v[178:179], v[178:179], 1, s[38:39]
	s_add_u32 m0, s100, 0x8000
	s_waitcnt lgkmcnt(3)
	v_mfma_f32_16x16x32_bf16 v[152:155], v[98:101], v[102:105], v[34:37]
	global_load_lds_dwordx4 v2, s[98:99]
	v_mfma_f32_16x16x32_bf16 v[94:97], v[110:113], v[102:105], v[94:97]
	ds_read_b128 v[156:159], v128
	s_add_u32 m0, s100, 0xc000
	v_mfma_f32_16x16x32_bf16 v[160:163], v[144:147], v[102:105], v[38:41]
	global_load_lds_dwordx4 v3, s[98:99]
	v_mfma_f32_16x16x32_bf16 v[90:93], v[148:151], v[102:105], v[90:93]
	ds_read_b128 v[102:105], v128 offset:2048
	s_add_u32 m0, s100, 0x9000
	s_waitcnt lgkmcnt(4)
	v_mfma_f32_16x16x32_bf16 v[164:167], v[98:101], v[106:109], v[42:45]
	global_load_lds_dwordx4 v4, s[98:99]
	v_mfma_f32_16x16x32_bf16 v[86:89], v[110:113], v[106:109], v[86:89]
	ds_read_b128 v[194:197], v128 offset:4096
	s_add_u32 m0, s100, 0xd000
	v_mfma_f32_16x16x32_bf16 v[198:201], v[144:147], v[106:109], v[46:49]
	global_load_lds_dwordx4 v5, s[98:99]
	v_mfma_f32_16x16x32_bf16 v[82:85], v[148:151], v[106:109], v[82:85]
	ds_read_b128 v[106:109], v128 offset:6144
	s_add_u32 m0, s100, 0xa000
	s_waitcnt lgkmcnt(5)
	v_mfma_f32_16x16x32_bf16 v[202:205], v[98:101], v[132:135], v[50:53]
	global_load_lds_dwordx4 v6, s[98:99]
	v_mfma_f32_16x16x32_bf16 v[78:81], v[110:113], v[132:135], v[78:81]
	ds_read_b128 v[206:209], v130 offset:16384
	s_add_u32 m0, s100, 0xe000
	v_mfma_f32_16x16x32_bf16 v[210:213], v[144:147], v[132:135], v[54:57]
	global_load_lds_dwordx4 v7, s[98:99]
	v_mfma_f32_16x16x32_bf16 v[70:73], v[148:151], v[132:135], v[70:73]
	ds_read_b128 v[132:135], v130 offset:18432
	s_add_u32 m0, s100, 0xb000
	s_waitcnt lgkmcnt(6)
	v_mfma_f32_16x16x32_bf16 v[98:101], v[98:101], v[140:143], v[58:61]
	global_load_lds_dwordx4 v8, s[98:99]
	v_mfma_f32_16x16x32_bf16 v[66:69], v[110:113], v[140:143], v[66:69]
	ds_read_b128 v[110:113], v130 offset:20480
	s_add_u32 m0, s100, 0xf000
	v_mfma_f32_16x16x32_bf16 v[144:147], v[144:147], v[140:143], v[62:65]
	global_load_lds_dwordx4 v9, s[98:99]
	v_mfma_f32_16x16x32_bf16 v[74:77], v[148:151], v[140:143], v[74:77]
	ds_read_b128 v[140:143], v130 offset:22528
	s_waitcnt lgkmcnt(3)
	v_mfma_f32_16x16x32_bf16 v[148:151], v[206:209], v[156:159], v[152:155]
	s_waitcnt lgkmcnt(2)
	v_mfma_f32_16x16x32_bf16 v[94:97], v[132:135], v[156:159], v[94:97]
	s_waitcnt lgkmcnt(1)
	v_mfma_f32_16x16x32_bf16 v[152:155], v[110:113], v[156:159], v[160:163]
	s_waitcnt lgkmcnt(0)
	v_mfma_f32_16x16x32_bf16 v[90:93], v[140:143], v[156:159], v[90:93]
	v_mfma_f32_16x16x32_bf16 v[156:159], v[206:209], v[102:105], v[164:167]
	v_mfma_f32_16x16x32_bf16 v[86:89], v[132:135], v[102:105], v[86:89]
	v_mfma_f32_16x16x32_bf16 v[160:163], v[110:113], v[102:105], v[198:201]
	v_mfma_f32_16x16x32_bf16 v[82:85], v[140:143], v[102:105], v[82:85]
	v_mfma_f32_16x16x32_bf16 v[102:105], v[206:209], v[194:197], v[202:205]
	v_mfma_f32_16x16x32_bf16 v[78:81], v[132:135], v[194:197], v[78:81]
	v_mfma_f32_16x16x32_bf16 v[164:167], v[110:113], v[194:197], v[210:213]
	v_mfma_f32_16x16x32_bf16 v[70:73], v[140:143], v[194:197], v[70:73]
	v_mfma_f32_16x16x32_bf16 v[98:101], v[206:209], v[106:109], v[98:101]
	v_mfma_f32_16x16x32_bf16 v[66:69], v[132:135], v[106:109], v[66:69]
	v_mfma_f32_16x16x32_bf16 v[110:113], v[110:113], v[106:109], v[144:147]
	v_mfma_f32_16x16x32_bf16 v[74:77], v[140:143], v[106:109], v[74:77]
	s_waitcnt vmcnt(0)
	s_setprio 0
	s_waitcnt lgkmcnt(0)
	s_barrier
	s_setprio 1
	ds_read_b128 v[26:29], v127 offset:49152
	ds_read_b128 v[30:33], v127 offset:51200
	ds_read_b128 v[132:135], v127 offset:53248
	ds_read_b128 v[140:143], v127 offset:55296
	ds_read_b128 v[10:13], v129 offset:32768
	ds_read_b128 v[18:21], v129 offset:34816
	ds_read_b128 v[106:109], v129 offset:36864
	ds_read_b128 v[122:125], v129 offset:38912
	s_add_u32 m0, s100, 0x0
	s_waitcnt lgkmcnt(3)
	v_mfma_f32_16x16x32_bf16 v[144:147], v[26:29], v[10:13], v[148:151]
	global_load_lds_dwordx4 v[180:181], off
	v_mfma_f32_16x16x32_bf16 v[94:97], v[30:33], v[10:13], v[94:97]
	ds_read_b128 v[148:151], v128 offset:32768
	s_add_u32 m0, s100, 0x4000
	v_mfma_f32_16x16x32_bf16 v[152:155], v[132:135], v[10:13], v[152:155]
	global_load_lds_dwordx4 v[186:187], off
	v_mfma_f32_16x16x32_bf16 v[90:93], v[140:143], v[10:13], v[90:93]
	ds_read_b128 v[194:197], v128 offset:34816
	s_add_u32 m0, s100, 0x1000
	s_waitcnt lgkmcnt(4)
	v_mfma_f32_16x16x32_bf16 v[156:159], v[26:29], v[18:21], v[156:159]
	global_load_lds_dwordx4 v[114:115], off
	v_mfma_f32_16x16x32_bf16 v[86:89], v[30:33], v[18:21], v[86:89]
	ds_read_b128 v[198:201], v128 offset:36864
	s_add_u32 m0, s100, 0x5000
	v_mfma_f32_16x16x32_bf16 v[160:163], v[132:135], v[18:21], v[160:163]
	global_load_lds_dwordx4 v[174:175], off
	v_mfma_f32_16x16x32_bf16 v[82:85], v[140:143], v[18:21], v[82:85]
	ds_read_b128 v[126:129], v128 offset:38912
	s_add_u32 m0, s100, 0x2000
	s_waitcnt lgkmcnt(5)
	v_mfma_f32_16x16x32_bf16 v[202:205], v[26:29], v[106:109], v[102:105]
	global_load_lds_dwordx4 v[188:189], off
	v_mfma_f32_16x16x32_bf16 v[78:81], v[30:33], v[106:109], v[78:81]
	ds_read_b128 v[206:209], v130 offset:49152
	s_add_u32 m0, s100, 0x6000
	v_mfma_f32_16x16x32_bf16 v[164:167], v[132:135], v[106:109], v[164:167]
	global_load_lds_dwordx4 v[176:177], off
	v_mfma_f32_16x16x32_bf16 v[70:73], v[140:143], v[106:109], v[70:73]
	ds_read_b128 v[210:213], v130 offset:51200
	s_add_u32 m0, s100, 0x3000
	s_waitcnt lgkmcnt(6)
	v_mfma_f32_16x16x32_bf16 v[214:217], v[26:29], v[122:125], v[98:101]
	global_load_lds_dwordx4 v[136:137], off
	v_mfma_f32_16x16x32_bf16 v[66:69], v[30:33], v[122:125], v[66:69]
	ds_read_b128 v[218:221], v130 offset:53248
	s_add_u32 m0, s100, 0x7000
	v_mfma_f32_16x16x32_bf16 v[110:113], v[132:135], v[122:125], v[110:113]
	global_load_lds_dwordx4 v[178:179], off
	v_mfma_f32_16x16x32_bf16 v[122:125], v[140:143], v[122:125], v[74:77]
	s_waitcnt lgkmcnt(2)
	v_mfma_f32_16x16x32_bf16 v[132:135], v[206:209], v[148:151], v[144:147]
	s_waitcnt lgkmcnt(0)
	v_mfma_f32_16x16x32_bf16 v[144:147], v[218:221], v[148:151], v[152:155]
	ds_read_b128 v[152:155], v130 offset:55296
	v_mfma_f32_16x16x32_bf16 v[140:143], v[210:213], v[148:151], v[94:97]
	s_waitcnt lgkmcnt(0)
	v_mfma_f32_16x16x32_bf16 v[148:151], v[152:155], v[148:151], v[90:93]
	v_mfma_f32_16x16x32_bf16 v[98:101], v[152:155], v[194:197], v[82:85]
	v_mfma_f32_16x16x32_bf16 v[90:93], v[210:213], v[198:201], v[78:81]
	v_mfma_f32_16x16x32_bf16 v[82:85], v[152:155], v[198:201], v[70:73]
	v_mfma_f32_16x16x32_bf16 v[78:81], v[206:209], v[126:129], v[214:217]
	v_mfma_f32_16x16x32_bf16 v[74:77], v[210:213], v[126:129], v[66:69]
	v_mfma_f32_16x16x32_bf16 v[66:69], v[218:221], v[126:129], v[110:113]
	v_mfma_f32_16x16x32_bf16 v[70:73], v[152:155], v[126:129], v[122:125]
	v_mfma_f32_16x16x32_bf16 v[156:159], v[206:209], v[194:197], v[156:159]
	v_mfma_f32_16x16x32_bf16 v[106:109], v[210:213], v[194:197], v[86:89]
	v_mfma_f32_16x16x32_bf16 v[102:105], v[218:221], v[194:197], v[160:163]
	v_mfma_f32_16x16x32_bf16 v[94:97], v[206:209], v[198:201], v[202:205]
	v_mfma_f32_16x16x32_bf16 v[86:89], v[218:221], v[198:201], v[164:167]
	s_setprio 0
	v_add_u32_e32 v110, s4, v116
	v_ashrrev_i32_e32 v111, 31, v110
	v_readlane_b32 s44, v253, 18
	v_lshlrev_b64 v[112:113], 12, v[110:111]
	v_or_b32_e32 v0, s5, v117
	v_readlane_b32 s58, v253, 32
	v_readlane_b32 s59, v253, 33
	v_lshlrev_b64 v[114:115], 2, v[0:1]
	v_lshl_add_u64 v[166:167], v[110:111], 3, s[0:1]
	v_lshl_add_u64 v[112:113], s[58:59], 0, v[112:113]
	v_lshl_add_u64 v[164:165], v[112:113], 0, v[114:115]
	s_barrier
	global_load_dwordx2 v[130:131], v[166:167], off
	global_load_dwordx4 v[122:125], v[164:165], off
	v_lshl_add_u64 v[112:113], s[34:35], 0, v[114:115]
	v_lshl_add_u64 v[110:111], s[40:41], 0, v[114:115]
	global_load_dwordx4 v[126:129], v[112:113], off
	global_load_dwordx4 v[152:155], v[110:111], off
	s_mov_b32 s14, 0x3fb504f3
	global_load_dwordx4 v[160:163], v[164:165], off offset:16
	s_mov_b64 s[42:43], -1
	v_readlane_b32 s45, v253, 19
	v_readlane_b32 s46, v253, 20
	v_readlane_b32 s47, v253, 21
	v_readlane_b32 s48, v253, 22
	v_readlane_b32 s49, v253, 23
	v_readlane_b32 s50, v253, 24
	v_readlane_b32 s51, v253, 25
	v_readlane_b32 s52, v253, 26
	v_readlane_b32 s53, v253, 27
	v_readlane_b32 s54, v253, 28
	v_readlane_b32 s55, v253, 29
	v_readlane_b32 s56, v253, 30
	v_readlane_b32 s57, v253, 31
	s_waitcnt vmcnt(3)
	v_pk_add_f32 v[122:123], v[122:123], v[130:131] op_sel_hi:[1,0] neg_lo:[0,1] neg_hi:[0,1]
	v_pk_add_f32 v[124:125], v[124:125], v[130:131] op_sel_hi:[1,0] neg_lo:[0,1] neg_hi:[0,1]
	v_pk_mul_f32 v[122:123], v[122:123], v[130:131] op_sel:[0,1]
	v_pk_mul_f32 v[124:125], v[124:125], v[130:131] op_sel:[0,1]
	s_waitcnt vmcnt(1)
	v_pk_fma_f32 v[122:123], v[122:123], v[126:127], v[152:153]
	v_pk_fma_f32 v[124:125], v[124:125], v[128:129], v[154:155]
	v_pk_fma_f32 v[122:123], v[122:123], s[14:15], v[132:133] op_sel_hi:[1,0,1]
	v_pk_fma_f32 v[124:125], v[124:125], s[14:15], v[134:135] op_sel_hi:[1,0,1]
	global_store_dwordx4 v[164:165], v[122:125], off
	global_load_dwordx2 v[134:135], v[166:167], off
	global_load_dwordx4 v[126:129], v[110:111], off offset:16
	global_load_dwordx4 v[130:133], v[164:165], off offset:128
	s_waitcnt vmcnt(2)
	v_pk_add_f32 v[136:137], v[160:161], v[134:135] op_sel_hi:[1,0] neg_lo:[0,1] neg_hi:[0,1]
	global_load_dwordx4 v[122:125], v[112:113], off offset:16
	v_pk_add_f32 v[152:153], v[162:163], v[134:135] op_sel_hi:[1,0] neg_lo:[0,1] neg_hi:[0,1]
	v_pk_mul_f32 v[136:137], v[136:137], v[134:135] op_sel:[0,1]
	v_pk_mul_f32 v[134:135], v[152:153], v[134:135] op_sel:[0,1]
	s_waitcnt vmcnt(0)
	v_pk_fma_f32 v[122:123], v[136:137], v[122:123], v[126:127]
	v_pk_fma_f32 v[124:125], v[134:135], v[124:125], v[128:129]
	v_pk_fma_f32 v[122:123], v[122:123], s[14:15], v[140:141] op_sel_hi:[1,0,1]
	v_pk_fma_f32 v[124:125], v[124:125], s[14:15], v[142:143] op_sel_hi:[1,0,1]
	global_store_dwordx4 v[164:165], v[122:125], off offset:16
	global_load_dwordx2 v[140:141], v[166:167], off
	global_load_dwordx4 v[126:129], v[110:111], off offset:128
	global_load_dwordx4 v[134:137], v[164:165], off offset:144
	s_waitcnt vmcnt(2)
	v_pk_add_f32 v[130:131], v[130:131], v[140:141] op_sel_hi:[1,0] neg_lo:[0,1] neg_hi:[0,1]
	global_load_dwordx4 v[122:125], v[112:113], off offset:128
	v_pk_add_f32 v[132:133], v[132:133], v[140:141] op_sel_hi:[1,0] neg_lo:[0,1] neg_hi:[0,1]
	v_pk_mul_f32 v[130:131], v[130:131], v[140:141] op_sel:[0,1]
	v_pk_mul_f32 v[132:133], v[132:133], v[140:141] op_sel:[0,1]
	s_waitcnt vmcnt(0)
	v_pk_fma_f32 v[122:123], v[130:131], v[122:123], v[126:127]
	v_pk_fma_f32 v[124:125], v[132:133], v[124:125], v[128:129]
	v_pk_fma_f32 v[122:123], v[122:123], s[14:15], v[144:145] op_sel_hi:[1,0,1]
	v_pk_fma_f32 v[124:125], v[124:125], s[14:15], v[146:147] op_sel_hi:[1,0,1]
	global_store_dwordx4 v[164:165], v[122:125], off offset:128
	global_load_dwordx2 v[140:141], v[166:167], off
	global_load_dwordx4 v[126:129], v[110:111], off offset:144
	v_add_u32_e32 v130, s4, v118
	global_load_dwordx4 v[122:125], v[112:113], off offset:144
	v_ashrrev_i32_e32 v131, 31, v130
	v_lshlrev_b64 v[132:133], 12, v[130:131]
	v_lshl_add_u64 v[142:143], v[130:131], 3, s[0:1]
	v_lshl_add_u64 v[130:131], s[58:59], 0, v[132:133]
	v_lshl_add_u64 v[144:145], v[130:131], 0, v[114:115]
	global_load_dwordx4 v[130:133], v[144:145], off
	s_waitcnt vmcnt(3)
	v_pk_add_f32 v[134:135], v[134:135], v[140:141] op_sel_hi:[1,0] neg_lo:[0,1] neg_hi:[0,1]
	v_pk_add_f32 v[136:137], v[136:137], v[140:141] op_sel_hi:[1,0] neg_lo:[0,1] neg_hi:[0,1]
	v_pk_mul_f32 v[134:135], v[134:135], v[140:141] op_sel:[0,1]
	v_pk_mul_f32 v[136:137], v[136:137], v[140:141] op_sel:[0,1]
	s_waitcnt vmcnt(1)
	v_pk_fma_f32 v[122:123], v[134:135], v[122:123], v[126:127]
	v_pk_fma_f32 v[124:125], v[136:137], v[124:125], v[128:129]
	v_pk_fma_f32 v[122:123], v[122:123], s[14:15], v[148:149] op_sel_hi:[1,0,1]
	v_pk_fma_f32 v[124:125], v[124:125], s[14:15], v[150:151] op_sel_hi:[1,0,1]
	global_store_dwordx4 v[164:165], v[122:125], off offset:144
	global_load_dwordx2 v[140:141], v[142:143], off
	global_load_dwordx4 v[126:129], v[110:111], off
	global_load_dwordx4 v[134:137], v[144:145], off offset:16
	s_waitcnt vmcnt(2)
	v_pk_add_f32 v[130:131], v[130:131], v[140:141] op_sel_hi:[1,0] neg_lo:[0,1] neg_hi:[0,1]
	global_load_dwordx4 v[122:125], v[112:113], off
	v_pk_add_f32 v[132:133], v[132:133], v[140:141] op_sel_hi:[1,0] neg_lo:[0,1] neg_hi:[0,1]
	v_pk_mul_f32 v[130:131], v[130:131], v[140:141] op_sel:[0,1]
	v_pk_mul_f32 v[132:133], v[132:133], v[140:141] op_sel:[0,1]
	s_waitcnt vmcnt(0)
	v_pk_fma_f32 v[122:123], v[130:131], v[122:123], v[126:127]
	v_pk_fma_f32 v[124:125], v[132:133], v[124:125], v[128:129]
	v_pk_fma_f32 v[122:123], v[122:123], s[14:15], v[156:157] op_sel_hi:[1,0,1]
	v_pk_fma_f32 v[124:125], v[124:125], s[14:15], v[158:159] op_sel_hi:[1,0,1]
	global_store_dwordx4 v[144:145], v[122:125], off
	global_load_dwordx2 v[140:141], v[142:143], off
	global_load_dwordx4 v[126:129], v[110:111], off offset:16
	global_load_dwordx4 v[130:133], v[144:145], off offset:128
	s_waitcnt vmcnt(2)
	v_pk_add_f32 v[134:135], v[134:135], v[140:141] op_sel_hi:[1,0] neg_lo:[0,1] neg_hi:[0,1]
	global_load_dwordx4 v[122:125], v[112:113], off offset:16
	v_pk_add_f32 v[136:137], v[136:137], v[140:141] op_sel_hi:[1,0] neg_lo:[0,1] neg_hi:[0,1]
	v_pk_mul_f32 v[134:135], v[134:135], v[140:141] op_sel:[0,1]
	v_pk_mul_f32 v[136:137], v[136:137], v[140:141] op_sel:[0,1]
	s_waitcnt vmcnt(0)
	v_pk_fma_f32 v[122:123], v[134:135], v[122:123], v[126:127]
	v_pk_fma_f32 v[124:125], v[136:137], v[124:125], v[128:129]
	v_pk_fma_f32 v[106:107], v[122:123], s[14:15], v[106:107] op_sel_hi:[1,0,1]
	v_pk_fma_f32 v[108:109], v[124:125], s[14:15], v[108:109] op_sel_hi:[1,0,1]
	global_store_dwordx4 v[144:145], v[106:109], off offset:16
	global_load_dwordx2 v[134:135], v[142:143], off
	global_load_dwordx4 v[122:125], v[110:111], off offset:128
	global_load_dwordx4 v[126:129], v[144:145], off offset:144
	s_waitcnt vmcnt(2)
	v_pk_add_f32 v[130:131], v[130:131], v[134:135] op_sel_hi:[1,0] neg_lo:[0,1] neg_hi:[0,1]
	global_load_dwordx4 v[106:109], v[112:113], off offset:128
	v_pk_add_f32 v[132:133], v[132:133], v[134:135] op_sel_hi:[1,0] neg_lo:[0,1] neg_hi:[0,1]
	v_pk_mul_f32 v[130:131], v[130:131], v[134:135] op_sel:[0,1]
	v_pk_mul_f32 v[132:133], v[132:133], v[134:135] op_sel:[0,1]
	s_waitcnt vmcnt(0)
	v_pk_fma_f32 v[106:107], v[130:131], v[106:107], v[122:123]
	v_pk_fma_f32 v[108:109], v[132:133], v[108:109], v[124:125]
	v_pk_fma_f32 v[102:103], v[106:107], s[14:15], v[102:103] op_sel_hi:[1,0,1]
	v_pk_fma_f32 v[104:105], v[108:109], s[14:15], v[104:105] op_sel_hi:[1,0,1]
	global_store_dwordx4 v[144:145], v[102:105], off offset:128
	global_load_dwordx2 v[130:131], v[142:143], off
	global_load_dwordx4 v[106:109], v[110:111], off offset:144
	v_add_u32_e32 v122, s4, v119
	global_load_dwordx4 v[102:105], v[112:113], off offset:144
	v_ashrrev_i32_e32 v123, 31, v122
	v_lshlrev_b64 v[124:125], 12, v[122:123]
	v_lshl_add_u64 v[132:133], v[122:123], 3, s[0:1]
	v_lshl_add_u64 v[122:123], s[58:59], 0, v[124:125]
	v_lshl_add_u64 v[134:135], v[122:123], 0, v[114:115]
	global_load_dwordx4 v[122:125], v[134:135], off
	s_waitcnt vmcnt(3)
	v_pk_add_f32 v[126:127], v[126:127], v[130:131] op_sel_hi:[1,0] neg_lo:[0,1] neg_hi:[0,1]
	v_pk_add_f32 v[128:129], v[128:129], v[130:131] op_sel_hi:[1,0] neg_lo:[0,1] neg_hi:[0,1]
	v_pk_mul_f32 v[126:127], v[126:127], v[130:131] op_sel:[0,1]
	v_pk_mul_f32 v[128:129], v[128:129], v[130:131] op_sel:[0,1]
	s_waitcnt vmcnt(1)
	v_pk_fma_f32 v[102:103], v[126:127], v[102:103], v[106:107]
	v_pk_fma_f32 v[104:105], v[128:129], v[104:105], v[108:109]
	v_pk_fma_f32 v[98:99], v[102:103], s[14:15], v[98:99] op_sel_hi:[1,0,1]
	v_pk_fma_f32 v[100:101], v[104:105], s[14:15], v[100:101] op_sel_hi:[1,0,1]
	global_store_dwordx4 v[144:145], v[98:101], off offset:144
	global_load_dwordx2 v[126:127], v[132:133], off
	global_load_dwordx4 v[102:105], v[110:111], off
	global_load_dwordx4 v[106:109], v[134:135], off offset:16
	s_waitcnt vmcnt(2)
	v_pk_add_f32 v[122:123], v[122:123], v[126:127] op_sel_hi:[1,0] neg_lo:[0,1] neg_hi:[0,1]
	global_load_dwordx4 v[98:101], v[112:113], off
	v_pk_add_f32 v[124:125], v[124:125], v[126:127] op_sel_hi:[1,0] neg_lo:[0,1] neg_hi:[0,1]
	v_pk_mul_f32 v[122:123], v[122:123], v[126:127] op_sel:[0,1]
	v_pk_mul_f32 v[124:125], v[124:125], v[126:127] op_sel:[0,1]
	s_waitcnt vmcnt(0)
	v_pk_fma_f32 v[98:99], v[122:123], v[98:99], v[102:103]
	v_pk_fma_f32 v[100:101], v[124:125], v[100:101], v[104:105]
	v_pk_fma_f32 v[94:95], v[98:99], s[14:15], v[94:95] op_sel_hi:[1,0,1]
	v_pk_fma_f32 v[96:97], v[100:101], s[14:15], v[96:97] op_sel_hi:[1,0,1]
	global_store_dwordx4 v[134:135], v[94:97], off
	global_load_dwordx2 v[122:123], v[132:133], off
	global_load_dwordx4 v[98:101], v[110:111], off offset:16
	global_load_dwordx4 v[102:105], v[134:135], off offset:128
	s_waitcnt vmcnt(2)
	v_pk_add_f32 v[106:107], v[106:107], v[122:123] op_sel_hi:[1,0] neg_lo:[0,1] neg_hi:[0,1]
	global_load_dwordx4 v[94:97], v[112:113], off offset:16
	v_pk_add_f32 v[108:109], v[108:109], v[122:123] op_sel_hi:[1,0] neg_lo:[0,1] neg_hi:[0,1]
	v_pk_mul_f32 v[106:107], v[106:107], v[122:123] op_sel:[0,1]
	v_pk_mul_f32 v[108:109], v[108:109], v[122:123] op_sel:[0,1]
	s_waitcnt vmcnt(0)
	v_pk_fma_f32 v[94:95], v[106:107], v[94:95], v[98:99]
	v_pk_fma_f32 v[96:97], v[108:109], v[96:97], v[100:101]
	v_pk_fma_f32 v[90:91], v[94:95], s[14:15], v[90:91] op_sel_hi:[1,0,1]
	v_pk_fma_f32 v[92:93], v[96:97], s[14:15], v[92:93] op_sel_hi:[1,0,1]
	global_store_dwordx4 v[134:135], v[90:93], off offset:16
	global_load_dwordx2 v[106:107], v[132:133], off
	global_load_dwordx4 v[94:97], v[110:111], off offset:128
	global_load_dwordx4 v[98:101], v[134:135], off offset:144
	s_waitcnt vmcnt(2)
	v_pk_add_f32 v[102:103], v[102:103], v[106:107] op_sel_hi:[1,0] neg_lo:[0,1] neg_hi:[0,1]
	global_load_dwordx4 v[90:93], v[112:113], off offset:128
	v_pk_add_f32 v[104:105], v[104:105], v[106:107] op_sel_hi:[1,0] neg_lo:[0,1] neg_hi:[0,1]
	v_pk_mul_f32 v[102:103], v[102:103], v[106:107] op_sel:[0,1]
	v_pk_mul_f32 v[104:105], v[104:105], v[106:107] op_sel:[0,1]
	s_waitcnt vmcnt(0)
	v_pk_fma_f32 v[90:91], v[102:103], v[90:91], v[94:95]
	v_pk_fma_f32 v[92:93], v[104:105], v[92:93], v[96:97]
	v_pk_fma_f32 v[86:87], v[90:91], s[14:15], v[86:87] op_sel_hi:[1,0,1]
	v_pk_fma_f32 v[88:89], v[92:93], s[14:15], v[88:89] op_sel_hi:[1,0,1]
	global_store_dwordx4 v[134:135], v[86:89], off offset:128
	global_load_dwordx2 v[102:103], v[132:133], off
	global_load_dwordx4 v[90:93], v[110:111], off offset:144
	v_add_u32_e32 v94, s4, v120
	global_load_dwordx4 v[86:89], v[112:113], off offset:144
	v_ashrrev_i32_e32 v95, 31, v94
	v_lshlrev_b64 v[96:97], 12, v[94:95]
	v_lshl_add_u64 v[104:105], v[94:95], 3, s[0:1]
	v_lshl_add_u64 v[94:95], s[58:59], 0, v[96:97]
	v_lshl_add_u64 v[106:107], v[94:95], 0, v[114:115]
	global_load_dwordx4 v[94:97], v[106:107], off
	s_waitcnt vmcnt(3)
	v_pk_add_f32 v[98:99], v[98:99], v[102:103] op_sel_hi:[1,0] neg_lo:[0,1] neg_hi:[0,1]
	v_pk_add_f32 v[100:101], v[100:101], v[102:103] op_sel_hi:[1,0] neg_lo:[0,1] neg_hi:[0,1]
	v_pk_mul_f32 v[98:99], v[98:99], v[102:103] op_sel:[0,1]
	v_pk_mul_f32 v[100:101], v[100:101], v[102:103] op_sel:[0,1]
	s_waitcnt vmcnt(1)
	v_pk_fma_f32 v[86:87], v[98:99], v[86:87], v[90:91]
	v_pk_fma_f32 v[88:89], v[100:101], v[88:89], v[92:93]
	v_pk_fma_f32 v[82:83], v[86:87], s[14:15], v[82:83] op_sel_hi:[1,0,1]
	v_pk_fma_f32 v[84:85], v[88:89], s[14:15], v[84:85] op_sel_hi:[1,0,1]
	global_store_dwordx4 v[134:135], v[82:85], off offset:144
	global_load_dwordx2 v[98:99], v[104:105], off
	global_load_dwordx4 v[86:89], v[110:111], off
	global_load_dwordx4 v[90:93], v[106:107], off offset:16
	s_waitcnt vmcnt(2)
	v_pk_add_f32 v[94:95], v[94:95], v[98:99] op_sel_hi:[1,0] neg_lo:[0,1] neg_hi:[0,1]
	global_load_dwordx4 v[82:85], v[112:113], off
	v_pk_add_f32 v[96:97], v[96:97], v[98:99] op_sel_hi:[1,0] neg_lo:[0,1] neg_hi:[0,1]
	v_pk_mul_f32 v[94:95], v[94:95], v[98:99] op_sel:[0,1]
	v_pk_mul_f32 v[96:97], v[96:97], v[98:99] op_sel:[0,1]
	s_waitcnt vmcnt(0)
	v_pk_fma_f32 v[82:83], v[94:95], v[82:83], v[86:87]
	v_pk_fma_f32 v[84:85], v[96:97], v[84:85], v[88:89]
	v_pk_fma_f32 v[78:79], v[82:83], s[14:15], v[78:79] op_sel_hi:[1,0,1]
	v_pk_fma_f32 v[80:81], v[84:85], s[14:15], v[80:81] op_sel_hi:[1,0,1]
	global_store_dwordx4 v[106:107], v[78:81], off
	global_load_dwordx2 v[94:95], v[104:105], off
	global_load_dwordx4 v[82:85], v[110:111], off offset:16
	global_load_dwordx4 v[86:89], v[106:107], off offset:128
	s_waitcnt vmcnt(2)
	v_pk_add_f32 v[90:91], v[90:91], v[94:95] op_sel_hi:[1,0] neg_lo:[0,1] neg_hi:[0,1]
	global_load_dwordx4 v[78:81], v[112:113], off offset:16
	v_pk_add_f32 v[92:93], v[92:93], v[94:95] op_sel_hi:[1,0] neg_lo:[0,1] neg_hi:[0,1]
	v_pk_mul_f32 v[90:91], v[90:91], v[94:95] op_sel:[0,1]
	v_pk_mul_f32 v[92:93], v[92:93], v[94:95] op_sel:[0,1]
	s_waitcnt vmcnt(0)
	v_pk_fma_f32 v[78:79], v[90:91], v[78:79], v[82:83]
	v_pk_fma_f32 v[80:81], v[92:93], v[80:81], v[84:85]
	v_pk_fma_f32 v[74:75], v[78:79], s[14:15], v[74:75] op_sel_hi:[1,0,1]
	v_pk_fma_f32 v[76:77], v[80:81], s[14:15], v[76:77] op_sel_hi:[1,0,1]
	global_store_dwordx4 v[106:107], v[74:77], off offset:16
	global_load_dwordx2 v[90:91], v[104:105], off
	global_load_dwordx4 v[78:81], v[110:111], off offset:128
	global_load_dwordx4 v[82:85], v[106:107], off offset:144
	s_waitcnt vmcnt(2)
	v_pk_add_f32 v[86:87], v[86:87], v[90:91] op_sel_hi:[1,0] neg_lo:[0,1] neg_hi:[0,1]
	global_load_dwordx4 v[74:77], v[112:113], off offset:128
	v_pk_add_f32 v[88:89], v[88:89], v[90:91] op_sel_hi:[1,0] neg_lo:[0,1] neg_hi:[0,1]
	v_pk_mul_f32 v[86:87], v[86:87], v[90:91] op_sel:[0,1]
	v_pk_mul_f32 v[88:89], v[88:89], v[90:91] op_sel:[0,1]
	s_waitcnt vmcnt(0)
	v_pk_fma_f32 v[74:75], v[86:87], v[74:75], v[78:79]
	v_pk_fma_f32 v[76:77], v[88:89], v[76:77], v[80:81]
	v_pk_fma_f32 v[66:67], v[74:75], s[14:15], v[66:67] op_sel_hi:[1,0,1]
	v_pk_fma_f32 v[68:69], v[76:77], s[14:15], v[68:69] op_sel_hi:[1,0,1]
	global_store_dwordx4 v[106:107], v[66:69], off offset:128
	global_load_dwordx2 v[78:79], v[104:105], off
	global_load_dwordx4 v[74:77], v[110:111], off offset:144
	s_waitcnt vmcnt(1)
	v_pk_add_f32 v[80:81], v[82:83], v[78:79] op_sel_hi:[1,0] neg_lo:[0,1] neg_hi:[0,1]
	global_load_dwordx4 v[66:69], v[112:113], off offset:144
	v_pk_add_f32 v[82:83], v[84:85], v[78:79] op_sel_hi:[1,0] neg_lo:[0,1] neg_hi:[0,1]
	v_pk_mul_f32 v[80:81], v[80:81], v[78:79] op_sel:[0,1]
	v_pk_mul_f32 v[78:79], v[82:83], v[78:79] op_sel:[0,1]
	s_waitcnt vmcnt(0)
	v_pk_fma_f32 v[66:67], v[80:81], v[66:67], v[74:75]
	v_pk_fma_f32 v[68:69], v[78:79], v[68:69], v[76:77]
	v_pk_fma_f32 v[66:67], v[66:67], s[14:15], v[70:71] op_sel_hi:[1,0,1]
	v_pk_fma_f32 v[68:69], v[68:69], s[14:15], v[72:73] op_sel_hi:[1,0,1]
	global_store_dwordx4 v[106:107], v[66:69], off offset:144
	s_cmp_lg_u32 s101, 0
	s_cbranch_scc1 .LBB0_126
	v_mov_b32_e32 v0, v169
	v_mov_b32_e32 v67, v169
	s_movk_i32 s4, 0xb00
	v_lshrrev_b32_e32 v66, 3, v0
	v_lshrrev_b32_e32 v69, 3, v67
	v_add_u32_e32 v66, s9, v66
	v_add_u32_e32 v69, s10, v69
	v_lshlrev_b32_e32 v0, 3, v0
	v_mul_lo_u32 v66, v66, s4
	v_lshlrev_b32_e32 v67, 3, v67
	v_mul_lo_u32 v69, v69, s4
	v_and_or_b32 v0, v0, 56, v66
	v_and_or_b32 v72, v67, 56, v69
	v_add_u32_e32 v66, 0x16000, v0
	v_add_u32_e32 v68, 0x2c000, v0
	v_add_u32_e32 v70, 0x42000, v0
	v_add_u32_e32 v74, 0x16000, v72
	v_add_u32_e32 v76, 0x2c000, v72
	v_add_u32_e32 v78, 0x42000, v72
	s_mov_b64 s[42:43], 0
	s_branch .LBB0_126

.LBB0_132:
	s_andn2_b64 vcc, exec, s[28:29]
	s_cbranch_vccnz .LBB0_140
	v_readlane_b32 s0, v254, 41
	v_readlane_b32 s1, v254, 42
	s_mov_b64 s[28:29], 0
	v_mov_b32_e32 v80, v169
	s_andn2_b64 vcc, exec, s[0:1]
	s_cbranch_vccnz .LBB0_140
	s_add_u32 s28, s72, s28
	v_readlane_b32 s0, v255, 36
	s_addc_u32 s29, s73, s29
	v_readlane_b32 s1, v255, 37
	s_add_u32 s38, s28, 0x4991000
	s_mul_hi_i32 s1, s0, 0xb00000
	s_mul_i32 s0, s0, 0xb00000
	s_addc_u32 s39, s29, 0
	s_add_u32 s2, s28, s0
	s_addc_u32 s4, s29, s1
	v_mov_b32_e32 v0, v169
	s_add_u32 s42, s2, 0x1e80000
	s_load_dword s2, s[22:23], 0x0
	s_addc_u32 s43, s4, 0
	s_waitcnt vmcnt(7)
	v_lshrrev_b32_e32 v2, 3, v0
	v_readlane_b32 s4, v254, 43
	v_lshlrev_b32_e32 v0, 3, v0
	v_and_b32_e32 v0, 56, v0
	v_add_u32_e32 v2, s4, v2
	v_lshl_or_b32 v0, v2, 10, v0
	v_mov_b32_e32 v2, v169
	v_readlane_b32 s10, v254, 44
	v_lshrrev_b32_e32 v3, 3, v2
	v_lshlrev_b32_e32 v2, 3, v2
	v_add_u32_e32 v3, s10, v3
	v_and_b32_e32 v2, 56, v2
	v_lshl_or_b32 v72, v3, 10, v2
	s_waitcnt lgkmcnt(0)
	v_add_u32_e32 v66, 0x8000, v0
	v_add_u32_e32 v68, 0x10000, v0
	v_add_u32_e32 v70, 0x18000, v0
	v_add_u32_e32 v74, 0x8000, v72
	v_add_u32_e32 v76, 0x10000, v72
	v_add_u32_e32 v78, 0x18000, v72
	v_mov_b32_e32 v73, v1
	v_mov_b32_e32 v67, v1
	v_mov_b32_e32 v75, v1
	v_mov_b32_e32 v69, v1
	v_mov_b32_e32 v77, v1
	v_mov_b32_e32 v71, v1
	v_mov_b32_e32 v79, v1
	v_lshl_add_u64 v[2:3], v[0:1], 1, s[38:39]
	s_waitcnt vmcnt(6)
	v_lshl_add_u64 v[6:7], v[72:73], 1, s[42:43]
	s_waitcnt vmcnt(5)
	v_lshl_add_u64 v[10:11], v[66:67], 1, s[38:39]
	s_waitcnt vmcnt(4)
	v_lshl_add_u64 v[14:15], v[74:75], 1, s[42:43]
	s_waitcnt vmcnt(3)
	v_lshl_add_u64 v[18:19], v[68:69], 1, s[38:39]
	s_waitcnt vmcnt(2)
	v_lshl_add_u64 v[22:23], v[76:77], 1, s[42:43]
	s_waitcnt vmcnt(1)
	v_lshl_add_u64 v[26:27], v[70:71], 1, s[38:39]
	s_waitcnt vmcnt(0)
	v_lshl_add_u64 v[30:31], v[78:79], 1, s[42:43]
	v_lshrrev_b32_e32 v34, 6, v169
	v_lshlrev_b32_e32 v34, 10, v34
	s_nop 0
	v_readfirstlane_b32 s100, v34
	v_lshrrev_b32_e32 v35, 3, v169
	v_and_b32_e32 v36, 3, v35
	v_bfe_u32 v37, v35, 4, 1
	v_lshl_or_b32 v36, v37, 2, v36
	v_bfe_u32 v37, v35, 2, 1
	v_lshl_or_b32 v36, v37, 3, v36
	v_bfe_u32 v37, v35, 3, 1
	v_lshl_or_b32 v36, v37, 4, v36
	v_sub_u32_e32 v36, v36, v35
	v_mul_i32_i24_e32 v36, 0x800, v36
	v_and_b32_e32 v35, 7, v35
	v_lshlrev_b32_e32 v35, 4, v35
	v_ashrrev_i32_e32 v37, 31, v36
	v_xor_b32_e32 v2, v2, v35
	v_lshl_add_u64 v[6:7], v[6:7], 0, v[36:37]
	v_xor_b32_e32 v6, v6, v35
	v_xor_b32_e32 v10, v10, v35
	v_lshl_add_u64 v[14:15], v[14:15], 0, v[36:37]
	v_xor_b32_e32 v14, v14, v35
	v_xor_b32_e32 v18, v18, v35
	v_lshl_add_u64 v[22:23], v[22:23], 0, v[36:37]
	v_xor_b32_e32 v22, v22, v35
	v_xor_b32_e32 v26, v26, v35
	v_lshl_add_u64 v[30:31], v[30:31], 0, v[36:37]
	v_xor_b32_e32 v30, v30, v35
	s_add_u32 m0, s100, 0x0
	s_nop 0
	global_load_lds_dwordx4 v[2:3], off
	s_add_u32 m0, s100, 0x4000
	s_nop 0
	global_load_lds_dwordx4 v[6:7], off
	s_add_u32 m0, s100, 0x1000
	s_nop 0
	global_load_lds_dwordx4 v[10:11], off
	s_add_u32 m0, s100, 0x5000
	s_nop 0
	global_load_lds_dwordx4 v[14:15], off
	s_add_u32 m0, s100, 0x2000
	s_nop 0
	global_load_lds_dwordx4 v[18:19], off
	s_add_u32 m0, s100, 0x6000
	s_nop 0
	global_load_lds_dwordx4 v[22:23], off
	s_add_u32 m0, s100, 0x3000
	s_nop 0
	global_load_lds_dwordx4 v[26:27], off
	s_add_u32 m0, s100, 0x7000
	s_nop 0
	global_load_lds_dwordx4 v[30:31], off
	s_waitcnt vmcnt(0)
	v_and_b32_e32 v67, 15, v80
	v_ashrrev_i32_e32 v69, 1, v80
	s_movk_i32 s5, 0xffc0
	v_and_or_b32 v118, v69, s5, v67
	v_lshrrev_b32_e32 v67, 1, v80
	s_add_u32 s44, s28, 0xa991000
	v_and_b32_e32 v119, 64, v80
	v_and_b32_e32 v80, 24, v67
	s_addc_u32 s45, s29, 0
	s_waitcnt lgkmcnt(0)
	s_lshr_b32 s2, s2, 3
	v_or_b32_e32 v120, 16, v118
	v_or_b32_e32 v121, 32, v118
	v_or_b32_e32 v122, 48, v118
	v_lshlrev_b32_e32 v98, 1, v80
	v_readlane_b32 s9, v254, 57
	s_branch .LBB0_136

.LBB0_137:
	s_setprio 1
	s_add_u32 s98, s46, s16
	s_addc_u32 s99, s47, 0
	s_add_u32 s98, s98, 0x80
	s_addc_u32 s99, s99, 0
	ds_read_b128 v[132:135], v128 offset:16384
	ds_read_b128 v[152:155], v128 offset:18432
	ds_read_b128 v[160:163], v128 offset:20480
	ds_read_b128 v[164:167], v128 offset:22528
	ds_read_b128 v[140:143], v130
	ds_read_b128 v[144:147], v130 offset:2048
	ds_read_b128 v[148:151], v130 offset:4096
	ds_read_b128 v[156:159], v130 offset:6144
	s_add_u32 m0, s100, 0x8000
	s_waitcnt lgkmcnt(3)
	v_mfma_f32_16x16x32_bf16 v[34:37], v[132:135], v[140:143], v[34:37]
	global_load_lds_dwordx4 v194, s[98:99]
	v_mfma_f32_16x16x32_bf16 v[94:97], v[152:155], v[140:143], v[94:97]
	ds_read_b128 v[198:201], v129
	s_add_u32 m0, s100, 0xc000
	v_mfma_f32_16x16x32_bf16 v[38:41], v[160:163], v[140:143], v[38:41]
	global_load_lds_dwordx4 v195, s[98:99]
	v_mfma_f32_16x16x32_bf16 v[90:93], v[164:167], v[140:143], v[90:93]
	ds_read_b128 v[140:143], v129 offset:2048
	s_add_u32 m0, s100, 0x9000
	s_waitcnt lgkmcnt(4)
	v_mfma_f32_16x16x32_bf16 v[42:45], v[132:135], v[144:147], v[42:45]
	global_load_lds_dwordx4 v196, s[98:99]
	v_mfma_f32_16x16x32_bf16 v[86:89], v[152:155], v[144:147], v[86:89]
	ds_read_b128 v[210:213], v129 offset:4096
	s_add_u32 m0, s100, 0xd000
	v_mfma_f32_16x16x32_bf16 v[46:49], v[160:163], v[144:147], v[46:49]
	global_load_lds_dwordx4 v197, s[98:99]
	v_mfma_f32_16x16x32_bf16 v[82:85], v[164:167], v[144:147], v[82:85]
	ds_read_b128 v[144:147], v129 offset:6144
	s_add_u32 m0, s100, 0xa000
	s_waitcnt lgkmcnt(5)
	v_mfma_f32_16x16x32_bf16 v[50:53], v[132:135], v[148:151], v[50:53]
	global_load_lds_dwordx4 v202, s[98:99]
	v_mfma_f32_16x16x32_bf16 v[78:81], v[152:155], v[148:151], v[78:81]
	ds_read_b128 v[222:225], v131 offset:16384
	s_add_u32 m0, s100, 0xe000
	v_mfma_f32_16x16x32_bf16 v[54:57], v[160:163], v[148:151], v[54:57]
	global_load_lds_dwordx4 v203, s[98:99]
	v_mfma_f32_16x16x32_bf16 v[70:73], v[164:167], v[148:151], v[70:73]
	ds_read_b128 v[148:151], v131 offset:18432
	s_add_u32 m0, s100, 0xb000
	s_waitcnt lgkmcnt(6)
	v_mfma_f32_16x16x32_bf16 v[58:61], v[132:135], v[156:159], v[58:61]
	global_load_lds_dwordx4 v204, s[98:99]
	v_mfma_f32_16x16x32_bf16 v[66:69], v[152:155], v[156:159], v[66:69]
	ds_read_b128 v[152:155], v131 offset:20480
	s_add_u32 m0, s100, 0xf000
	v_mfma_f32_16x16x32_bf16 v[62:65], v[160:163], v[156:159], v[62:65]
	global_load_lds_dwordx4 v205, s[98:99]
	v_mfma_f32_16x16x32_bf16 v[74:77], v[164:167], v[156:159], v[74:77]
	ds_read_b128 v[156:159], v131 offset:22528
	s_waitcnt lgkmcnt(3)
	v_mfma_f32_16x16x32_bf16 v[34:37], v[222:225], v[198:201], v[34:37]
	s_waitcnt lgkmcnt(2)
	v_mfma_f32_16x16x32_bf16 v[94:97], v[148:151], v[198:201], v[94:97]
	s_waitcnt lgkmcnt(1)
	v_mfma_f32_16x16x32_bf16 v[38:41], v[152:155], v[198:201], v[38:41]
	s_waitcnt lgkmcnt(0)
	v_mfma_f32_16x16x32_bf16 v[90:93], v[156:159], v[198:201], v[90:93]
	v_mfma_f32_16x16x32_bf16 v[42:45], v[222:225], v[140:143], v[42:45]
	v_mfma_f32_16x16x32_bf16 v[86:89], v[148:151], v[140:143], v[86:89]
	v_mfma_f32_16x16x32_bf16 v[46:49], v[152:155], v[140:143], v[46:49]
	v_mfma_f32_16x16x32_bf16 v[82:85], v[156:159], v[140:143], v[82:85]
	v_mfma_f32_16x16x32_bf16 v[50:53], v[222:225], v[210:213], v[50:53]
	v_mfma_f32_16x16x32_bf16 v[78:81], v[148:151], v[210:213], v[78:81]
	v_mfma_f32_16x16x32_bf16 v[54:57], v[152:155], v[210:213], v[54:57]
	v_mfma_f32_16x16x32_bf16 v[70:73], v[156:159], v[210:213], v[70:73]
	v_mfma_f32_16x16x32_bf16 v[58:61], v[222:225], v[144:147], v[58:61]
	v_mfma_f32_16x16x32_bf16 v[66:69], v[148:151], v[144:147], v[66:69]
	v_mfma_f32_16x16x32_bf16 v[62:65], v[152:155], v[144:147], v[62:65]
	v_mfma_f32_16x16x32_bf16 v[74:77], v[156:159], v[144:147], v[74:77]
	s_waitcnt vmcnt(0)
	s_setprio 0
	s_waitcnt lgkmcnt(0)
	s_barrier
	s_setprio 1
	s_add_u32 s98, s98, 0x80
	s_addc_u32 s99, s99, 0
	ds_read_b128 v[26:29], v128 offset:49152
	ds_read_b128 v[30:33], v128 offset:51200
	ds_read_b128 v[148:151], v128 offset:53248
	ds_read_b128 v[152:155], v128 offset:55296
	ds_read_b128 v[10:13], v130 offset:32768
	ds_read_b128 v[18:21], v130 offset:34816
	ds_read_b128 v[140:143], v130 offset:36864
	ds_read_b128 v[144:147], v130 offset:38912
	s_add_u32 m0, s100, 0x0
	s_waitcnt lgkmcnt(3)
	v_mfma_f32_16x16x32_bf16 v[34:37], v[26:29], v[10:13], v[34:37]
	global_load_lds_dwordx4 v194, s[98:99]
	v_mfma_f32_16x16x32_bf16 v[94:97], v[30:33], v[10:13], v[94:97]
	ds_read_b128 v[156:159], v129 offset:32768
	s_add_u32 m0, s100, 0x4000
	v_mfma_f32_16x16x32_bf16 v[38:41], v[148:151], v[10:13], v[38:41]
	global_load_lds_dwordx4 v195, s[98:99]
	v_mfma_f32_16x16x32_bf16 v[90:93], v[152:155], v[10:13], v[90:93]
	ds_read_b128 v[164:167], v129 offset:34816
	s_add_u32 m0, s100, 0x1000
	s_waitcnt lgkmcnt(4)
	v_mfma_f32_16x16x32_bf16 v[42:45], v[26:29], v[18:21], v[42:45]
	global_load_lds_dwordx4 v196, s[98:99]
	v_mfma_f32_16x16x32_bf16 v[86:89], v[30:33], v[18:21], v[86:89]
	ds_read_b128 v[198:201], v129 offset:36864
	s_add_u32 m0, s100, 0x5000
	v_mfma_f32_16x16x32_bf16 v[46:49], v[148:151], v[18:21], v[46:49]
	global_load_lds_dwordx4 v197, s[98:99]
	v_mfma_f32_16x16x32_bf16 v[82:85], v[152:155], v[18:21], v[82:85]
	ds_read_b128 v[210:213], v129 offset:38912
	s_add_u32 m0, s100, 0x2000
	s_waitcnt lgkmcnt(5)
	v_mfma_f32_16x16x32_bf16 v[50:53], v[26:29], v[140:143], v[50:53]
	global_load_lds_dwordx4 v202, s[98:99]
	v_mfma_f32_16x16x32_bf16 v[78:81], v[30:33], v[140:143], v[78:81]
	ds_read_b128 v[222:225], v131 offset:49152
	s_add_u32 m0, s100, 0x6000
	v_mfma_f32_16x16x32_bf16 v[54:57], v[148:151], v[140:143], v[54:57]
	global_load_lds_dwordx4 v203, s[98:99]
	v_mfma_f32_16x16x32_bf16 v[70:73], v[152:155], v[140:143], v[70:73]
	ds_read_b128 v[140:143], v131 offset:51200
	s_add_u32 m0, s100, 0x3000
	s_waitcnt lgkmcnt(6)
	v_mfma_f32_16x16x32_bf16 v[58:61], v[26:29], v[144:147], v[58:61]
	global_load_lds_dwordx4 v204, s[98:99]
	v_mfma_f32_16x16x32_bf16 v[66:69], v[30:33], v[144:147], v[66:69]
	ds_read_b128 v[230:233], v131 offset:53248
	s_add_u32 m0, s100, 0x7000
	v_mfma_f32_16x16x32_bf16 v[62:65], v[148:151], v[144:147], v[62:65]
	global_load_lds_dwordx4 v205, s[98:99]
	v_mfma_f32_16x16x32_bf16 v[74:77], v[152:155], v[144:147], v[74:77]
	ds_read_b128 v[144:147], v131 offset:55296
	s_waitcnt lgkmcnt(3)
	v_mfma_f32_16x16x32_bf16 v[34:37], v[222:225], v[156:159], v[34:37]
	s_waitcnt lgkmcnt(2)
	v_mfma_f32_16x16x32_bf16 v[94:97], v[140:143], v[156:159], v[94:97]
	s_waitcnt lgkmcnt(1)
	v_mfma_f32_16x16x32_bf16 v[38:41], v[230:233], v[156:159], v[38:41]
	s_waitcnt lgkmcnt(0)
	v_mfma_f32_16x16x32_bf16 v[90:93], v[144:147], v[156:159], v[90:93]
	v_mfma_f32_16x16x32_bf16 v[42:45], v[222:225], v[164:167], v[42:45]
	v_mfma_f32_16x16x32_bf16 v[86:89], v[140:143], v[164:167], v[86:89]
	v_mfma_f32_16x16x32_bf16 v[46:49], v[230:233], v[164:167], v[46:49]
	v_mfma_f32_16x16x32_bf16 v[82:85], v[144:147], v[164:167], v[82:85]
	v_mfma_f32_16x16x32_bf16 v[50:53], v[222:225], v[198:201], v[50:53]
	v_mfma_f32_16x16x32_bf16 v[78:81], v[140:143], v[198:201], v[78:81]
	v_mfma_f32_16x16x32_bf16 v[54:57], v[230:233], v[198:201], v[54:57]
	v_mfma_f32_16x16x32_bf16 v[70:73], v[144:147], v[198:201], v[70:73]
	v_mfma_f32_16x16x32_bf16 v[58:61], v[222:225], v[210:213], v[58:61]
	v_mfma_f32_16x16x32_bf16 v[66:69], v[140:143], v[210:213], v[66:69]
	v_mfma_f32_16x16x32_bf16 v[62:65], v[230:233], v[210:213], v[62:65]
	v_mfma_f32_16x16x32_bf16 v[74:77], v[144:147], v[210:213], v[74:77]
	s_waitcnt vmcnt(0)
	s_setprio 0
	s_add_i32 s9, s9, 2
	s_add_u32 s46, s46, 0x100
	s_addc_u32 s47, s47, 0
	s_cmp_lt_u32 s9, 12
	s_waitcnt lgkmcnt(0)
	s_barrier
	s_cbranch_scc1 .LBB0_137
	v_mov_b32_e32 v2, v194
	v_mov_b32_e32 v3, v195
	v_mov_b32_e32 v4, v196
	v_mov_b32_e32 v5, v197
	v_mov_b32_e32 v6, v202
	v_mov_b32_e32 v7, v203
	v_mov_b32_e32 v8, v204
	v_mov_b32_e32 v9, v205
	s_add_u32 s98, s46, s16
	s_addc_u32 s99, s47, 0
	s_add_u32 s98, s98, 0x80
	s_addc_u32 s99, s99, 0
	s_add_i32 s9, s8, s2
	s_cmpk_lt_u32 s9, 0x580
	s_cselect_b32 s8, s9, s8
	s_mul_hi_u32 s10, s8, 0xba2e8ba3
	s_lshr_b32 s10, s10, 8
	s_mul_i32 s11, s10, 0x160
	v_mov_b32_e32 v0, v169
	s_sub_i32 s11, s8, s11
	s_lshl_b32 s8, s10, 3
	s_add_i32 s8, s8, s21
	s_and_b32 s10, s11, 7
	v_lshlrev_b32_e32 v100, 3, v0
	v_lshlrev_b32_e32 v0, 7, v0
	s_or_b32 s8, s8, s10
	v_and_b32_e32 v0, 0xfffffc00, v0
	v_lshl_add_u32 v0, s8, 17, v0
	v_and_or_b32 v0, v100, 56, v0
	v_mov_b32_e32 v100, v169
	s_lshl_b32 s10, s11, 4
	s_and_b32 s10, s10, 0x1f80
	v_lshrrev_b32_e32 v101, 3, v100
	v_lshlrev_b32_e32 v100, 3, v100
	v_add_u32_e32 v101, s10, v101
	v_and_b32_e32 v100, 56, v100
	v_lshl_or_b32 v160, v101, 10, v100
	s_cmpk_gt_u32 s9, 0x57f
	s_cselect_b32 s101, 1, 0
	v_add_u32_e32 v116, 0x8000, v0
	v_add_u32_e32 v136, 0x10000, v0
	v_add_u32_e32 v174, 0x18000, v0
	v_add_u32_e32 v176, 0x8000, v160
	v_add_u32_e32 v178, 0x10000, v160
	v_add_u32_e32 v180, 0x18000, v160
	s_setprio 1
	ds_read_b128 v[100:103], v128 offset:16384
	ds_read_b128 v[112:115], v128 offset:18432
	ds_read_b128 v[140:143], v128 offset:20480
	ds_read_b128 v[144:147], v128 offset:22528
	ds_read_b128 v[104:107], v130
	ds_read_b128 v[108:111], v130 offset:2048
	ds_read_b128 v[124:127], v130 offset:4096
	ds_read_b128 v[132:135], v130 offset:6144
	v_lshrrev_b32_e32 v14, 3, v169
	v_and_b32_e32 v15, 3, v14
	v_bfe_u32 v16, v14, 4, 1
	v_lshl_or_b32 v15, v16, 2, v15
	v_bfe_u32 v16, v14, 2, 1
	v_lshl_or_b32 v15, v16, 3, v15
	v_bfe_u32 v16, v14, 3, 1
	v_lshl_or_b32 v15, v16, 4, v15
	v_sub_u32_e32 v15, v15, v14
	v_mul_i32_i24_e32 v15, 0x400, v15
	v_and_b32_e32 v14, 7, v14
	v_lshlrev_b32_e32 v14, 3, v14
	v_xor_b32_e32 v0, v0, v14
	v_add_u32_e32 v160, v160, v15
	v_xor_b32_e32 v160, v160, v14
	v_xor_b32_e32 v116, v116, v14
	v_add_u32_e32 v176, v176, v15
	v_xor_b32_e32 v176, v176, v14
	v_xor_b32_e32 v136, v136, v14
	v_add_u32_e32 v178, v178, v15
	v_xor_b32_e32 v178, v178, v14
	v_xor_b32_e32 v174, v174, v14
	v_add_u32_e32 v180, v180, v15
	v_xor_b32_e32 v180, v180, v14
	v_mov_b32_e32 v161, v1
	v_mov_b32_e32 v117, v1
	v_mov_b32_e32 v177, v1
	v_mov_b32_e32 v137, v1
	v_mov_b32_e32 v179, v1
	v_mov_b32_e32 v175, v1
	v_mov_b32_e32 v181, v1
	v_lshl_add_u64 v[186:187], v[0:1], 1, s[38:39]
	v_lshl_add_u64 v[188:189], v[160:161], 1, s[42:43]
	v_lshl_add_u64 v[116:117], v[116:117], 1, s[38:39]
	v_lshl_add_u64 v[176:177], v[176:177], 1, s[42:43]
	v_lshl_add_u64 v[136:137], v[136:137], 1, s[38:39]
	v_lshl_add_u64 v[178:179], v[178:179], 1, s[42:43]
	v_lshl_add_u64 v[174:175], v[174:175], 1, s[38:39]
	v_lshl_add_u64 v[180:181], v[180:181], 1, s[42:43]
	s_add_u32 m0, s100, 0x8000
	s_waitcnt lgkmcnt(3)
	v_mfma_f32_16x16x32_bf16 v[148:151], v[100:103], v[104:107], v[34:37]
	global_load_lds_dwordx4 v2, s[98:99]
	v_mfma_f32_16x16x32_bf16 v[94:97], v[112:115], v[104:107], v[94:97]
	ds_read_b128 v[152:155], v129
	s_add_u32 m0, s100, 0xc000
	v_mfma_f32_16x16x32_bf16 v[156:159], v[140:143], v[104:107], v[38:41]
	global_load_lds_dwordx4 v3, s[98:99]
	v_mfma_f32_16x16x32_bf16 v[90:93], v[144:147], v[104:107], v[90:93]
	ds_read_b128 v[104:107], v129 offset:2048
	s_add_u32 m0, s100, 0x9000
	s_waitcnt lgkmcnt(4)
	v_mfma_f32_16x16x32_bf16 v[160:163], v[100:103], v[108:111], v[42:45]
	global_load_lds_dwordx4 v4, s[98:99]
	v_mfma_f32_16x16x32_bf16 v[86:89], v[112:115], v[108:111], v[86:89]
	ds_read_b128 v[164:167], v129 offset:4096
	s_add_u32 m0, s100, 0xd000
	v_mfma_f32_16x16x32_bf16 v[194:197], v[140:143], v[108:111], v[46:49]
	global_load_lds_dwordx4 v5, s[98:99]
	v_mfma_f32_16x16x32_bf16 v[82:85], v[144:147], v[108:111], v[82:85]
	ds_read_b128 v[108:111], v129 offset:6144
	s_add_u32 m0, s100, 0xa000
	s_waitcnt lgkmcnt(5)
	v_mfma_f32_16x16x32_bf16 v[198:201], v[100:103], v[124:127], v[50:53]
	global_load_lds_dwordx4 v6, s[98:99]
	v_mfma_f32_16x16x32_bf16 v[78:81], v[112:115], v[124:127], v[78:81]
	ds_read_b128 v[202:205], v131 offset:16384
	s_add_u32 m0, s100, 0xe000
	v_mfma_f32_16x16x32_bf16 v[206:209], v[140:143], v[124:127], v[54:57]
	global_load_lds_dwordx4 v7, s[98:99]
	v_mfma_f32_16x16x32_bf16 v[70:73], v[144:147], v[124:127], v[70:73]
	ds_read_b128 v[124:127], v131 offset:18432
	s_add_u32 m0, s100, 0xb000
	s_waitcnt lgkmcnt(6)
	v_mfma_f32_16x16x32_bf16 v[100:103], v[100:103], v[132:135], v[58:61]
	global_load_lds_dwordx4 v8, s[98:99]
	v_mfma_f32_16x16x32_bf16 v[66:69], v[112:115], v[132:135], v[66:69]
	ds_read_b128 v[112:115], v131 offset:20480
	s_add_u32 m0, s100, 0xf000
	v_mfma_f32_16x16x32_bf16 v[140:143], v[140:143], v[132:135], v[62:65]
	global_load_lds_dwordx4 v9, s[98:99]
	v_mfma_f32_16x16x32_bf16 v[74:77], v[144:147], v[132:135], v[74:77]
	ds_read_b128 v[132:135], v131 offset:22528
	s_waitcnt lgkmcnt(3)
	v_mfma_f32_16x16x32_bf16 v[144:147], v[202:205], v[152:155], v[148:151]
	s_waitcnt lgkmcnt(2)
	v_mfma_f32_16x16x32_bf16 v[94:97], v[124:127], v[152:155], v[94:97]
	s_waitcnt lgkmcnt(1)
	v_mfma_f32_16x16x32_bf16 v[148:151], v[112:115], v[152:155], v[156:159]
	s_waitcnt lgkmcnt(0)
	v_mfma_f32_16x16x32_bf16 v[90:93], v[132:135], v[152:155], v[90:93]
	v_mfma_f32_16x16x32_bf16 v[152:155], v[202:205], v[104:107], v[160:163]
	v_mfma_f32_16x16x32_bf16 v[86:89], v[124:127], v[104:107], v[86:89]
	v_mfma_f32_16x16x32_bf16 v[156:159], v[112:115], v[104:107], v[194:197]
	v_mfma_f32_16x16x32_bf16 v[82:85], v[132:135], v[104:107], v[82:85]
	v_mfma_f32_16x16x32_bf16 v[104:107], v[202:205], v[164:167], v[198:201]
	v_mfma_f32_16x16x32_bf16 v[78:81], v[124:127], v[164:167], v[78:81]
	v_mfma_f32_16x16x32_bf16 v[160:163], v[112:115], v[164:167], v[206:209]
	v_mfma_f32_16x16x32_bf16 v[70:73], v[132:135], v[164:167], v[70:73]
	v_mfma_f32_16x16x32_bf16 v[100:103], v[202:205], v[108:111], v[100:103]
	v_mfma_f32_16x16x32_bf16 v[66:69], v[124:127], v[108:111], v[66:69]
	v_mfma_f32_16x16x32_bf16 v[112:115], v[112:115], v[108:111], v[140:143]
	v_mfma_f32_16x16x32_bf16 v[74:77], v[132:135], v[108:111], v[74:77]
	s_waitcnt vmcnt(0)
	s_setprio 0
	s_waitcnt lgkmcnt(0)
	s_barrier
	s_setprio 1
	ds_read_b128 v[26:29], v128 offset:49152
	ds_read_b128 v[30:33], v128 offset:51200
	ds_read_b128 v[132:135], v128 offset:53248
	ds_read_b128 v[140:143], v128 offset:55296
	ds_read_b128 v[10:13], v130 offset:32768
	ds_read_b128 v[18:21], v130 offset:34816
	ds_read_b128 v[108:111], v130 offset:36864
	ds_read_b128 v[124:127], v130 offset:38912
	s_add_u32 m0, s100, 0x0
	s_waitcnt lgkmcnt(3)
	v_mfma_f32_16x16x32_bf16 v[144:147], v[26:29], v[10:13], v[144:147]
	global_load_lds_dwordx4 v[186:187], off
	v_mfma_f32_16x16x32_bf16 v[94:97], v[30:33], v[10:13], v[94:97]
	ds_read_b128 v[164:167], v129 offset:32768
	s_add_u32 m0, s100, 0x4000
	v_mfma_f32_16x16x32_bf16 v[148:151], v[132:135], v[10:13], v[148:151]
	global_load_lds_dwordx4 v[188:189], off
	v_mfma_f32_16x16x32_bf16 v[90:93], v[140:143], v[10:13], v[90:93]
	ds_read_b128 v[194:197], v129 offset:34816
	s_add_u32 m0, s100, 0x1000
	s_waitcnt lgkmcnt(4)
	v_mfma_f32_16x16x32_bf16 v[152:155], v[26:29], v[18:21], v[152:155]
	global_load_lds_dwordx4 v[116:117], off
	v_mfma_f32_16x16x32_bf16 v[86:89], v[30:33], v[18:21], v[86:89]
	ds_read_b128 v[198:201], v129 offset:36864
	s_add_u32 m0, s100, 0x5000
	v_mfma_f32_16x16x32_bf16 v[156:159], v[132:135], v[18:21], v[156:159]
	global_load_lds_dwordx4 v[176:177], off
	v_mfma_f32_16x16x32_bf16 v[82:85], v[140:143], v[18:21], v[82:85]
	ds_read_b128 v[202:205], v129 offset:38912
	s_add_u32 m0, s100, 0x2000
	s_waitcnt lgkmcnt(5)
	v_mfma_f32_16x16x32_bf16 v[104:107], v[26:29], v[108:111], v[104:107]
	global_load_lds_dwordx4 v[136:137], off
	v_mfma_f32_16x16x32_bf16 v[78:81], v[30:33], v[108:111], v[78:81]
	ds_read_b128 v[206:209], v131 offset:49152
	s_add_u32 m0, s100, 0x6000
	v_mfma_f32_16x16x32_bf16 v[160:163], v[132:135], v[108:111], v[160:163]
	global_load_lds_dwordx4 v[178:179], off
	v_mfma_f32_16x16x32_bf16 v[70:73], v[140:143], v[108:111], v[70:73]
	ds_read_b128 v[108:111], v131 offset:51200
	s_add_u32 m0, s100, 0x3000
	s_waitcnt lgkmcnt(6)
	v_mfma_f32_16x16x32_bf16 v[100:103], v[26:29], v[124:127], v[100:103]
	global_load_lds_dwordx4 v[174:175], off
	v_mfma_f32_16x16x32_bf16 v[66:69], v[30:33], v[124:127], v[66:69]
	ds_read_b128 v[210:213], v131 offset:53248
	s_add_u32 m0, s100, 0x7000
	v_mfma_f32_16x16x32_bf16 v[112:115], v[132:135], v[124:127], v[112:115]
	global_load_lds_dwordx4 v[180:181], off
	v_mfma_f32_16x16x32_bf16 v[124:127], v[140:143], v[124:127], v[74:77]
	ds_read_b128 v[128:131], v131 offset:55296
	s_waitcnt lgkmcnt(3)
	v_mfma_f32_16x16x32_bf16 v[132:135], v[206:209], v[164:167], v[144:147]
	s_waitcnt lgkmcnt(2)
	v_mfma_f32_16x16x32_bf16 v[140:143], v[108:111], v[164:167], v[94:97]
	s_waitcnt lgkmcnt(1)
	v_mfma_f32_16x16x32_bf16 v[144:147], v[210:213], v[164:167], v[148:151]
	s_waitcnt lgkmcnt(0)
	v_mfma_f32_16x16x32_bf16 v[148:151], v[128:131], v[164:167], v[90:93]
	v_mfma_f32_16x16x32_bf16 v[152:155], v[206:209], v[194:197], v[152:155]
	v_mfma_f32_16x16x32_bf16 v[164:167], v[108:111], v[194:197], v[86:89]
	v_mfma_f32_16x16x32_bf16 v[156:159], v[210:213], v[194:197], v[156:159]
	v_mfma_f32_16x16x32_bf16 v[194:197], v[128:131], v[194:197], v[82:85]
	v_mfma_f32_16x16x32_bf16 v[94:97], v[206:209], v[198:201], v[104:107]
	v_mfma_f32_16x16x32_bf16 v[86:89], v[108:111], v[198:201], v[78:81]
	v_mfma_f32_16x16x32_bf16 v[90:93], v[210:213], v[198:201], v[160:163]
	v_mfma_f32_16x16x32_bf16 v[82:85], v[128:131], v[198:201], v[70:73]
	v_mfma_f32_16x16x32_bf16 v[74:77], v[206:209], v[202:205], v[100:103]
	v_mfma_f32_16x16x32_bf16 v[66:69], v[108:111], v[202:205], v[66:69]
	v_mfma_f32_16x16x32_bf16 v[70:73], v[210:213], v[202:205], v[112:115]
	v_mfma_f32_16x16x32_bf16 v[78:81], v[128:131], v[202:205], v[124:127]
	s_setprio 0
	v_mul_f32_e32 v0, 0xbfb8aa3b, v132
	v_exp_f32_e32 v0, v0
	v_mul_f32_e32 v99, 0xbfb8aa3b, v133
	v_exp_f32_e32 v99, v99
	v_mul_f32_e32 v101, 0xbfb8aa3b, v135
	v_add_f32_e32 v0, 1.0, v0
	v_rcp_f32_e32 v100, v0
	v_add_f32_e32 v0, 1.0, v99
	v_mul_f32_e32 v99, 0xbfb8aa3b, v134
	v_exp_f32_e32 v99, v99
	v_exp_f32_e32 v103, v101
	v_rcp_f32_e32 v101, v0
	v_mul_f32_e32 v108, 0xbfb8aa3b, v152
	v_add_f32_e32 v0, 1.0, v99
	v_mul_f32_e32 v99, 0xbfb8aa3b, v140
	v_rcp_f32_e32 v102, v0
	v_add_f32_e32 v0, 1.0, v103
	v_exp_f32_e32 v99, v99
	v_mul_f32_e32 v103, 0xbfb8aa3b, v141
	v_exp_f32_e32 v105, v103
	v_rcp_f32_e32 v103, v0
	v_add_f32_e32 v0, 1.0, v99
	v_mul_f32_e32 v99, 0xbfb8aa3b, v142
	v_rcp_f32_e32 v104, v0
	v_add_f32_e32 v0, 1.0, v105
	v_exp_f32_e32 v99, v99
	v_mul_f32_e32 v105, 0xbfb8aa3b, v143
	v_exp_f32_e32 v107, v105
	v_rcp_f32_e32 v105, v0
	v_add_f32_e32 v0, 1.0, v99
	v_rcp_f32_e32 v106, v0
	v_add_f32_e32 v0, 1.0, v107
	v_rcp_f32_e32 v107, v0
	v_pk_mul_f32 v[100:101], v[132:133], v[100:101]
	v_pk_mul_f32 v[102:103], v[134:135], v[102:103]
	v_pk_mul_f32 v[100:101], v[144:145], v[100:101]
	v_pk_mul_f32 v[102:103], v[146:147], v[102:103]
	v_cvt_pk_bf16_f32 v100, v100, v101
	v_cvt_pk_bf16_f32 v101, v102, v103
	v_pk_mul_f32 v[102:103], v[140:141], v[104:105]
	v_pk_mul_f32 v[104:105], v[142:143], v[106:107]
	v_pk_mul_f32 v[102:103], v[148:149], v[102:103]
	v_pk_mul_f32 v[104:105], v[150:151], v[104:105]
	v_add_u32_e32 v0, s4, v118
	v_cvt_pk_bf16_f32 v102, v102, v103
	v_cvt_pk_bf16_f32 v103, v104, v105
	v_mov_b64_e32 v[104:105], s[44:45]
	v_mad_i64_i32 v[106:107], s[14:15], v0, s20, v[104:105]
	v_or_b32_e32 v0, s5, v119
	v_mul_f32_e32 v109, 0xbfb8aa3b, v153
	v_lshl_add_u64 v[106:107], v[106:107], 0, v[0:1]
	v_mov_b32_e32 v99, v1
	v_exp_f32_e32 v108, v108
	v_exp_f32_e32 v109, v109
	v_lshl_add_u64 v[106:107], v[106:107], 0, v[98:99]
	s_barrier
	global_store_dwordx4 v[106:107], v[100:103], off
	v_mul_f32_e32 v106, 0xbfb8aa3b, v164
	v_mul_f32_e32 v107, 0xbfb8aa3b, v165
	v_mul_f32_e32 v102, 0xbfb8aa3b, v154
	v_mul_f32_e32 v103, 0xbfb8aa3b, v155
	v_exp_f32_e32 v102, v102
	v_exp_f32_e32 v103, v103
	v_add_f32_e32 v100, 1.0, v108
	v_add_f32_e32 v101, 1.0, v109
	v_mul_f32_e32 v108, 0xbfb8aa3b, v166
	v_mul_f32_e32 v109, 0xbfb8aa3b, v167
	v_exp_f32_e32 v106, v106
	v_exp_f32_e32 v107, v107
	v_exp_f32_e32 v108, v108
	v_exp_f32_e32 v109, v109
	v_add_f32_e32 v102, 1.0, v102
	v_add_f32_e32 v103, 1.0, v103
	v_rcp_f32_e32 v100, v100
	v_rcp_f32_e32 v101, v101
	v_rcp_f32_e32 v102, v102
	v_rcp_f32_e32 v103, v103
	v_add_f32_e32 v106, 1.0, v106
	v_add_f32_e32 v107, 1.0, v107
	v_add_f32_e32 v108, 1.0, v108
	v_add_f32_e32 v109, 1.0, v109
	v_rcp_f32_e32 v106, v106
	v_rcp_f32_e32 v107, v107
	v_rcp_f32_e32 v108, v108
	v_rcp_f32_e32 v109, v109
	v_pk_mul_f32 v[100:101], v[152:153], v[100:101]
	v_pk_mul_f32 v[102:103], v[154:155], v[102:103]
	v_pk_mul_f32 v[100:101], v[156:157], v[100:101]
	v_pk_mul_f32 v[102:103], v[158:159], v[102:103]
	v_cvt_pk_bf16_f32 v100, v100, v101
	v_cvt_pk_bf16_f32 v101, v102, v103
	v_pk_mul_f32 v[102:103], v[164:165], v[106:107]
	v_pk_mul_f32 v[106:107], v[166:167], v[108:109]
	v_add_u32_e32 v110, s4, v120
	v_pk_mul_f32 v[102:103], v[194:195], v[102:103]
	v_pk_mul_f32 v[106:107], v[196:197], v[106:107]
	v_cvt_pk_bf16_f32 v102, v102, v103
	v_cvt_pk_bf16_f32 v103, v106, v107
	v_mad_i64_i32 v[106:107], s[14:15], v110, s20, v[104:105]
	v_mul_f32_e32 v108, 0xbfb8aa3b, v94
	v_mul_f32_e32 v109, 0xbfb8aa3b, v95
	v_lshl_add_u64 v[106:107], v[106:107], 0, v[0:1]
	v_exp_f32_e32 v108, v108
	v_exp_f32_e32 v109, v109
	v_lshl_add_u64 v[106:107], v[106:107], 0, v[98:99]
	global_store_dwordx4 v[106:107], v[100:103], off
	v_mul_f32_e32 v106, 0xbfb8aa3b, v86
	v_mul_f32_e32 v107, 0xbfb8aa3b, v87
	v_mul_f32_e32 v102, 0xbfb8aa3b, v96
	v_mul_f32_e32 v103, 0xbfb8aa3b, v97
	v_exp_f32_e32 v102, v102
	v_exp_f32_e32 v103, v103
	v_exp_f32_e32 v106, v106
	v_exp_f32_e32 v107, v107
	v_add_f32_e32 v100, 1.0, v108
	v_add_f32_e32 v101, 1.0, v109
	v_mul_f32_e32 v108, 0xbfb8aa3b, v88
	v_mul_f32_e32 v109, 0xbfb8aa3b, v89
	v_exp_f32_e32 v108, v108
	v_exp_f32_e32 v109, v109
	v_rcp_f32_e32 v100, v100
	v_rcp_f32_e32 v101, v101
	v_add_f32_e32 v102, 1.0, v102
	v_add_f32_e32 v103, 1.0, v103
	v_add_f32_e32 v106, 1.0, v106
	v_add_f32_e32 v107, 1.0, v107
	v_rcp_f32_e32 v102, v102
	v_rcp_f32_e32 v103, v103
	v_rcp_f32_e32 v106, v106
	v_rcp_f32_e32 v107, v107
	v_add_f32_e32 v108, 1.0, v108
	v_add_f32_e32 v109, 1.0, v109
	v_rcp_f32_e32 v108, v108
	v_rcp_f32_e32 v109, v109
	v_pk_mul_f32 v[94:95], v[94:95], v[100:101]
	v_pk_mul_f32 v[86:87], v[86:87], v[106:107]
	v_pk_mul_f32 v[90:91], v[90:91], v[94:95]
	v_pk_mul_f32 v[94:95], v[96:97], v[102:103]
	v_pk_mul_f32 v[82:83], v[82:83], v[86:87]
	v_pk_mul_f32 v[92:93], v[92:93], v[94:95]
	v_cvt_pk_bf16_f32 v90, v90, v91
	v_cvt_pk_bf16_f32 v91, v92, v93
	v_cvt_pk_bf16_f32 v92, v82, v83
	v_pk_mul_f32 v[82:83], v[88:89], v[108:109]
	v_add_u32_e32 v110, s4, v121
	v_pk_mul_f32 v[82:83], v[84:85], v[82:83]
	v_mul_f32_e32 v84, 0xbfb8aa3b, v74
	v_mul_f32_e32 v85, 0xbfb8aa3b, v75
	v_exp_f32_e32 v84, v84
	v_exp_f32_e32 v85, v85
	v_cvt_pk_bf16_f32 v93, v82, v83
	v_mad_i64_i32 v[82:83], s[14:15], v110, s20, v[104:105]
	v_lshl_add_u64 v[82:83], v[82:83], 0, v[0:1]
	v_lshl_add_u64 v[82:83], v[82:83], 0, v[98:99]
	global_store_dwordx4 v[82:83], v[90:93], off
	v_add_f32_e32 v82, 1.0, v84
	v_add_f32_e32 v83, 1.0, v85
	v_mul_f32_e32 v84, 0xbfb8aa3b, v76
	v_mul_f32_e32 v85, 0xbfb8aa3b, v77
	v_mul_f32_e32 v86, 0xbfb8aa3b, v66
	v_mul_f32_e32 v87, 0xbfb8aa3b, v67
	v_exp_f32_e32 v84, v84
	v_exp_f32_e32 v85, v85
	v_exp_f32_e32 v86, v86
	v_exp_f32_e32 v87, v87
	v_mul_f32_e32 v88, 0xbfb8aa3b, v68
	v_mul_f32_e32 v89, 0xbfb8aa3b, v69
	v_exp_f32_e32 v88, v88
	v_exp_f32_e32 v89, v89
	v_rcp_f32_e32 v82, v82
	v_rcp_f32_e32 v83, v83
	v_add_f32_e32 v84, 1.0, v84
	v_add_f32_e32 v85, 1.0, v85
	v_add_f32_e32 v86, 1.0, v86
	v_add_f32_e32 v87, 1.0, v87
	v_rcp_f32_e32 v84, v84
	v_rcp_f32_e32 v85, v85
	v_rcp_f32_e32 v86, v86
	v_rcp_f32_e32 v87, v87
	v_add_f32_e32 v88, 1.0, v88
	v_add_f32_e32 v89, 1.0, v89
	v_rcp_f32_e32 v88, v88
	v_rcp_f32_e32 v89, v89
	v_pk_mul_f32 v[74:75], v[74:75], v[82:83]
	v_pk_mul_f32 v[66:67], v[66:67], v[86:87]
	v_pk_mul_f32 v[70:71], v[70:71], v[74:75]
	v_pk_mul_f32 v[74:75], v[76:77], v[84:85]
	v_pk_mul_f32 v[66:67], v[78:79], v[66:67]
	v_pk_mul_f32 v[72:73], v[72:73], v[74:75]
	v_cvt_pk_bf16_f32 v70, v70, v71
	v_cvt_pk_bf16_f32 v71, v72, v73
	v_cvt_pk_bf16_f32 v72, v66, v67
	v_pk_mul_f32 v[66:67], v[68:69], v[88:89]
	v_add_u32_e32 v90, s4, v122
	v_pk_mul_f32 v[66:67], v[80:81], v[66:67]
	s_nop 0
	v_cvt_pk_bf16_f32 v73, v66, v67
	v_mad_i64_i32 v[66:67], s[4:5], v90, s20, v[104:105]
	v_lshl_add_u64 v[66:67], v[66:67], 0, v[0:1]
	v_lshl_add_u64 v[66:67], v[66:67], 0, v[98:99]
	global_store_dwordx4 v[66:67], v[70:73], off
	s_cmp_lg_u32 s101, 0
	s_cbranch_scc0 .LBB0_135

.LBB0_152:
	s_andn2_b64 vcc, exec, s[0:1]
	s_cbranch_vccnz .LBB0_228
	v_readlane_b32 s4, v254, 37
	v_readlane_b32 s5, v254, 38
	s_mov_b64 s[0:1], 0
	v_mov_b32_e32 v80, v169
	s_andn2_b64 vcc, exec, s[4:5]
	s_cbranch_vccnz .LBB0_228
	v_mov_b32_e32 v0, v169
	s_load_dword s2, s[22:23], 0x0
	v_readlane_b32 s8, v254, 39
	s_waitcnt vmcnt(7)
	v_lshrrev_b32_e32 v2, 3, v0
	v_lshlrev_b32_e32 v0, 3, v0
	s_add_u32 s0, s72, s0
	v_add_u32_e32 v2, s8, v2
	v_and_b32_e32 v0, 56, v0
	s_addc_u32 s1, s73, s1
	v_readlane_b32 s4, v255, 36
	v_lshl_or_b32 v0, v2, 10, v0
	v_mov_b32_e32 v2, v169
	s_add_u32 s0, s0, 0x1a991000
	v_readlane_b32 s5, v255, 37
	s_addc_u32 s1, s1, 0
	s_waitcnt lgkmcnt(0)
	s_lshr_b32 s2, s2, 3
	s_lshl_b64 s[28:29], s[4:5], 21
	v_readlane_b32 s4, v254, 47
	v_lshrrev_b32_e32 v3, 3, v2
	v_readlane_b32 s9, v254, 40
	v_lshlrev_b32_e32 v2, 3, v2
	s_add_u32 s34, s4, s28
	v_readlane_b32 s4, v254, 48
	v_add_u32_e32 v3, s9, v3
	v_and_b32_e32 v2, 56, v2
	s_addc_u32 s35, s4, s29
	v_lshl_or_b32 v72, v3, 10, v2
	v_readlane_b32 s4, v254, 45
	v_add_u32_e32 v66, 0x8000, v0
	v_add_u32_e32 v68, 0x10000, v0
	v_add_u32_e32 v70, 0x18000, v0
	v_add_u32_e32 v74, 0x8000, v72
	v_add_u32_e32 v76, 0x10000, v72
	v_add_u32_e32 v78, 0x18000, v72
	v_readlane_b32 s5, v254, 46
	v_mov_b32_e32 v73, v1
	v_mov_b32_e32 v67, v1
	v_mov_b32_e32 v75, v1
	v_mov_b32_e32 v69, v1
	v_mov_b32_e32 v77, v1
	v_mov_b32_e32 v71, v1
	v_mov_b32_e32 v79, v1
	v_lshl_add_u64 v[2:3], v[0:1], 1, s[4:5]
	s_waitcnt vmcnt(6)
	v_lshl_add_u64 v[6:7], v[72:73], 1, s[34:35]
	s_waitcnt vmcnt(5)
	v_lshl_add_u64 v[10:11], v[66:67], 1, s[4:5]
	s_waitcnt vmcnt(4)
	v_lshl_add_u64 v[14:15], v[74:75], 1, s[34:35]
	s_waitcnt vmcnt(3)
	v_lshl_add_u64 v[18:19], v[68:69], 1, s[4:5]
	s_waitcnt vmcnt(2)
	v_lshl_add_u64 v[22:23], v[76:77], 1, s[34:35]
	s_waitcnt vmcnt(1)
	v_lshl_add_u64 v[26:27], v[70:71], 1, s[4:5]
	s_waitcnt vmcnt(0)
	v_lshl_add_u64 v[30:31], v[78:79], 1, s[34:35]
	v_lshrrev_b32_e32 v34, 6, v169
	v_lshlrev_b32_e32 v34, 10, v34
	s_nop 0
	v_readfirstlane_b32 s100, v34
	v_lshrrev_b32_e32 v35, 3, v169
	v_and_b32_e32 v36, 3, v35
	v_bfe_u32 v37, v35, 4, 1
	v_lshl_or_b32 v36, v37, 2, v36
	v_bfe_u32 v37, v35, 2, 1
	v_lshl_or_b32 v36, v37, 3, v36
	v_bfe_u32 v37, v35, 3, 1
	v_lshl_or_b32 v36, v37, 4, v36
	v_sub_u32_e32 v36, v36, v35
	v_mul_i32_i24_e32 v36, 0x800, v36
	v_and_b32_e32 v35, 7, v35
	v_lshlrev_b32_e32 v35, 4, v35
	v_ashrrev_i32_e32 v37, 31, v36
	v_xor_b32_e32 v2, v2, v35
	v_lshl_add_u64 v[6:7], v[6:7], 0, v[36:37]
	v_xor_b32_e32 v6, v6, v35
	v_xor_b32_e32 v10, v10, v35
	v_lshl_add_u64 v[14:15], v[14:15], 0, v[36:37]
	v_xor_b32_e32 v14, v14, v35
	v_xor_b32_e32 v18, v18, v35
	v_lshl_add_u64 v[22:23], v[22:23], 0, v[36:37]
	v_xor_b32_e32 v22, v22, v35
	v_xor_b32_e32 v26, v26, v35
	v_lshl_add_u64 v[30:31], v[30:31], 0, v[36:37]
	v_xor_b32_e32 v30, v30, v35
	s_add_u32 m0, s100, 0x0
	s_nop 0
	global_load_lds_dwordx4 v[2:3], off
	s_add_u32 m0, s100, 0x4000
	s_nop 0
	global_load_lds_dwordx4 v[6:7], off
	s_add_u32 m0, s100, 0x1000
	s_nop 0
	global_load_lds_dwordx4 v[10:11], off
	s_add_u32 m0, s100, 0x5000
	s_nop 0
	global_load_lds_dwordx4 v[14:15], off
	s_add_u32 m0, s100, 0x2000
	s_nop 0
	global_load_lds_dwordx4 v[18:19], off
	s_add_u32 m0, s100, 0x6000
	s_nop 0
	global_load_lds_dwordx4 v[22:23], off
	s_add_u32 m0, s100, 0x3000
	s_nop 0
	global_load_lds_dwordx4 v[26:27], off
	s_add_u32 m0, s100, 0x7000
	s_nop 0
	global_load_lds_dwordx4 v[30:31], off
	s_waitcnt vmcnt(0)
	s_add_i32 s4, s65, 7
	v_readlane_b32 s40, v253, 2
	s_cmp_lt_u32 s4, 17
	v_readlane_b32 s41, v253, 3
	s_cselect_b32 s41, s41, 0
	s_cselect_b32 s40, s40, 0
	v_and_b32_e32 v69, 15, v80
	v_ashrrev_i32_e32 v71, 1, v80
	s_movk_i32 s4, 0xffc0
	v_readlane_b32 s42, v253, 4
	v_readlane_b32 s43, v253, 5
	s_cmp_lg_u64 s[40:41], 0
	v_and_b32_e32 v67, 64, v80
	v_and_or_b32 v152, v71, s4, v69
	v_lshrrev_b32_e32 v69, 1, v80
	s_cselect_b64 s[42:43], -1, 0
	v_and_or_b32 v153, v69, 24, v67
	v_or_b32_e32 v154, 16, v152
	v_or_b32_e32 v155, 32, v152
	v_or_b32_e32 v156, 48, v152
	v_readlane_b32 s5, v254, 57
	v_readlane_b32 s44, v253, 6
	v_readlane_b32 s45, v253, 7
	v_readlane_b32 s46, v253, 8
	v_readlane_b32 s47, v253, 9
	v_readlane_b32 s48, v253, 10
	v_readlane_b32 s49, v253, 11
	v_readlane_b32 s50, v253, 12
	v_readlane_b32 s51, v253, 13
	v_readlane_b32 s52, v253, 14
	v_readlane_b32 s53, v253, 15
	v_readlane_b32 s54, v253, 16
	v_readlane_b32 s55, v253, 17
	s_branch .LBB0_156

.LBB0_156:
	v_mov_b32_e32 v67, v169
	s_mov_b32 s11, s5
	v_lshrrev_b32_e32 v69, 4, v67
	v_ashrrev_i32_e32 v71, 3, v67
	v_lshrrev_b32_e32 v77, 1, v67
	v_and_b32_e32 v80, 4, v69
	v_and_b32_e32 v81, 3, v71
	v_and_b32_e32 v73, 7, v67
	v_xor_b32_e32 v75, v71, v67
	v_and_b32_e32 v77, 16, v77
	v_and_b32_e32 v79, 8, v69
	v_or_b32_e32 v82, v80, v81
	v_lshlrev_b32_e32 v75, 4, v75
	v_or3_b32 v77, v77, v79, v82
	v_bitop3_b32 v79, v80, v73, v81 bitop3:0x36
	v_lshlrev_b32_e32 v71, 7, v71
	v_lshlrev_b32_e32 v79, 4, v79
	v_and_or_b32 v117, v75, s24, v71
	v_lshl_or_b32 v116, v77, 7, v79
	v_lshlrev_b32_e32 v34, 7, v67
	v_and_b32_e32 v35, 0x780, v34
	v_and_b32_e32 v118, 0x2780, v34
	v_bitop3_b32 v34, v69, v73, 3 bitop3:0x6c
	v_bfe_u32 v77, v67, 4, 2
	v_lshlrev_b32_e32 v119, 4, v34
	v_lshlrev_b32_e32 v34, 6, v67
	v_mov_b32_e32 v75, v1
	v_and_or_b32 v120, v34, s30, v35
	v_bitop3_b32 v34, v77, v73, 4 bitop3:0x36
	v_mov_b32_e32 v73, v1
	v_mov_b32_e32 v67, v1
	v_mov_b32_e32 v69, v1
	v_mov_b32_e32 v77, v1
	v_mov_b32_e32 v71, v1
	v_mov_b32_e32 v79, v1
	v_lshl_add_u64 v[100:101], v[74:75], 1, s[28:29]
	v_mov_b32_e32 v74, 0
	s_mov_b32 s10, s9
	s_mov_b32 s4, s8
	v_lshlrev_b32_e32 v121, 4, v34
	v_lshl_add_u64 v[98:99], v[72:73], 1, s[28:29]
	v_lshl_add_u64 v[102:103], v[76:77], 1, s[28:29]
	v_lshl_add_u64 v[104:105], v[78:79], 1, s[28:29]
	v_lshlrev_b64 v[106:107], 1, v[0:1]
	v_lshlrev_b64 v[108:109], 1, v[66:67]
	v_lshlrev_b64 v[110:111], 1, v[68:69]
	v_lshlrev_b64 v[112:113], 1, v[70:71]
	s_mov_b32 s5, -2
	s_mov_b64 s[38:39], s[72:73]
	v_mov_b32_e32 v75, v74
	v_mov_b32_e32 v76, v74
	v_mov_b32_e32 v77, v74
	v_mov_b32_e32 v62, v74
	v_mov_b32_e32 v63, v74
	v_mov_b32_e32 v64, v74
	v_mov_b32_e32 v65, v74
	v_mov_b32_e32 v66, v74
	v_mov_b32_e32 v67, v74
	v_mov_b32_e32 v68, v74
	v_mov_b32_e32 v69, v74
	v_mov_b32_e32 v58, v74
	v_mov_b32_e32 v59, v74
	v_mov_b32_e32 v60, v74
	v_mov_b32_e32 v61, v74
	v_mov_b32_e32 v70, v74
	v_mov_b32_e32 v71, v74
	v_mov_b32_e32 v72, v74
	v_mov_b32_e32 v73, v74
	v_mov_b32_e32 v54, v74
	v_mov_b32_e32 v55, v74
	v_mov_b32_e32 v56, v74
	v_mov_b32_e32 v57, v74
	v_mov_b32_e32 v78, v74
	v_mov_b32_e32 v79, v74
	v_mov_b32_e32 v80, v74
	v_mov_b32_e32 v81, v74
	v_mov_b32_e32 v50, v74
	v_mov_b32_e32 v51, v74
	v_mov_b32_e32 v52, v74
	v_mov_b32_e32 v53, v74
	v_mov_b32_e32 v82, v74
	v_mov_b32_e32 v83, v74
	v_mov_b32_e32 v84, v74
	v_mov_b32_e32 v85, v74
	v_mov_b32_e32 v46, v74
	v_mov_b32_e32 v47, v74
	v_mov_b32_e32 v48, v74
	v_mov_b32_e32 v49, v74
	v_mov_b32_e32 v86, v74
	v_mov_b32_e32 v87, v74
	v_mov_b32_e32 v88, v74
	v_mov_b32_e32 v89, v74
	v_mov_b32_e32 v42, v74
	v_mov_b32_e32 v43, v74
	v_mov_b32_e32 v44, v74
	v_mov_b32_e32 v45, v74
	v_mov_b32_e32 v90, v74
	v_mov_b32_e32 v91, v74
	v_mov_b32_e32 v92, v74
	v_mov_b32_e32 v93, v74
	v_mov_b32_e32 v38, v74
	v_mov_b32_e32 v39, v74
	v_mov_b32_e32 v40, v74
	v_mov_b32_e32 v41, v74
	v_mov_b32_e32 v94, v74
	v_mov_b32_e32 v95, v74
	v_mov_b32_e32 v96, v74
	v_mov_b32_e32 v97, v74
	v_mov_b32_e32 v34, v74
	v_mov_b32_e32 v35, v74
	v_mov_b32_e32 v36, v74
	v_mov_b32_e32 v37, v74
	s_waitcnt vmcnt(0)
	s_waitcnt lgkmcnt(0)
	s_barrier
	v_lshrrev_b32_e32 v222, 6, v169
	v_lshlrev_b32_e32 v222, 10, v222
	v_lshrrev_b32_e32 v223, 3, v169
	v_readfirstlane_b32 s100, v222
	v_and_b32_e32 v222, 3, v223
	v_bfe_u32 v224, v223, 4, 1
	v_lshl_or_b32 v222, v224, 2, v222
	v_bfe_u32 v224, v223, 2, 1
	v_lshl_or_b32 v222, v224, 3, v222
	v_bfe_u32 v224, v223, 3, 1
	v_lshl_or_b32 v222, v224, 4, v222
	v_sub_u32_e32 v222, v222, v223
	v_mul_i32_i24_e32 v222, 0x800, v222
	v_and_b32_e32 v223, 7, v223
	v_lshlrev_b32_e32 v223, 4, v223
	v_add_u32_e32 v210, 0xef11000, v106
	v_xor_b32_e32 v194, v210, v223
	v_mov_b32_e32 v211, v98
	v_add_u32_e32 v195, v211, v222
	v_xor_b32_e32 v195, v195, v223
	v_add_u32_e32 v212, 0xef11000, v108
	v_xor_b32_e32 v196, v212, v223
	v_mov_b32_e32 v213, v100
	v_add_u32_e32 v197, v213, v222
	v_xor_b32_e32 v197, v197, v223
	v_add_u32_e32 v218, 0xef11000, v110
	v_xor_b32_e32 v202, v218, v223
	v_mov_b32_e32 v219, v102
	v_add_u32_e32 v203, v219, v222
	v_xor_b32_e32 v203, v203, v223
	v_add_u32_e32 v220, 0xef11000, v112
	v_xor_b32_e32 v204, v220, v223
	v_mov_b32_e32 v221, v104
	v_add_u32_e32 v205, v221, v222
	v_xor_b32_e32 v205, v205, v223
.LBB0_157:
	s_setprio 1
	s_add_u32 s98, s38, s36
	s_addc_u32 s99, s39, 0
	s_add_u32 s98, s98, 0x80
	s_addc_u32 s99, s99, 0
	v_add_u32_e32 v122, v119, v118
	v_add_u32_e32 v124, v119, v120
	v_add_u32_e32 v123, v121, v120
	ds_read_b128 v[126:129], v122 offset:16384
	ds_read_b128 v[144:147], v122 offset:18432
	ds_read_b128 v[158:161], v122 offset:20480
	ds_read_b128 v[162:165], v122 offset:22528
	ds_read_b128 v[130:133], v124
	ds_read_b128 v[134:137], v124 offset:2048
	ds_read_b128 v[140:143], v124 offset:4096
	ds_read_b128 v[148:151], v124 offset:6144
	s_add_u32 m0, s100, 0x8000
	s_waitcnt lgkmcnt(3)
	v_mfma_f32_16x16x32_bf16 v[34:37], v[126:129], v[130:133], v[34:37]
	global_load_lds_dwordx4 v194, s[98:99]
	v_mfma_f32_16x16x32_bf16 v[94:97], v[144:147], v[130:133], v[94:97]
	ds_read_b128 v[198:201], v123
	s_add_u32 m0, s100, 0xc000
	v_mfma_f32_16x16x32_bf16 v[38:41], v[158:161], v[130:133], v[38:41]
	global_load_lds_dwordx4 v195, s[98:99]
	v_mfma_f32_16x16x32_bf16 v[90:93], v[162:165], v[130:133], v[90:93]
	ds_read_b128 v[206:209], v123 offset:2048
	s_add_u32 m0, s100, 0x9000
	s_waitcnt lgkmcnt(4)
	v_mfma_f32_16x16x32_bf16 v[42:45], v[126:129], v[134:137], v[42:45]
	global_load_lds_dwordx4 v196, s[98:99]
	v_mfma_f32_16x16x32_bf16 v[86:89], v[144:147], v[134:137], v[86:89]
	ds_read_b128 v[214:217], v123 offset:4096
	s_add_u32 m0, s100, 0xd000
	v_mfma_f32_16x16x32_bf16 v[46:49], v[158:161], v[134:137], v[46:49]
	global_load_lds_dwordx4 v197, s[98:99]
	v_mfma_f32_16x16x32_bf16 v[82:85], v[162:165], v[134:137], v[82:85]
	v_add_u32_e32 v130, v121, v118
	ds_read_b128 v[132:135], v123 offset:6144
	s_add_u32 m0, s100, 0xa000
	s_waitcnt lgkmcnt(5)
	v_mfma_f32_16x16x32_bf16 v[50:53], v[126:129], v[140:143], v[50:53]
	global_load_lds_dwordx4 v202, s[98:99]
	v_mfma_f32_16x16x32_bf16 v[78:81], v[144:147], v[140:143], v[78:81]
	ds_read_b128 v[226:229], v130 offset:16384
	s_add_u32 m0, s100, 0xe000
	v_mfma_f32_16x16x32_bf16 v[54:57], v[158:161], v[140:143], v[54:57]
	global_load_lds_dwordx4 v203, s[98:99]
	v_mfma_f32_16x16x32_bf16 v[70:73], v[162:165], v[140:143], v[70:73]
	ds_read_b128 v[140:143], v130 offset:18432
	s_add_u32 m0, s100, 0xb000
	s_waitcnt lgkmcnt(6)
	v_mfma_f32_16x16x32_bf16 v[58:61], v[126:129], v[148:151], v[58:61]
	global_load_lds_dwordx4 v204, s[98:99]
	v_mfma_f32_16x16x32_bf16 v[66:69], v[144:147], v[148:151], v[66:69]
	ds_read_b128 v[144:147], v130 offset:20480
	s_add_u32 m0, s100, 0xf000
	v_mfma_f32_16x16x32_bf16 v[62:65], v[158:161], v[148:151], v[62:65]
	global_load_lds_dwordx4 v205, s[98:99]
	v_mfma_f32_16x16x32_bf16 v[74:77], v[162:165], v[148:151], v[74:77]
	ds_read_b128 v[148:151], v130 offset:22528
	s_waitcnt lgkmcnt(3)
	v_mfma_f32_16x16x32_bf16 v[34:37], v[226:229], v[198:201], v[34:37]
	s_waitcnt lgkmcnt(2)
	v_mfma_f32_16x16x32_bf16 v[94:97], v[140:143], v[198:201], v[94:97]
	s_waitcnt lgkmcnt(1)
	v_mfma_f32_16x16x32_bf16 v[38:41], v[144:147], v[198:201], v[38:41]
	s_waitcnt lgkmcnt(0)
	v_mfma_f32_16x16x32_bf16 v[90:93], v[148:151], v[198:201], v[90:93]
	v_mfma_f32_16x16x32_bf16 v[42:45], v[226:229], v[206:209], v[42:45]
	v_mfma_f32_16x16x32_bf16 v[86:89], v[140:143], v[206:209], v[86:89]
	v_mfma_f32_16x16x32_bf16 v[46:49], v[144:147], v[206:209], v[46:49]
	v_mfma_f32_16x16x32_bf16 v[82:85], v[148:151], v[206:209], v[82:85]
	v_mfma_f32_16x16x32_bf16 v[50:53], v[226:229], v[214:217], v[50:53]
	v_mfma_f32_16x16x32_bf16 v[78:81], v[140:143], v[214:217], v[78:81]
	v_mfma_f32_16x16x32_bf16 v[54:57], v[144:147], v[214:217], v[54:57]
	v_mfma_f32_16x16x32_bf16 v[70:73], v[148:151], v[214:217], v[70:73]
	v_mfma_f32_16x16x32_bf16 v[58:61], v[226:229], v[132:135], v[58:61]
	v_mfma_f32_16x16x32_bf16 v[66:69], v[140:143], v[132:135], v[66:69]
	v_mfma_f32_16x16x32_bf16 v[62:65], v[144:147], v[132:135], v[62:65]
	v_mfma_f32_16x16x32_bf16 v[74:77], v[148:151], v[132:135], v[74:77]
	s_waitcnt vmcnt(0)
	s_setprio 0
	s_waitcnt lgkmcnt(0)
	s_barrier
	s_setprio 1
	s_add_u32 s98, s98, 0x80
	s_addc_u32 s99, s99, 0
	ds_read_b128 v[26:29], v122 offset:49152
	ds_read_b128 v[30:33], v122 offset:51200
	ds_read_b128 v[144:147], v122 offset:53248
	ds_read_b128 v[148:151], v122 offset:55296
	ds_read_b128 v[10:13], v124 offset:32768
	ds_read_b128 v[18:21], v124 offset:34816
	ds_read_b128 v[132:135], v124 offset:36864
	ds_read_b128 v[140:143], v124 offset:38912
	s_add_u32 m0, s100, 0x0
	s_waitcnt lgkmcnt(3)
	v_mfma_f32_16x16x32_bf16 v[34:37], v[26:29], v[10:13], v[34:37]
	global_load_lds_dwordx4 v194, s[98:99]
	v_mfma_f32_16x16x32_bf16 v[94:97], v[30:33], v[10:13], v[94:97]
	ds_read_b128 v[162:165], v123 offset:32768
	s_add_u32 m0, s100, 0x4000
	v_mfma_f32_16x16x32_bf16 v[38:41], v[144:147], v[10:13], v[38:41]
	global_load_lds_dwordx4 v195, s[98:99]
	v_mfma_f32_16x16x32_bf16 v[90:93], v[148:151], v[10:13], v[90:93]
	ds_read_b128 v[198:201], v123 offset:34816
	s_add_u32 m0, s100, 0x1000
	s_waitcnt lgkmcnt(4)
	v_mfma_f32_16x16x32_bf16 v[42:45], v[26:29], v[18:21], v[42:45]
	global_load_lds_dwordx4 v196, s[98:99]
	v_mfma_f32_16x16x32_bf16 v[86:89], v[30:33], v[18:21], v[86:89]
	ds_read_b128 v[206:209], v123 offset:36864
	s_add_u32 m0, s100, 0x5000
	v_mfma_f32_16x16x32_bf16 v[46:49], v[144:147], v[18:21], v[46:49]
	global_load_lds_dwordx4 v197, s[98:99]
	v_mfma_f32_16x16x32_bf16 v[82:85], v[148:151], v[18:21], v[82:85]
	ds_read_b128 v[214:217], v123 offset:38912
	s_add_u32 m0, s100, 0x2000
	s_waitcnt lgkmcnt(5)
	v_mfma_f32_16x16x32_bf16 v[50:53], v[26:29], v[132:135], v[50:53]
	global_load_lds_dwordx4 v202, s[98:99]
	v_mfma_f32_16x16x32_bf16 v[78:81], v[30:33], v[132:135], v[78:81]
	ds_read_b128 v[226:229], v130 offset:49152
	s_add_u32 m0, s100, 0x6000
	v_mfma_f32_16x16x32_bf16 v[54:57], v[144:147], v[132:135], v[54:57]
	global_load_lds_dwordx4 v203, s[98:99]
	v_mfma_f32_16x16x32_bf16 v[70:73], v[148:151], v[132:135], v[70:73]
	ds_read_b128 v[132:135], v130 offset:51200
	s_add_u32 m0, s100, 0x3000
	s_waitcnt lgkmcnt(6)
	v_mfma_f32_16x16x32_bf16 v[58:61], v[26:29], v[140:143], v[58:61]
	global_load_lds_dwordx4 v204, s[98:99]
	v_mfma_f32_16x16x32_bf16 v[66:69], v[30:33], v[140:143], v[66:69]
	ds_read_b128 v[234:237], v130 offset:53248
	s_add_u32 m0, s100, 0x7000
	v_mfma_f32_16x16x32_bf16 v[62:65], v[144:147], v[140:143], v[62:65]
	global_load_lds_dwordx4 v205, s[98:99]
	v_mfma_f32_16x16x32_bf16 v[74:77], v[148:151], v[140:143], v[74:77]
	ds_read_b128 v[140:143], v130 offset:55296
	s_waitcnt lgkmcnt(3)
	v_mfma_f32_16x16x32_bf16 v[34:37], v[226:229], v[162:165], v[34:37]
	s_waitcnt lgkmcnt(2)
	v_mfma_f32_16x16x32_bf16 v[94:97], v[132:135], v[162:165], v[94:97]
	s_waitcnt lgkmcnt(1)
	v_mfma_f32_16x16x32_bf16 v[38:41], v[234:237], v[162:165], v[38:41]
	s_waitcnt lgkmcnt(0)
	v_mfma_f32_16x16x32_bf16 v[90:93], v[140:143], v[162:165], v[90:93]
	v_mfma_f32_16x16x32_bf16 v[42:45], v[226:229], v[198:201], v[42:45]
	v_mfma_f32_16x16x32_bf16 v[86:89], v[132:135], v[198:201], v[86:89]
	v_mfma_f32_16x16x32_bf16 v[46:49], v[234:237], v[198:201], v[46:49]
	v_mfma_f32_16x16x32_bf16 v[82:85], v[140:143], v[198:201], v[82:85]
	v_mfma_f32_16x16x32_bf16 v[50:53], v[226:229], v[206:209], v[50:53]
	v_mfma_f32_16x16x32_bf16 v[78:81], v[132:135], v[206:209], v[78:81]
	v_mfma_f32_16x16x32_bf16 v[54:57], v[234:237], v[206:209], v[54:57]
	v_mfma_f32_16x16x32_bf16 v[70:73], v[140:143], v[206:209], v[70:73]
	v_mfma_f32_16x16x32_bf16 v[58:61], v[226:229], v[214:217], v[58:61]
	v_mfma_f32_16x16x32_bf16 v[66:69], v[132:135], v[214:217], v[66:69]
	v_mfma_f32_16x16x32_bf16 v[62:65], v[234:237], v[214:217], v[62:65]
	v_mfma_f32_16x16x32_bf16 v[74:77], v[140:143], v[214:217], v[74:77]
	s_waitcnt vmcnt(0)
	s_setprio 0
	s_add_i32 s5, s5, 2
	s_add_u32 s38, s38, 0x100
	s_addc_u32 s39, s39, 0
	s_cmp_lt_u32 s5, 12
	s_waitcnt lgkmcnt(0)
	s_barrier
	s_cbranch_scc1 .LBB0_157
	v_mov_b32_e32 v2, v194
	v_mov_b32_e32 v3, v195
	v_mov_b32_e32 v4, v196
	v_mov_b32_e32 v5, v197
	v_mov_b32_e32 v6, v202
	v_mov_b32_e32 v7, v203
	v_mov_b32_e32 v8, v204
	v_mov_b32_e32 v9, v205
	s_add_u32 s98, s38, s36
	s_addc_u32 s99, s39, 0
	s_add_u32 s98, s98, 0x80
	s_addc_u32 s99, s99, 0
	s_add_i32 s5, s11, s2
	s_cmpk_lt_u32 s5, 0x100
	s_cselect_b64 s[44:45], -1, 0
	s_and_b64 s[8:9], s[44:45], exec
	s_cselect_b32 s9, s5, s11
	s_lshr_b32 s8, s9, 3
	s_and_b32 s8, s8, 0x1fffff8
	s_add_i32 s8, s8, s21
	s_and_b32 s11, s9, 7
	v_mov_b32_e32 v0, v169
	s_or_b32 s8, s8, s11
	s_lshl_b32 s8, s8, 7
	v_lshrrev_b32_e32 v98, 3, v0
	v_lshlrev_b32_e32 v0, 3, v0
	v_add_u32_e32 v98, s8, v98
	v_and_b32_e32 v0, 56, v0
	v_lshl_or_b32 v0, v98, 10, v0
	v_mov_b32_e32 v98, v169
	s_lshl_b32 s9, s9, 4
	s_and_b32 s9, s9, 0x380
	v_lshrrev_b32_e32 v99, 3, v98
	v_lshlrev_b32_e32 v98, 3, v98
	v_add_u32_e32 v99, s9, v99
	v_and_b32_e32 v98, 56, v98
	v_add_u32_e32 v114, 0x8000, v0
	v_add_u32_e32 v136, 0x10000, v0
	v_lshl_or_b32 v162, v99, 10, v98
	v_add_u32_e32 v166, 0x18000, v0
	v_add_u32_e32 v174, 0x8000, v162
	v_add_u32_e32 v176, 0x10000, v162
	v_add_u32_e32 v178, 0x18000, v162
	s_setprio 1
	ds_read_b128 v[98:101], v122 offset:16384
	ds_read_b128 v[110:113], v122 offset:18432
	ds_read_b128 v[132:135], v122 offset:20480
	ds_read_b128 v[140:143], v122 offset:22528
	ds_read_b128 v[102:105], v124
	ds_read_b128 v[106:109], v124 offset:2048
	ds_read_b128 v[118:121], v124 offset:4096
	ds_read_b128 v[126:129], v124 offset:6144
	v_lshrrev_b32_e32 v14, 3, v169
	v_and_b32_e32 v15, 3, v14
	v_bfe_u32 v16, v14, 4, 1
	v_lshl_or_b32 v15, v16, 2, v15
	v_bfe_u32 v16, v14, 2, 1
	v_lshl_or_b32 v15, v16, 3, v15
	v_bfe_u32 v16, v14, 3, 1
	v_lshl_or_b32 v15, v16, 4, v15
	v_sub_u32_e32 v15, v15, v14
	v_mul_i32_i24_e32 v15, 0x400, v15
	v_and_b32_e32 v14, 7, v14
	v_lshlrev_b32_e32 v14, 3, v14
	v_xor_b32_e32 v0, v0, v14
	v_add_u32_e32 v162, v162, v15
	v_xor_b32_e32 v162, v162, v14
	v_xor_b32_e32 v114, v114, v14
	v_add_u32_e32 v174, v174, v15
	v_xor_b32_e32 v174, v174, v14
	v_xor_b32_e32 v136, v136, v14
	v_add_u32_e32 v176, v176, v15
	v_xor_b32_e32 v176, v176, v14
	v_xor_b32_e32 v166, v166, v14
	v_add_u32_e32 v178, v178, v15
	v_xor_b32_e32 v178, v178, v14
	v_readlane_b32 s14, v254, 45
	v_readlane_b32 s15, v254, 46
	v_mov_b32_e32 v163, v1
	v_mov_b32_e32 v115, v1
	v_mov_b32_e32 v175, v1
	v_mov_b32_e32 v137, v1
	v_mov_b32_e32 v177, v1
	v_mov_b32_e32 v167, v1
	v_mov_b32_e32 v179, v1
	v_lshl_add_u64 v[180:181], v[0:1], 1, s[14:15]
	v_lshl_add_u64 v[186:187], v[162:163], 1, s[34:35]
	v_lshl_add_u64 v[188:189], v[114:115], 1, s[14:15]
	v_lshl_add_u64 v[174:175], v[174:175], 1, s[34:35]
	v_lshl_add_u64 v[136:137], v[136:137], 1, s[14:15]
	v_lshl_add_u64 v[176:177], v[176:177], 1, s[34:35]
	v_lshl_add_u64 v[166:167], v[166:167], 1, s[14:15]
	v_lshl_add_u64 v[178:179], v[178:179], 1, s[34:35]
	s_add_u32 m0, s100, 0x8000
	s_waitcnt lgkmcnt(3)
	v_mfma_f32_16x16x32_bf16 v[144:147], v[98:101], v[102:105], v[34:37]
	global_load_lds_dwordx4 v2, s[98:99]
	v_mfma_f32_16x16x32_bf16 v[94:97], v[110:113], v[102:105], v[94:97]
	ds_read_b128 v[148:151], v123
	s_add_u32 m0, s100, 0xc000
	v_mfma_f32_16x16x32_bf16 v[158:161], v[132:135], v[102:105], v[38:41]
	global_load_lds_dwordx4 v3, s[98:99]
	v_mfma_f32_16x16x32_bf16 v[90:93], v[140:143], v[102:105], v[90:93]
	ds_read_b128 v[102:105], v123 offset:2048
	s_add_u32 m0, s100, 0x9000
	s_waitcnt lgkmcnt(4)
	v_mfma_f32_16x16x32_bf16 v[162:165], v[98:101], v[106:109], v[42:45]
	global_load_lds_dwordx4 v4, s[98:99]
	v_mfma_f32_16x16x32_bf16 v[86:89], v[110:113], v[106:109], v[86:89]
	ds_read_b128 v[194:197], v123 offset:4096
	s_add_u32 m0, s100, 0xd000
	v_mfma_f32_16x16x32_bf16 v[198:201], v[132:135], v[106:109], v[46:49]
	global_load_lds_dwordx4 v5, s[98:99]
	v_mfma_f32_16x16x32_bf16 v[82:85], v[140:143], v[106:109], v[82:85]
	ds_read_b128 v[106:109], v123 offset:6144
	s_add_u32 m0, s100, 0xa000
	s_waitcnt lgkmcnt(5)
	v_mfma_f32_16x16x32_bf16 v[202:205], v[98:101], v[118:121], v[50:53]
	global_load_lds_dwordx4 v6, s[98:99]
	v_mfma_f32_16x16x32_bf16 v[78:81], v[110:113], v[118:121], v[78:81]
	ds_read_b128 v[206:209], v130 offset:16384
	s_add_u32 m0, s100, 0xe000
	v_mfma_f32_16x16x32_bf16 v[210:213], v[132:135], v[118:121], v[54:57]
	global_load_lds_dwordx4 v7, s[98:99]
	v_mfma_f32_16x16x32_bf16 v[70:73], v[140:143], v[118:121], v[70:73]
	ds_read_b128 v[118:121], v130 offset:18432
	s_add_u32 m0, s100, 0xb000
	s_waitcnt lgkmcnt(6)
	v_mfma_f32_16x16x32_bf16 v[98:101], v[98:101], v[126:129], v[58:61]
	global_load_lds_dwordx4 v8, s[98:99]
	v_mfma_f32_16x16x32_bf16 v[66:69], v[110:113], v[126:129], v[66:69]
	ds_read_b128 v[110:113], v130 offset:20480
	s_add_u32 m0, s100, 0xf000
	v_mfma_f32_16x16x32_bf16 v[132:135], v[132:135], v[126:129], v[62:65]
	global_load_lds_dwordx4 v9, s[98:99]
	v_mfma_f32_16x16x32_bf16 v[74:77], v[140:143], v[126:129], v[74:77]
	ds_read_b128 v[126:129], v130 offset:22528
	s_waitcnt lgkmcnt(3)
	v_mfma_f32_16x16x32_bf16 v[140:143], v[206:209], v[148:151], v[144:147]
	s_waitcnt lgkmcnt(2)
	v_mfma_f32_16x16x32_bf16 v[94:97], v[118:121], v[148:151], v[94:97]
	s_waitcnt lgkmcnt(1)
	v_mfma_f32_16x16x32_bf16 v[144:147], v[110:113], v[148:151], v[158:161]
	s_waitcnt lgkmcnt(0)
	v_mfma_f32_16x16x32_bf16 v[90:93], v[126:129], v[148:151], v[90:93]
	v_mfma_f32_16x16x32_bf16 v[148:151], v[206:209], v[102:105], v[162:165]
	v_mfma_f32_16x16x32_bf16 v[86:89], v[118:121], v[102:105], v[86:89]
	v_mfma_f32_16x16x32_bf16 v[158:161], v[110:113], v[102:105], v[198:201]
	v_mfma_f32_16x16x32_bf16 v[82:85], v[126:129], v[102:105], v[82:85]
	v_mfma_f32_16x16x32_bf16 v[102:105], v[206:209], v[194:197], v[202:205]
	v_mfma_f32_16x16x32_bf16 v[78:81], v[118:121], v[194:197], v[78:81]
	v_mfma_f32_16x16x32_bf16 v[162:165], v[110:113], v[194:197], v[210:213]
	v_mfma_f32_16x16x32_bf16 v[70:73], v[126:129], v[194:197], v[70:73]
	v_mfma_f32_16x16x32_bf16 v[98:101], v[206:209], v[106:109], v[98:101]
	v_mfma_f32_16x16x32_bf16 v[66:69], v[118:121], v[106:109], v[66:69]
	v_mfma_f32_16x16x32_bf16 v[110:113], v[110:113], v[106:109], v[132:135]
	v_mfma_f32_16x16x32_bf16 v[74:77], v[126:129], v[106:109], v[74:77]
	s_waitcnt vmcnt(0)
	s_setprio 0
	s_waitcnt lgkmcnt(0)
	s_barrier
	s_setprio 1
	ds_read_b128 v[26:29], v122 offset:49152
	ds_read_b128 v[10:13], v124 offset:32768
	ds_read_b128 v[18:21], v124 offset:34816
	ds_read_b128 v[30:33], v122 offset:51200
	ds_read_b128 v[106:109], v124 offset:36864
	ds_read_b128 v[114:117], v124 offset:38912
	ds_read_b128 v[118:121], v122 offset:53248
	ds_read_b128 v[124:127], v122 offset:55296
	s_add_u32 m0, s100, 0x0
	s_waitcnt lgkmcnt(6)
	v_mfma_f32_16x16x32_bf16 v[132:135], v[26:29], v[10:13], v[140:143]
	global_load_lds_dwordx4 v[180:181], off
	s_waitcnt lgkmcnt(4)
	v_mfma_f32_16x16x32_bf16 v[94:97], v[30:33], v[10:13], v[94:97]
	ds_read_b128 v[140:143], v123 offset:32768
	s_add_u32 m0, s100, 0x4000
	s_waitcnt lgkmcnt(2)
	v_mfma_f32_16x16x32_bf16 v[144:147], v[118:121], v[10:13], v[144:147]
	global_load_lds_dwordx4 v[186:187], off
	s_waitcnt lgkmcnt(1)
	v_mfma_f32_16x16x32_bf16 v[90:93], v[124:127], v[10:13], v[90:93]
	ds_read_b128 v[194:197], v123 offset:34816
	s_add_u32 m0, s100, 0x1000
	v_mfma_f32_16x16x32_bf16 v[148:151], v[26:29], v[18:21], v[148:151]
	global_load_lds_dwordx4 v[188:189], off
	v_mfma_f32_16x16x32_bf16 v[86:89], v[30:33], v[18:21], v[86:89]
	ds_read_b128 v[198:201], v123 offset:36864
	s_add_u32 m0, s100, 0x5000
	v_mfma_f32_16x16x32_bf16 v[158:161], v[118:121], v[18:21], v[158:161]
	global_load_lds_dwordx4 v[174:175], off
	v_mfma_f32_16x16x32_bf16 v[82:85], v[124:127], v[18:21], v[82:85]
	ds_read_b128 v[202:205], v123 offset:38912
	s_add_u32 m0, s100, 0x2000
	v_mfma_f32_16x16x32_bf16 v[206:209], v[26:29], v[106:109], v[102:105]
	global_load_lds_dwordx4 v[136:137], off
	v_mfma_f32_16x16x32_bf16 v[78:81], v[30:33], v[106:109], v[78:81]
	ds_read_b128 v[210:213], v130 offset:49152
	s_add_u32 m0, s100, 0x6000
	v_mfma_f32_16x16x32_bf16 v[162:165], v[118:121], v[106:109], v[162:165]
	global_load_lds_dwordx4 v[176:177], off
	v_mfma_f32_16x16x32_bf16 v[70:73], v[124:127], v[106:109], v[70:73]
	ds_read_b128 v[214:217], v130 offset:51200
	s_add_u32 m0, s100, 0x3000
	v_mfma_f32_16x16x32_bf16 v[218:221], v[26:29], v[114:117], v[98:101]
	global_load_lds_dwordx4 v[166:167], off
	v_mfma_f32_16x16x32_bf16 v[66:69], v[30:33], v[114:117], v[66:69]
	ds_read_b128 v[222:225], v130 offset:53248
	s_add_u32 m0, s100, 0x7000
	v_mfma_f32_16x16x32_bf16 v[226:229], v[118:121], v[114:117], v[110:113]
	global_load_lds_dwordx4 v[178:179], off
	v_mfma_f32_16x16x32_bf16 v[230:233], v[124:127], v[114:117], v[74:77]
	s_waitcnt lgkmcnt(2)
	v_mfma_f32_16x16x32_bf16 v[126:129], v[210:213], v[140:143], v[132:135]
	ds_read_b128 v[130:133], v130 offset:55296
	s_waitcnt lgkmcnt(2)
	v_mfma_f32_16x16x32_bf16 v[122:125], v[214:217], v[140:143], v[94:97]
	s_waitcnt lgkmcnt(1)
	v_mfma_f32_16x16x32_bf16 v[118:121], v[222:225], v[140:143], v[144:147]
	s_waitcnt lgkmcnt(0)
	v_mfma_f32_16x16x32_bf16 v[114:117], v[130:133], v[140:143], v[90:93]
	v_mfma_f32_16x16x32_bf16 v[110:113], v[210:213], v[194:197], v[148:151]
	v_mfma_f32_16x16x32_bf16 v[106:109], v[214:217], v[194:197], v[86:89]
	v_mfma_f32_16x16x32_bf16 v[102:105], v[222:225], v[194:197], v[158:161]
	v_mfma_f32_16x16x32_bf16 v[98:101], v[130:133], v[194:197], v[82:85]
	v_mfma_f32_16x16x32_bf16 v[94:97], v[210:213], v[198:201], v[206:209]
	v_mfma_f32_16x16x32_bf16 v[90:93], v[214:217], v[198:201], v[78:81]
	v_mfma_f32_16x16x32_bf16 v[86:89], v[222:225], v[198:201], v[162:165]
	v_mfma_f32_16x16x32_bf16 v[82:85], v[130:133], v[198:201], v[70:73]
	v_mfma_f32_16x16x32_bf16 v[78:81], v[210:213], v[202:205], v[218:221]
	v_mfma_f32_16x16x32_bf16 v[74:77], v[214:217], v[202:205], v[66:69]
	v_mfma_f32_16x16x32_bf16 v[70:73], v[222:225], v[202:205], v[226:229]
	v_mfma_f32_16x16x32_bf16 v[66:69], v[130:133], v[202:205], v[230:233]
	s_setprio 0
	v_add_u32_e32 v134, s4, v152
	v_ashrrev_i32_e32 v135, 31, v134
	v_lshlrev_b64 v[136:137], 12, v[134:135]
	v_or_b32_e32 v140, s10, v153
	v_mov_b32_e32 v141, v1
	v_cndmask_b32_e64 v0, 0, 1, s[42:43]
	v_lshl_add_u64 v[130:131], s[40:41], 0, v[136:137]
	v_cmp_ne_u32_e64 s[38:39], 1, v0
	s_andn2_b64 vcc, exec, s[42:43]
	v_lshl_add_u64 v[146:147], v[140:141], 2, v[130:131]
	s_barrier
	s_cbranch_vccnz .LBB0_160
	global_load_dwordx4 v[130:133], v[146:147], off
	s_mov_b64 s[46:47], 0
	s_branch .LBB0_161

.LBB0_468:
	s_and_b64 vcc, exec, s[0:1]
	s_cbranch_vccz .LBB0_668
	v_readlane_b32 s0, v255, 40
	s_cmp_lg_u32 s0, 0
	s_cbranch_scc1 .LBB0_668
	v_readlane_b32 s0, v254, 55
	v_readlane_b32 s1, v254, 56
	s_mov_b64 s[28:29], 0
	v_mov_b32_e32 v80, v169
	s_andn2_b64 vcc, exec, s[0:1]
	s_cbranch_vccnz .LBB0_668
	v_mov_b32_e32 v0, v169
	s_load_dword s2, s[22:23], 0x0
	v_readlane_b32 s9, v254, 58
	s_waitcnt vmcnt(7)
	v_lshrrev_b32_e32 v2, 3, v0
	v_lshlrev_b32_e32 v0, 3, v0
	v_add_u32_e32 v2, s9, v2
	v_and_b32_e32 v0, 56, v0
	s_add_u32 s34, s72, s28
	v_lshl_or_b32 v0, v2, 10, v0
	v_mov_b32_e32 v2, v169
	v_readlane_b32 s0, v255, 36
	s_addc_u32 s35, s73, s29
	v_readlane_b32 s1, v255, 37
	s_add_u32 s48, s34, 0x4991000
	v_lshrrev_b32_e32 v3, 3, v2
	v_readlane_b32 s10, v254, 59
	v_lshlrev_b32_e32 v2, 3, v2
	s_mul_hi_i32 s1, s0, 0x840000
	s_mul_i32 s0, s0, 0x840000
	s_addc_u32 s49, s35, 0
	v_add_u32_e32 v3, s10, v3
	v_and_b32_e32 v2, 56, v2
	s_add_u32 s50, s34, s0
	v_lshl_or_b32 v72, v3, 10, v2
	s_addc_u32 s51, s35, s1
	s_waitcnt lgkmcnt(0)
	v_add_u32_e32 v66, 0x8000, v0
	v_add_u32_e32 v68, 0x10000, v0
	v_add_u32_e32 v70, 0x18000, v0
	v_add_u32_e32 v74, 0x8000, v72
	v_add_u32_e32 v76, 0x10000, v72
	v_add_u32_e32 v78, 0x18000, v72
	v_mov_b32_e32 v73, v1
	v_mov_b32_e32 v67, v1
	v_mov_b32_e32 v75, v1
	v_mov_b32_e32 v69, v1
	v_mov_b32_e32 v77, v1
	v_mov_b32_e32 v71, v1
	v_mov_b32_e32 v79, v1
	v_lshl_add_u64 v[2:3], v[0:1], 1, s[48:49]
	s_waitcnt vmcnt(6)
	v_lshl_add_u64 v[6:7], v[72:73], 1, s[50:51]
	s_waitcnt vmcnt(5)
	v_lshl_add_u64 v[10:11], v[66:67], 1, s[48:49]
	s_waitcnt vmcnt(4)
	v_lshl_add_u64 v[14:15], v[74:75], 1, s[50:51]
	s_waitcnt vmcnt(3)
	v_lshl_add_u64 v[18:19], v[68:69], 1, s[48:49]
	s_waitcnt vmcnt(2)
	v_lshl_add_u64 v[22:23], v[76:77], 1, s[50:51]
	s_waitcnt vmcnt(1)
	v_lshl_add_u64 v[26:27], v[70:71], 1, s[48:49]
	s_waitcnt vmcnt(0)
	v_lshl_add_u64 v[30:31], v[78:79], 1, s[50:51]
	v_lshrrev_b32_e32 v34, 6, v169
	v_lshlrev_b32_e32 v34, 10, v34
	s_nop 0
	v_readfirstlane_b32 s100, v34
	v_lshrrev_b32_e32 v35, 3, v169
	v_and_b32_e32 v36, 3, v35
	v_bfe_u32 v37, v35, 4, 1
	v_lshl_or_b32 v36, v37, 2, v36
	v_bfe_u32 v37, v35, 2, 1
	v_lshl_or_b32 v36, v37, 3, v36
	v_bfe_u32 v37, v35, 3, 1
	v_lshl_or_b32 v36, v37, 4, v36
	v_sub_u32_e32 v36, v36, v35
	v_mul_i32_i24_e32 v36, 0x800, v36
	v_and_b32_e32 v35, 7, v35
	v_lshlrev_b32_e32 v35, 4, v35
	v_ashrrev_i32_e32 v37, 31, v36
	v_xor_b32_e32 v2, v2, v35
	v_lshl_add_u64 v[6:7], v[6:7], 0, v[36:37]
	v_xor_b32_e32 v6, v6, v35
	v_xor_b32_e32 v10, v10, v35
	v_lshl_add_u64 v[14:15], v[14:15], 0, v[36:37]
	v_xor_b32_e32 v14, v14, v35
	v_xor_b32_e32 v18, v18, v35
	v_lshl_add_u64 v[22:23], v[22:23], 0, v[36:37]
	v_xor_b32_e32 v22, v22, v35
	v_xor_b32_e32 v26, v26, v35
	v_lshl_add_u64 v[30:31], v[30:31], 0, v[36:37]
	v_xor_b32_e32 v30, v30, v35
	s_add_u32 m0, s100, 0x0
	s_nop 0
	global_load_lds_dwordx4 v[2:3], off
	s_add_u32 m0, s100, 0x4000
	s_nop 0
	global_load_lds_dwordx4 v[6:7], off
	s_add_u32 m0, s100, 0x1000
	s_nop 0
	global_load_lds_dwordx4 v[10:11], off
	s_add_u32 m0, s100, 0x5000
	s_nop 0
	global_load_lds_dwordx4 v[14:15], off
	s_add_u32 m0, s100, 0x2000
	s_nop 0
	global_load_lds_dwordx4 v[18:19], off
	s_add_u32 m0, s100, 0x6000
	s_nop 0
	global_load_lds_dwordx4 v[22:23], off
	s_add_u32 m0, s100, 0x3000
	s_nop 0
	global_load_lds_dwordx4 v[26:27], off
	s_add_u32 m0, s100, 0x7000
	s_nop 0
	global_load_lds_dwordx4 v[30:31], off
	s_waitcnt vmcnt(0)
	s_waitcnt lgkmcnt(0)
	s_lshr_b32 s2, s2, 3
	s_add_u32 s52, s34, 0x16991000
	s_addc_u32 s53, s35, 0
	v_readlane_b32 s4, v255, 38
	s_add_u32 s54, s34, 0xa991000
	v_readlane_b32 s5, v255, 39
	s_addc_u32 s55, s35, 0
	s_lshl_b64 s[4:5], s[4:5], 2
	s_add_u32 s4, s34, s4
	v_ashrrev_i32_e32 v71, 1, v80
	s_addc_u32 s5, s35, s5
	v_and_b32_e32 v67, 64, v80
	v_and_b32_e32 v69, 63, v80
	v_and_b32_e32 v141, 0xffffffc0, v71
	v_lshrrev_b32_e32 v71, 1, v80
	s_add_u32 s4, s4, 0x1a9d49d0
	v_and_b32_e32 v140, 15, v80
	v_and_or_b32 v142, v71, 24, v67
	v_cmp_eq_u32_e64 s[38:39], 0, v69
	s_addc_u32 s5, s5, 0
	v_readlane_b32 s8, v254, 57
	s_branch .LBB0_474

.LBB0_474:
	v_mov_b32_e32 v67, v169
	s_mov_b32 s11, s8
	v_lshrrev_b32_e32 v69, 4, v67
	v_ashrrev_i32_e32 v71, 3, v67
	v_lshrrev_b32_e32 v77, 1, v67
	v_and_b32_e32 v80, 4, v69
	v_and_b32_e32 v81, 3, v71
	v_and_b32_e32 v73, 7, v67
	v_xor_b32_e32 v75, v71, v67
	v_and_b32_e32 v77, 16, v77
	v_and_b32_e32 v79, 8, v69
	v_or_b32_e32 v82, v80, v81
	v_lshlrev_b32_e32 v75, 4, v75
	v_or3_b32 v77, v77, v79, v82
	v_bitop3_b32 v79, v80, v73, v81 bitop3:0x36
	v_lshlrev_b32_e32 v71, 7, v71
	v_lshlrev_b32_e32 v79, 4, v79
	v_and_or_b32 v115, v75, s24, v71
	v_lshl_or_b32 v114, v77, 7, v79
	v_lshlrev_b32_e32 v35, 7, v67
	v_bfe_u32 v34, v67, 4, 2
	v_and_b32_e32 v36, 0x780, v35
	v_and_b32_e32 v116, 0x2780, v35
	v_bitop3_b32 v35, v69, v73, 3 bitop3:0x6c
	v_mov_b32_e32 v75, v1
	v_lshlrev_b32_e32 v117, 4, v35
	v_lshlrev_b32_e32 v35, 6, v67
	v_bitop3_b32 v34, v34, v73, 4 bitop3:0x36
	v_mov_b32_e32 v73, v1
	v_mov_b32_e32 v67, v1
	v_mov_b32_e32 v69, v1
	v_mov_b32_e32 v77, v1
	v_mov_b32_e32 v71, v1
	v_mov_b32_e32 v79, v1
	v_lshl_add_u64 v[100:101], v[74:75], 1, s[0:1]
	v_mov_b32_e32 v74, 0
	s_mov_b32 s16, s10
	v_and_or_b32 v118, v35, s30, v36
	v_lshlrev_b32_e32 v119, 4, v34
	v_lshl_add_u64 v[98:99], v[72:73], 1, s[0:1]
	v_lshl_add_u64 v[102:103], v[76:77], 1, s[0:1]
	v_lshl_add_u64 v[104:105], v[78:79], 1, s[0:1]
	v_lshlrev_b64 v[106:107], 1, v[0:1]
	s_waitcnt lgkmcnt(8)
	v_lshlrev_b64 v[108:109], 1, v[66:67]
	v_lshlrev_b64 v[110:111], 1, v[68:69]
	v_lshlrev_b64 v[112:113], 1, v[70:71]
	s_mov_b32 s8, -2
	s_mov_b64 s[28:29], s[34:35]
	v_mov_b32_e32 v75, v74
	v_mov_b32_e32 v76, v74
	v_mov_b32_e32 v77, v74
	v_mov_b32_e32 v62, v74
	v_mov_b32_e32 v63, v74
	v_mov_b32_e32 v64, v74
	v_mov_b32_e32 v65, v74
	v_mov_b32_e32 v66, v74
	v_mov_b32_e32 v67, v74
	v_mov_b32_e32 v68, v74
	v_mov_b32_e32 v69, v74
	v_mov_b32_e32 v58, v74
	v_mov_b32_e32 v59, v74
	v_mov_b32_e32 v60, v74
	v_mov_b32_e32 v61, v74
	v_mov_b32_e32 v70, v74
	v_mov_b32_e32 v71, v74
	v_mov_b32_e32 v72, v74
	v_mov_b32_e32 v73, v74
	v_mov_b32_e32 v54, v74
	v_mov_b32_e32 v55, v74
	v_mov_b32_e32 v56, v74
	v_mov_b32_e32 v57, v74
	v_mov_b32_e32 v78, v74
	v_mov_b32_e32 v79, v74
	v_mov_b32_e32 v80, v74
	v_mov_b32_e32 v81, v74
	v_mov_b32_e32 v50, v74
	v_mov_b32_e32 v51, v74
	v_mov_b32_e32 v52, v74
	v_mov_b32_e32 v53, v74
	v_mov_b32_e32 v82, v74
	v_mov_b32_e32 v83, v74
	v_mov_b32_e32 v84, v74
	v_mov_b32_e32 v85, v74
	v_mov_b32_e32 v46, v74
	v_mov_b32_e32 v47, v74
	v_mov_b32_e32 v48, v74
	v_mov_b32_e32 v49, v74
	v_mov_b32_e32 v86, v74
	v_mov_b32_e32 v87, v74
	v_mov_b32_e32 v88, v74
	v_mov_b32_e32 v89, v74
	v_mov_b32_e32 v42, v74
	v_mov_b32_e32 v43, v74
	v_mov_b32_e32 v44, v74
	v_mov_b32_e32 v45, v74
	v_mov_b32_e32 v90, v74
	v_mov_b32_e32 v91, v74
	v_mov_b32_e32 v92, v74
	v_mov_b32_e32 v93, v74
	v_mov_b32_e32 v38, v74
	v_mov_b32_e32 v39, v74
	v_mov_b32_e32 v40, v74
	v_mov_b32_e32 v41, v74
	v_mov_b32_e32 v94, v74
	v_mov_b32_e32 v95, v74
	v_mov_b32_e32 v96, v74
	v_mov_b32_e32 v97, v74
	v_mov_b32_e32 v34, v74
	v_mov_b32_e32 v35, v74
	v_mov_b32_e32 v36, v74
	v_mov_b32_e32 v37, v74
	s_waitcnt vmcnt(0)
	s_waitcnt lgkmcnt(0)
	s_barrier
	v_lshrrev_b32_e32 v218, 6, v169
	v_lshlrev_b32_e32 v218, 10, v218
	v_lshrrev_b32_e32 v219, 3, v169
	v_readfirstlane_b32 s100, v218
	v_and_b32_e32 v218, 3, v219
	v_bfe_u32 v220, v219, 4, 1
	v_lshl_or_b32 v218, v220, 2, v218
	v_bfe_u32 v220, v219, 2, 1
	v_lshl_or_b32 v218, v220, 3, v218
	v_bfe_u32 v220, v219, 3, 1
	v_lshl_or_b32 v218, v220, 4, v218
	v_sub_u32_e32 v218, v218, v219
	v_mul_i32_i24_e32 v218, 0x800, v218
	v_and_b32_e32 v219, 7, v219
	v_lshlrev_b32_e32 v219, 4, v219
	v_add_u32_e32 v206, 0x4991000, v106
	v_xor_b32_e32 v164, v206, v219
	v_mov_b32_e32 v207, v98
	v_add_u32_e32 v165, v207, v218
	v_xor_b32_e32 v165, v165, v219
	v_add_u32_e32 v208, 0x4991000, v108
	v_xor_b32_e32 v166, v208, v219
	v_mov_b32_e32 v209, v100
	v_add_u32_e32 v167, v209, v218
	v_xor_b32_e32 v167, v167, v219
	v_add_u32_e32 v214, 0x4991000, v110
	v_xor_b32_e32 v198, v214, v219
	v_mov_b32_e32 v215, v102
	v_add_u32_e32 v199, v215, v218
	v_xor_b32_e32 v199, v199, v219
	v_add_u32_e32 v216, 0x4991000, v112
	v_xor_b32_e32 v200, v216, v219
	v_mov_b32_e32 v217, v104
	v_add_u32_e32 v201, v217, v218
	v_xor_b32_e32 v201, v201, v219
.LBB0_475:
	s_setprio 1
	s_add_u32 s98, s28, 0x80
	s_addc_u32 s99, s29, 0
	v_add_u32_e32 v120, v117, v116
	v_add_u32_e32 v122, v117, v118
	v_add_u32_e32 v121, v119, v118
	ds_read_b128 v[124:127], v120 offset:16384
	ds_read_b128 v[144:147], v120 offset:18432
	ds_read_b128 v[156:159], v120 offset:20480
	ds_read_b128 v[160:163], v120 offset:22528
	ds_read_b128 v[128:131], v122
	ds_read_b128 v[132:135], v122 offset:2048
	ds_read_b128 v[148:151], v122 offset:4096
	ds_read_b128 v[152:155], v122 offset:6144
	s_add_u32 m0, s100, 0x8000
	s_waitcnt lgkmcnt(3)
	v_mfma_f32_16x16x32_bf16 v[34:37], v[124:127], v[128:131], v[34:37]
	global_load_lds_dwordx4 v164, s[98:99]
	v_mfma_f32_16x16x32_bf16 v[94:97], v[144:147], v[128:131], v[94:97]
	ds_read_b128 v[194:197], v121
	s_add_u32 m0, s100, 0xc000
	v_mfma_f32_16x16x32_bf16 v[38:41], v[156:159], v[128:131], v[38:41]
	global_load_lds_dwordx4 v165, s[98:99]
	v_mfma_f32_16x16x32_bf16 v[90:93], v[160:163], v[128:131], v[90:93]
	v_add_u32_e32 v130, v119, v116
	ds_read_b128 v[202:205], v121 offset:2048
	s_add_u32 m0, s100, 0x9000
	s_waitcnt lgkmcnt(4)
	v_mfma_f32_16x16x32_bf16 v[42:45], v[124:127], v[132:135], v[42:45]
	global_load_lds_dwordx4 v166, s[98:99]
	v_mfma_f32_16x16x32_bf16 v[86:89], v[144:147], v[132:135], v[86:89]
	ds_read_b128 v[210:213], v121 offset:4096
	s_add_u32 m0, s100, 0xd000
	v_mfma_f32_16x16x32_bf16 v[46:49], v[156:159], v[132:135], v[46:49]
	global_load_lds_dwordx4 v167, s[98:99]
	v_mfma_f32_16x16x32_bf16 v[82:85], v[160:163], v[132:135], v[82:85]
	ds_read_b128 v[132:135], v121 offset:6144
	s_add_u32 m0, s100, 0xa000
	s_waitcnt lgkmcnt(5)
	v_mfma_f32_16x16x32_bf16 v[50:53], v[124:127], v[148:151], v[50:53]
	global_load_lds_dwordx4 v198, s[98:99]
	v_mfma_f32_16x16x32_bf16 v[78:81], v[144:147], v[148:151], v[78:81]
	ds_read_b128 v[222:225], v130 offset:16384
	s_add_u32 m0, s100, 0xe000
	v_mfma_f32_16x16x32_bf16 v[54:57], v[156:159], v[148:151], v[54:57]
	global_load_lds_dwordx4 v199, s[98:99]
	v_mfma_f32_16x16x32_bf16 v[70:73], v[160:163], v[148:151], v[70:73]
	ds_read_b128 v[148:151], v130 offset:18432
	s_add_u32 m0, s100, 0xb000
	s_waitcnt lgkmcnt(6)
	v_mfma_f32_16x16x32_bf16 v[58:61], v[124:127], v[152:155], v[58:61]
	global_load_lds_dwordx4 v200, s[98:99]
	v_mfma_f32_16x16x32_bf16 v[66:69], v[144:147], v[152:155], v[66:69]
	ds_read_b128 v[144:147], v130 offset:20480
	s_add_u32 m0, s100, 0xf000
	v_mfma_f32_16x16x32_bf16 v[62:65], v[156:159], v[152:155], v[62:65]
	global_load_lds_dwordx4 v201, s[98:99]
	v_mfma_f32_16x16x32_bf16 v[74:77], v[160:163], v[152:155], v[74:77]
	ds_read_b128 v[152:155], v130 offset:22528
	s_waitcnt lgkmcnt(3)
	v_mfma_f32_16x16x32_bf16 v[34:37], v[222:225], v[194:197], v[34:37]
	s_waitcnt lgkmcnt(2)
	v_mfma_f32_16x16x32_bf16 v[94:97], v[148:151], v[194:197], v[94:97]
	s_waitcnt lgkmcnt(1)
	v_mfma_f32_16x16x32_bf16 v[38:41], v[144:147], v[194:197], v[38:41]
	s_waitcnt lgkmcnt(0)
	v_mfma_f32_16x16x32_bf16 v[90:93], v[152:155], v[194:197], v[90:93]
	v_mfma_f32_16x16x32_bf16 v[42:45], v[222:225], v[202:205], v[42:45]
	v_mfma_f32_16x16x32_bf16 v[86:89], v[148:151], v[202:205], v[86:89]
	v_mfma_f32_16x16x32_bf16 v[46:49], v[144:147], v[202:205], v[46:49]
	v_mfma_f32_16x16x32_bf16 v[82:85], v[152:155], v[202:205], v[82:85]
	v_mfma_f32_16x16x32_bf16 v[50:53], v[222:225], v[210:213], v[50:53]
	v_mfma_f32_16x16x32_bf16 v[78:81], v[148:151], v[210:213], v[78:81]
	v_mfma_f32_16x16x32_bf16 v[54:57], v[144:147], v[210:213], v[54:57]
	v_mfma_f32_16x16x32_bf16 v[70:73], v[152:155], v[210:213], v[70:73]
	v_mfma_f32_16x16x32_bf16 v[58:61], v[222:225], v[132:135], v[58:61]
	v_mfma_f32_16x16x32_bf16 v[66:69], v[148:151], v[132:135], v[66:69]
	v_mfma_f32_16x16x32_bf16 v[62:65], v[144:147], v[132:135], v[62:65]
	v_mfma_f32_16x16x32_bf16 v[74:77], v[152:155], v[132:135], v[74:77]
	s_waitcnt vmcnt(0)
	s_setprio 0
	s_waitcnt lgkmcnt(0)
	s_barrier
	s_setprio 1
	s_add_u32 s98, s98, 0x80
	s_addc_u32 s99, s99, 0
	ds_read_b128 v[26:29], v120 offset:49152
	ds_read_b128 v[30:33], v120 offset:51200
	ds_read_b128 v[148:151], v120 offset:53248
	ds_read_b128 v[152:155], v120 offset:55296
	ds_read_b128 v[10:13], v122 offset:32768
	ds_read_b128 v[18:21], v122 offset:34816
	ds_read_b128 v[132:135], v122 offset:36864
	ds_read_b128 v[144:147], v122 offset:38912
	s_add_u32 m0, s100, 0x0
	s_waitcnt lgkmcnt(3)
	v_mfma_f32_16x16x32_bf16 v[34:37], v[26:29], v[10:13], v[34:37]
	global_load_lds_dwordx4 v164, s[98:99]
	v_mfma_f32_16x16x32_bf16 v[94:97], v[30:33], v[10:13], v[94:97]
	ds_read_b128 v[160:163], v121 offset:32768
	s_add_u32 m0, s100, 0x4000
	v_mfma_f32_16x16x32_bf16 v[38:41], v[148:151], v[10:13], v[38:41]
	global_load_lds_dwordx4 v165, s[98:99]
	v_mfma_f32_16x16x32_bf16 v[90:93], v[152:155], v[10:13], v[90:93]
	ds_read_b128 v[194:197], v121 offset:34816
	s_add_u32 m0, s100, 0x1000
	s_waitcnt lgkmcnt(4)
	v_mfma_f32_16x16x32_bf16 v[42:45], v[26:29], v[18:21], v[42:45]
	global_load_lds_dwordx4 v166, s[98:99]
	v_mfma_f32_16x16x32_bf16 v[86:89], v[30:33], v[18:21], v[86:89]
	ds_read_b128 v[202:205], v121 offset:36864
	s_add_u32 m0, s100, 0x5000
	v_mfma_f32_16x16x32_bf16 v[46:49], v[148:151], v[18:21], v[46:49]
	global_load_lds_dwordx4 v167, s[98:99]
	v_mfma_f32_16x16x32_bf16 v[82:85], v[152:155], v[18:21], v[82:85]
	ds_read_b128 v[210:213], v121 offset:38912
	s_add_u32 m0, s100, 0x2000
	s_waitcnt lgkmcnt(5)
	v_mfma_f32_16x16x32_bf16 v[50:53], v[26:29], v[132:135], v[50:53]
	global_load_lds_dwordx4 v198, s[98:99]
	v_mfma_f32_16x16x32_bf16 v[78:81], v[30:33], v[132:135], v[78:81]
	ds_read_b128 v[222:225], v130 offset:49152
	s_add_u32 m0, s100, 0x6000
	v_mfma_f32_16x16x32_bf16 v[54:57], v[148:151], v[132:135], v[54:57]
	global_load_lds_dwordx4 v199, s[98:99]
	v_mfma_f32_16x16x32_bf16 v[70:73], v[152:155], v[132:135], v[70:73]
	ds_read_b128 v[132:135], v130 offset:51200
	s_add_u32 m0, s100, 0x3000
	s_waitcnt lgkmcnt(6)
	v_mfma_f32_16x16x32_bf16 v[58:61], v[26:29], v[144:147], v[58:61]
	global_load_lds_dwordx4 v200, s[98:99]
	v_mfma_f32_16x16x32_bf16 v[66:69], v[30:33], v[144:147], v[66:69]
	ds_read_b128 v[230:233], v130 offset:53248
	s_add_u32 m0, s100, 0x7000
	v_mfma_f32_16x16x32_bf16 v[62:65], v[148:151], v[144:147], v[62:65]
	global_load_lds_dwordx4 v201, s[98:99]
	v_mfma_f32_16x16x32_bf16 v[74:77], v[152:155], v[144:147], v[74:77]
	ds_read_b128 v[144:147], v130 offset:55296
	s_waitcnt lgkmcnt(3)
	v_mfma_f32_16x16x32_bf16 v[34:37], v[222:225], v[160:163], v[34:37]
	s_waitcnt lgkmcnt(2)
	v_mfma_f32_16x16x32_bf16 v[94:97], v[132:135], v[160:163], v[94:97]
	s_waitcnt lgkmcnt(1)
	v_mfma_f32_16x16x32_bf16 v[38:41], v[230:233], v[160:163], v[38:41]
	s_waitcnt lgkmcnt(0)
	v_mfma_f32_16x16x32_bf16 v[90:93], v[144:147], v[160:163], v[90:93]
	v_mfma_f32_16x16x32_bf16 v[42:45], v[222:225], v[194:197], v[42:45]
	v_mfma_f32_16x16x32_bf16 v[86:89], v[132:135], v[194:197], v[86:89]
	v_mfma_f32_16x16x32_bf16 v[46:49], v[230:233], v[194:197], v[46:49]
	v_mfma_f32_16x16x32_bf16 v[82:85], v[144:147], v[194:197], v[82:85]
	v_mfma_f32_16x16x32_bf16 v[50:53], v[222:225], v[202:205], v[50:53]
	v_mfma_f32_16x16x32_bf16 v[78:81], v[132:135], v[202:205], v[78:81]
	v_mfma_f32_16x16x32_bf16 v[54:57], v[230:233], v[202:205], v[54:57]
	v_mfma_f32_16x16x32_bf16 v[70:73], v[144:147], v[202:205], v[70:73]
	v_mfma_f32_16x16x32_bf16 v[58:61], v[222:225], v[210:213], v[58:61]
	v_mfma_f32_16x16x32_bf16 v[66:69], v[132:135], v[210:213], v[66:69]
	v_mfma_f32_16x16x32_bf16 v[62:65], v[230:233], v[210:213], v[62:65]
	v_mfma_f32_16x16x32_bf16 v[74:77], v[144:147], v[210:213], v[74:77]
	s_waitcnt vmcnt(0)
	s_setprio 0
	s_add_i32 s8, s8, 2
	s_add_u32 s28, s28, 0x100
	s_addc_u32 s29, s29, 0
	s_cmp_lt_u32 s8, 12
	s_waitcnt lgkmcnt(0)
	s_barrier
	s_cbranch_scc1 .LBB0_475
	v_mov_b32_e32 v2, v164
	v_mov_b32_e32 v3, v165
	v_mov_b32_e32 v4, v166
	v_mov_b32_e32 v5, v167
	v_mov_b32_e32 v6, v198
	v_mov_b32_e32 v7, v199
	v_mov_b32_e32 v8, v200
	v_mov_b32_e32 v9, v201
	s_add_u32 s98, s28, 0x80
	s_addc_u32 s99, s29, 0
	s_add_i32 s8, s11, s2
	s_cmpk_lt_u32 s8, 0x420
	s_cselect_b64 s[56:57], -1, 0
	s_and_b64 s[14:15], s[56:57], exec
	s_cselect_b32 s10, s8, s11
	s_mul_hi_u32 s11, s10, 0x3e0f83e1
	s_lshr_b32 s11, s11, 6
	s_mul_i32 s14, s11, 0x108
	v_mov_b32_e32 v0, v169
	s_sub_i32 s10, s10, s14
	s_lshl_b32 s11, s11, 3
	s_add_i32 s11, s11, s21
	s_and_b32 s14, s10, 7
	v_lshlrev_b32_e32 v98, 3, v0
	v_lshlrev_b32_e32 v0, 7, v0
	s_or_b32 s11, s11, s14
	v_and_b32_e32 v0, 0xfffffc00, v0
	v_lshl_add_u32 v0, s11, 17, v0
	v_and_or_b32 v0, v98, 56, v0
	v_mov_b32_e32 v98, v169
	s_lshl_b32 s10, s10, 4
	s_and_b32 s10, s10, 0x1f80
	v_lshrrev_b32_e32 v99, 3, v98
	v_lshlrev_b32_e32 v98, 3, v98
	v_add_u32_e32 v99, s10, v99
	v_and_b32_e32 v98, 56, v98
	v_add_u32_e32 v128, 0x8000, v0
	v_add_u32_e32 v136, 0x10000, v0
	v_lshl_or_b32 v160, v99, 10, v98
	v_add_u32_e32 v210, 0x18000, v0
	v_add_u32_e32 v198, 0x8000, v160
	v_add_u32_e32 v212, 0x10000, v160
	v_add_u32_e32 v214, 0x18000, v160
	s_setprio 1
	ds_read_b128 v[98:101], v120 offset:16384
	ds_read_b128 v[110:113], v120 offset:18432
	ds_read_b128 v[132:135], v120 offset:20480
	ds_read_b128 v[144:147], v120 offset:22528
	ds_read_b128 v[102:105], v122
	ds_read_b128 v[106:109], v122 offset:2048
	ds_read_b128 v[116:119], v122 offset:4096
	ds_read_b128 v[124:127], v122 offset:6144
	v_lshrrev_b32_e32 v14, 3, v169
	v_and_b32_e32 v15, 3, v14
	v_bfe_u32 v16, v14, 4, 1
	v_lshl_or_b32 v15, v16, 2, v15
	v_bfe_u32 v16, v14, 2, 1
	v_lshl_or_b32 v15, v16, 3, v15
	v_bfe_u32 v16, v14, 3, 1
	v_lshl_or_b32 v15, v16, 4, v15
	v_sub_u32_e32 v15, v15, v14
	v_mul_i32_i24_e32 v15, 0x400, v15
	v_and_b32_e32 v14, 7, v14
	v_lshlrev_b32_e32 v14, 3, v14
	v_xor_b32_e32 v0, v0, v14
	v_add_u32_e32 v160, v160, v15
	v_xor_b32_e32 v160, v160, v14
	v_xor_b32_e32 v128, v128, v14
	v_add_u32_e32 v198, v198, v15
	v_xor_b32_e32 v198, v198, v14
	v_xor_b32_e32 v136, v136, v14
	v_add_u32_e32 v212, v212, v15
	v_xor_b32_e32 v212, v212, v14
	v_xor_b32_e32 v210, v210, v14
	v_add_u32_e32 v214, v214, v15
	v_xor_b32_e32 v214, v214, v14
	v_mov_b32_e32 v161, v1
	v_mov_b32_e32 v129, v1
	v_mov_b32_e32 v199, v1
	v_mov_b32_e32 v137, v1
	v_mov_b32_e32 v213, v1
	v_mov_b32_e32 v211, v1
	v_mov_b32_e32 v215, v1
	v_lshl_add_u64 v[216:217], v[0:1], 1, s[48:49]
	v_lshl_add_u64 v[218:219], v[160:161], 1, s[50:51]
	v_lshl_add_u64 v[220:221], v[128:129], 1, s[48:49]
	v_lshl_add_u64 v[222:223], v[198:199], 1, s[50:51]
	v_lshl_add_u64 v[136:137], v[136:137], 1, s[48:49]
	v_lshl_add_u64 v[212:213], v[212:213], 1, s[50:51]
	v_lshl_add_u64 v[224:225], v[210:211], 1, s[48:49]
	v_lshl_add_u64 v[226:227], v[214:215], 1, s[50:51]
	s_add_u32 m0, s100, 0x8000
	s_waitcnt lgkmcnt(3)
	v_mfma_f32_16x16x32_bf16 v[148:151], v[98:101], v[102:105], v[34:37]
	global_load_lds_dwordx4 v2, s[98:99]
	v_mfma_f32_16x16x32_bf16 v[94:97], v[110:113], v[102:105], v[94:97]
	ds_read_b128 v[152:155], v121
	s_add_u32 m0, s100, 0xc000
	v_mfma_f32_16x16x32_bf16 v[156:159], v[132:135], v[102:105], v[38:41]
	global_load_lds_dwordx4 v3, s[98:99]
	v_mfma_f32_16x16x32_bf16 v[90:93], v[144:147], v[102:105], v[90:93]
	ds_read_b128 v[102:105], v121 offset:2048
	s_add_u32 m0, s100, 0x9000
	s_waitcnt lgkmcnt(4)
	v_mfma_f32_16x16x32_bf16 v[160:163], v[98:101], v[106:109], v[42:45]
	global_load_lds_dwordx4 v4, s[98:99]
	v_mfma_f32_16x16x32_bf16 v[86:89], v[110:113], v[106:109], v[86:89]
	ds_read_b128 v[164:167], v121 offset:4096
	s_add_u32 m0, s100, 0xd000
	v_mfma_f32_16x16x32_bf16 v[194:197], v[132:135], v[106:109], v[46:49]
	global_load_lds_dwordx4 v5, s[98:99]
	v_mfma_f32_16x16x32_bf16 v[82:85], v[144:147], v[106:109], v[82:85]
	ds_read_b128 v[106:109], v121 offset:6144
	s_add_u32 m0, s100, 0xa000
	s_waitcnt lgkmcnt(5)
	v_mfma_f32_16x16x32_bf16 v[198:201], v[98:101], v[116:119], v[50:53]
	global_load_lds_dwordx4 v6, s[98:99]
	v_mfma_f32_16x16x32_bf16 v[78:81], v[110:113], v[116:119], v[78:81]
	ds_read_b128 v[202:205], v130 offset:16384
	s_add_u32 m0, s100, 0xe000
	v_mfma_f32_16x16x32_bf16 v[206:209], v[132:135], v[116:119], v[54:57]
	global_load_lds_dwordx4 v7, s[98:99]
	v_mfma_f32_16x16x32_bf16 v[70:73], v[144:147], v[116:119], v[70:73]
	ds_read_b128 v[116:119], v130 offset:18432
	s_add_u32 m0, s100, 0xb000
	s_waitcnt lgkmcnt(6)
	v_mfma_f32_16x16x32_bf16 v[98:101], v[98:101], v[124:127], v[58:61]
	global_load_lds_dwordx4 v8, s[98:99]
	v_mfma_f32_16x16x32_bf16 v[66:69], v[110:113], v[124:127], v[66:69]
	ds_read_b128 v[110:113], v130 offset:20480
	s_add_u32 m0, s100, 0xf000
	v_mfma_f32_16x16x32_bf16 v[132:135], v[132:135], v[124:127], v[62:65]
	global_load_lds_dwordx4 v9, s[98:99]
	v_mfma_f32_16x16x32_bf16 v[74:77], v[144:147], v[124:127], v[74:77]
	ds_read_b128 v[124:127], v130 offset:22528
	s_waitcnt lgkmcnt(3)
	v_mfma_f32_16x16x32_bf16 v[144:147], v[202:205], v[152:155], v[148:151]
	s_waitcnt lgkmcnt(2)
	v_mfma_f32_16x16x32_bf16 v[94:97], v[116:119], v[152:155], v[94:97]
	s_waitcnt lgkmcnt(1)
	v_mfma_f32_16x16x32_bf16 v[148:151], v[110:113], v[152:155], v[156:159]
	s_waitcnt lgkmcnt(0)
	v_mfma_f32_16x16x32_bf16 v[90:93], v[124:127], v[152:155], v[90:93]
	v_mfma_f32_16x16x32_bf16 v[152:155], v[202:205], v[102:105], v[160:163]
	v_mfma_f32_16x16x32_bf16 v[86:89], v[116:119], v[102:105], v[86:89]
	v_mfma_f32_16x16x32_bf16 v[156:159], v[110:113], v[102:105], v[194:197]
	v_mfma_f32_16x16x32_bf16 v[82:85], v[124:127], v[102:105], v[82:85]
	v_mfma_f32_16x16x32_bf16 v[102:105], v[202:205], v[164:167], v[198:201]
	v_mfma_f32_16x16x32_bf16 v[78:81], v[116:119], v[164:167], v[78:81]
	v_mfma_f32_16x16x32_bf16 v[160:163], v[110:113], v[164:167], v[206:209]
	v_mfma_f32_16x16x32_bf16 v[70:73], v[124:127], v[164:167], v[70:73]
	v_mfma_f32_16x16x32_bf16 v[98:101], v[202:205], v[106:109], v[98:101]
	v_mfma_f32_16x16x32_bf16 v[66:69], v[116:119], v[106:109], v[66:69]
	v_mfma_f32_16x16x32_bf16 v[110:113], v[110:113], v[106:109], v[132:135]
	v_mfma_f32_16x16x32_bf16 v[74:77], v[124:127], v[106:109], v[74:77]
	s_waitcnt vmcnt(0)
	s_setprio 0
	s_waitcnt lgkmcnt(0)
	s_barrier
	s_setprio 1
	ds_read_b128 v[26:29], v120 offset:49152
	ds_read_b128 v[10:13], v122 offset:32768
	ds_read_b128 v[18:21], v122 offset:34816
	ds_read_b128 v[30:33], v120 offset:51200
	ds_read_b128 v[106:109], v122 offset:36864
	ds_read_b128 v[114:117], v122 offset:38912
	ds_read_b128 v[122:125], v120 offset:53248
	ds_read_b128 v[126:129], v120 offset:55296
	s_add_u32 m0, s100, 0x0
	s_waitcnt lgkmcnt(6)
	v_mfma_f32_16x16x32_bf16 v[132:135], v[26:29], v[10:13], v[144:147]
	global_load_lds_dwordx4 v[216:217], off
	s_waitcnt lgkmcnt(4)
	v_mfma_f32_16x16x32_bf16 v[94:97], v[30:33], v[10:13], v[94:97]
	ds_read_b128 v[144:147], v121 offset:32768
	s_add_u32 m0, s100, 0x4000
	s_waitcnt lgkmcnt(2)
	v_mfma_f32_16x16x32_bf16 v[148:151], v[122:125], v[10:13], v[148:151]
	global_load_lds_dwordx4 v[218:219], off
	s_waitcnt lgkmcnt(1)
	v_mfma_f32_16x16x32_bf16 v[90:93], v[126:129], v[10:13], v[90:93]
	ds_read_b128 v[164:167], v121 offset:34816
	s_add_u32 m0, s100, 0x1000
	v_mfma_f32_16x16x32_bf16 v[152:155], v[26:29], v[18:21], v[152:155]
	global_load_lds_dwordx4 v[220:221], off
	v_mfma_f32_16x16x32_bf16 v[86:89], v[30:33], v[18:21], v[86:89]
	ds_read_b128 v[194:197], v121 offset:36864
	s_add_u32 m0, s100, 0x5000
	v_mfma_f32_16x16x32_bf16 v[156:159], v[122:125], v[18:21], v[156:159]
	global_load_lds_dwordx4 v[222:223], off
	v_mfma_f32_16x16x32_bf16 v[82:85], v[126:129], v[18:21], v[82:85]
	ds_read_b128 v[198:201], v121 offset:38912
	s_add_u32 m0, s100, 0x2000
	v_mfma_f32_16x16x32_bf16 v[202:205], v[26:29], v[106:109], v[102:105]
	global_load_lds_dwordx4 v[136:137], off
	v_mfma_f32_16x16x32_bf16 v[78:81], v[30:33], v[106:109], v[78:81]
	ds_read_b128 v[206:209], v130 offset:49152
	s_add_u32 m0, s100, 0x6000
	v_mfma_f32_16x16x32_bf16 v[160:163], v[122:125], v[106:109], v[160:163]
	global_load_lds_dwordx4 v[212:213], off
	v_mfma_f32_16x16x32_bf16 v[70:73], v[126:129], v[106:109], v[70:73]
	ds_read_b128 v[210:213], v130 offset:51200
	s_add_u32 m0, s100, 0x3000
	v_mfma_f32_16x16x32_bf16 v[214:217], v[26:29], v[114:117], v[98:101]
	global_load_lds_dwordx4 v[224:225], off
	v_mfma_f32_16x16x32_bf16 v[66:69], v[30:33], v[114:117], v[66:69]
	ds_read_b128 v[218:221], v130 offset:53248
	s_add_u32 m0, s100, 0x7000
	v_mfma_f32_16x16x32_bf16 v[222:225], v[122:125], v[114:117], v[110:113]
	global_load_lds_dwordx4 v[226:227], off
	v_mfma_f32_16x16x32_bf16 v[226:229], v[126:129], v[114:117], v[74:77]
	s_waitcnt lgkmcnt(2)
	v_mfma_f32_16x16x32_bf16 v[126:129], v[206:209], v[144:147], v[132:135]
	ds_read_b128 v[130:133], v130 offset:55296
	s_waitcnt lgkmcnt(2)
	v_mfma_f32_16x16x32_bf16 v[122:125], v[210:213], v[144:147], v[94:97]
	s_waitcnt lgkmcnt(1)
	v_mfma_f32_16x16x32_bf16 v[118:121], v[218:221], v[144:147], v[148:151]
	s_waitcnt lgkmcnt(0)
	v_mfma_f32_16x16x32_bf16 v[114:117], v[130:133], v[144:147], v[90:93]
	v_mfma_f32_16x16x32_bf16 v[110:113], v[206:209], v[164:167], v[152:155]
	v_mfma_f32_16x16x32_bf16 v[106:109], v[210:213], v[164:167], v[86:89]
	v_mfma_f32_16x16x32_bf16 v[102:105], v[218:221], v[164:167], v[156:159]
	v_mfma_f32_16x16x32_bf16 v[98:101], v[130:133], v[164:167], v[82:85]
	v_mfma_f32_16x16x32_bf16 v[94:97], v[206:209], v[194:197], v[202:205]
	v_mfma_f32_16x16x32_bf16 v[90:93], v[210:213], v[194:197], v[78:81]
	v_mfma_f32_16x16x32_bf16 v[86:89], v[218:221], v[194:197], v[160:163]
	v_mfma_f32_16x16x32_bf16 v[82:85], v[130:133], v[194:197], v[70:73]
	v_mfma_f32_16x16x32_bf16 v[74:77], v[206:209], v[198:201], v[214:217]
	v_mfma_f32_16x16x32_bf16 v[70:73], v[210:213], v[198:201], v[66:69]
	v_mfma_f32_16x16x32_bf16 v[66:69], v[218:221], v[198:201], v[222:225]
	v_mfma_f32_16x16x32_bf16 v[78:81], v[130:133], v[198:201], v[226:229]
	s_setprio 0
	s_cmpk_gt_u32 s16, 0x9ff
	s_cselect_b64 s[42:43], -1, 0
	s_and_b32 s17, s16, 0x1f00
	s_cmpk_eq_i32 s17, 0xe00
	s_cselect_b64 s[40:41], -1, 0
	s_cmpk_gt_u32 s16, 0x5ff
	s_cselect_b64 s[46:47], -1, 0
	s_cmpk_gt_u32 s16, 0xbff
	s_cselect_b64 s[62:63], -1, 0
	s_cmpk_lt_u32 s16, 0xd00
	s_cselect_b64 s[14:15], -1, 0
	s_and_b64 s[26:27], s[14:15], exec
	s_movk_i32 s21, 0xf300
	s_cselect_b32 s28, 0xfffff400, s21
	s_nor_b64 s[60:61], s[14:15], s[40:41]
	s_cmpk_gt_u32 s16, 0xfff
	s_cselect_b64 s[58:59], -1, 0
	s_cmpk_lt_u32 s16, 0xe00
	v_add_u32_e32 v0, s9, v141
	s_cselect_b64 s[14:15], -1, 0
	v_or_b32_e32 v136, v0, v140
	s_movk_i32 s21, 0xc0
	s_and_b64 s[14:15], s[14:15], exec
	v_mad_i64_i32 v[134:135], s[26:27], v136, s21, 0
	s_movk_i32 s21, 0x1fcf
	s_movk_i32 s14, 0xf100
	v_bitop3_b32 v144, v0, s21, v140 bitop3:0xc8
	v_ashrrev_i32_e32 v0, 5, v0
	s_cselect_b32 s15, 0xfffff300, s14
	s_mov_b32 s14, 0x18991000
	v_ashrrev_i32_e32 v137, 31, v136
	v_and_b32_e32 v0, 0xffffff00, v0
	s_cselect_b32 s14, s14, 0x19991000
	v_add_u32_e32 v145, s15, v0
	v_lshlrev_b64 v[132:133], 10, v[136:137]
	v_lshlrev_b64 v[130:131], 11, v[136:137]
	v_or_b32_e32 v0, s16, v142
	s_mov_b64 s[44:45], -1
	s_and_b64 vcc, exec, s[46:47]
	s_barrier
	s_cbranch_vccz .LBB0_496
	s_and_b64 vcc, exec, s[42:43]
	s_cbranch_vccz .LBB0_493
	s_and_b64 vcc, exec, s[62:63]
	s_cbranch_vccz .LBB0_490
	s_and_b64 vcc, exec, s[60:61]
	s_cbranch_vccz .LBB0_487
	s_and_b64 vcc, exec, s[58:59]
	s_cbranch_vccz .LBB0_484
	v_cmp_gt_u32_e32 vcc, s7, v0
	s_and_saveexec_b64 s[44:45], vcc
	s_cbranch_execz .LBB0_483
	v_mul_f32_e32 v137, 0xbfb8aa3b, v126
	v_exp_f32_e32 v137, v137
	v_mul_f32_e32 v143, 0xbfb8aa3b, v127
	v_exp_f32_e32 v143, v143
	v_mul_f32_e32 v147, 0xbfb8aa3b, v129
	v_add_f32_e32 v137, 1.0, v137
	v_rcp_f32_e32 v146, v137
	v_mul_f32_e32 v137, 0xbfb8aa3b, v128
	v_exp_f32_e32 v137, v137
	v_exp_f32_e32 v149, v147
	v_add_f32_e32 v143, 1.0, v143
	v_rcp_f32_e32 v147, v143
	v_add_f32_e32 v137, 1.0, v137
	v_mul_f32_e32 v143, 0xbfb8aa3b, v122
	v_rcp_f32_e32 v148, v137
	v_add_f32_e32 v137, 1.0, v149
	v_exp_f32_e32 v143, v143
	v_mul_f32_e32 v149, 0xbfb8aa3b, v123
	v_exp_f32_e32 v151, v149
	v_rcp_f32_e32 v149, v137
	v_add_f32_e32 v137, 1.0, v143
	v_mul_f32_e32 v143, 0xbfb8aa3b, v124
	v_rcp_f32_e32 v150, v137
	v_add_f32_e32 v137, 1.0, v151
	v_exp_f32_e32 v143, v143
	v_mul_f32_e32 v151, 0xbfb8aa3b, v125
	v_exp_f32_e32 v153, v151
	v_rcp_f32_e32 v151, v137
	v_add_f32_e32 v137, 1.0, v143
	v_rcp_f32_e32 v152, v137
	v_add_f32_e32 v137, 1.0, v153
	v_lshl_add_u64 v[154:155], s[34:35], 0, v[134:135]
	v_rcp_f32_e32 v153, v137
	v_lshl_add_u64 v[154:155], v[0:1], 2, v[154:155]
	v_add_co_u32_e32 v154, vcc, 0x438d000, v154
	s_nop 1
	v_addc_co_u32_e32 v155, vcc, 0, v155, vcc
	global_store_dwordx4 v[154:155], v[146:149], off
	global_store_dwordx4 v[154:155], v[150:153], off offset:16
